# K-loops read-heavy phases: the 2-DMA refill block now leads the load segment (ahead of all 16 ds_read_b128), on top of the DMA-first version
# speedup vs baseline: 1.0026x; 1.0026x over previous
; #define PG8_STAGE(bufoff, gbase, voff) do { _Pragma("unroll") for (int _i = 0; _i < 2; ++_i) \
;         __builtin_amdgcn_global_load_lds((const unsigned*)((const char*)(gbase) + (voff)[_i]), (LAS unsigned*)(lds + (bufoff) + ldsw + _i * 8192), 16, 0, 0); } while (0)
; #define PG8_LDA(dst, b, h) do { _Pragma("unroll") for (int m = 0; m < 4; ++m) _Pragma("unroll") for (int k = 0; k < 2; ++k) dst[m][k] = *(const LAS bf16x8*)(lds + PG8_SA(b, h) + aoff + m * 2048 + k * 1024); } while (0)
; #define PG8_LDB(dst, b, h) do { _Pragma("unroll") for (int n = 0; n < 2; ++n) _Pragma("unroll") for (int k = 0; k < 2; ++k) dst[n][k] = *(const LAS bf16x8*)(lds + PG8_SB(b, h) + boff + n * 2048 + k * 1024); } while (0)
; #define PG8_MMA(ai, bj, At, Bt) do { __builtin_amdgcn_s_setprio(1); _Pragma("unroll") for (int m = 0; m < 4; ++m) _Pragma("unroll") for (int n = 0; n < 2; ++n) _Pragma("unroll") for (int k = 0; k < 2; ++k) \
;         acc[ai][bj][m][n] = __builtin_amdgcn_mfma_f32_16x16x32_bf16(Bt[n][k], At[m][k], acc[ai][bj][m][n], 0, 0, 0); __builtin_amdgcn_s_setprio(0); } while (0)
; #define PG8_WAIT_V(n) asm volatile("s_waitcnt vmcnt(" #n ")" ::: "memory")
; #define PG8_WAIT_L(n) asm volatile("s_waitcnt lgkmcnt(" #n ")" ::: "memory")
; #define PG8_BAR __builtin_amdgcn_s_barrier()
; #define PG8_SCHED __builtin_amdgcn_sched_barrier(0)
; template <class Epi>
; __device__ __forceinline__ void gemm_phase(LAS unsigned char* lds, const int tid, const Gemm g, const StaticOrder& S, const Epi& E) {
;     ...
;             const bool last = (t == nt - 2);
;             const char* a1 = cA + (size_t)(t + 1) * kstep;
;             const char* a2 = last ? nA : cA + (size_t)(t + 2) * kstep; const char* b2 = last ? nB : cB + (size_t)(t + 2) * kstep;
;             const char* a3 = a2 + kstep; const char* b3 = b2 + kstep;
;             PG8_LDB(B0, 0, 0); PG8_LDB(B1, 0, 1); PG8_SCHED; PG8_LDA(At, 0, 0); PG8_STAGE(PG8_SA(1, 1), a1 + hstepA, voffA);
;             PG8_WAIT_V(8); PG8_WAIT_L(0); PG8_BAR; PG8_MMA(0, 0, At, B0); PG8_MMA(0, 1, At, B1); PG8_BAR; PG8_SCHED;
;             PG8_LDA(At, 0, 1); PG8_STAGE(PG8_SB(0, 0), b2, voffB); PG8_STAGE(PG8_SB(0, 1), b2 + hstepB, voffB); PG8_STAGE(PG8_SA(0, 0), a2, voffA);
.LBB0_414:
	v_lshl_add_u64 v[160:161], s[68:69], 0, v[152:153]
	s_add_i32 m0, s83, 0xc000
	s_nop 0
	global_load_lds_dwordx4 v[160:161], off
	v_lshl_add_u64 v[160:161], s[68:69], 0, v[154:155]
	s_add_i32 m0, s83, 0xe000
	s_nop 0
	global_load_lds_dwordx4 v[160:161], off
	s_add_u32 s10, s68, 0xfffc0080
	s_addc_u32 s11, s69, -1
	s_add_i32 s17, 0, 0x10000
	s_cmp_eq_u32 s16, 12
	s_cselect_b32 s73, s7, s11
	s_cselect_b32 s72, s67, s10
	s_cselect_b32 s71, s5, s76
	s_cselect_b32 s70, vcc_lo, vcc_hi
	s_add_i32 s0, 0, 0x14000
	v_add_u32_e32 v70, s17, v202
	v_add_u32_e32 v160, s0, v202
	ds_read_b128 v[50:53], v70
	ds_read_b128 v[54:57], v70 offset:1024
	ds_read_b128 v[66:69], v70 offset:2048
	ds_read_b128 v[70:73], v70 offset:3072
	ds_read_b128 v[156:159], v160
	ds_read_b128 v[170:173], v160 offset:1024
	ds_read_b128 v[174:177], v160 offset:2048
	ds_read_b128 v[178:181], v160 offset:3072
	ds_read_b128 v[216:219], v215
	ds_read_b128 v[220:223], v215 offset:1024
	ds_read_b128 v[224:227], v215 offset:2048
	ds_read_b128 v[228:231], v215 offset:3072
	ds_read_b128 v[232:235], v215 offset:4096
	ds_read_b128 v[236:239], v215 offset:5120
	ds_read_b128 v[240:243], v215 offset:6144
	ds_read_b128 v[244:247], v215 offset:7168
	s_waitcnt vmcnt(8)
	s_waitcnt lgkmcnt(0)
	s_barrier
	s_setprio 1
	s_waitcnt lgkmcnt(0)
	v_mfma_f32_16x16x32_bf16 v[142:145], v[50:53], v[216:219], v[142:145]
	v_mfma_f32_16x16x32_bf16 v[138:141], v[66:69], v[216:219], v[138:141]
	v_mfma_f32_16x16x32_bf16 v[126:129], v[50:53], v[224:227], v[126:129]
	v_mfma_f32_16x16x32_bf16 v[122:125], v[66:69], v[224:227], v[122:125]
	v_mfma_f32_16x16x32_bf16 v[110:113], v[50:53], v[232:235], v[110:113]
	v_mfma_f32_16x16x32_bf16 v[106:109], v[66:69], v[232:235], v[106:109]
	v_mfma_f32_16x16x32_bf16 v[94:97], v[50:53], v[240:243], v[94:97]
	v_mfma_f32_16x16x32_bf16 v[90:93], v[66:69], v[240:243], v[90:93]
	v_mfma_f32_16x16x32_bf16 v[142:145], v[54:57], v[220:223], v[142:145]
	v_mfma_f32_16x16x32_bf16 v[138:141], v[70:73], v[220:223], v[138:141]
	v_mfma_f32_16x16x32_bf16 v[126:129], v[54:57], v[228:231], v[126:129]
	v_mfma_f32_16x16x32_bf16 v[122:125], v[70:73], v[228:231], v[122:125]
	v_mfma_f32_16x16x32_bf16 v[110:113], v[54:57], v[236:239], v[110:113]
	v_mfma_f32_16x16x32_bf16 v[106:109], v[70:73], v[236:239], v[106:109]
	v_mfma_f32_16x16x32_bf16 v[94:97], v[54:57], v[244:247], v[94:97]
	v_mfma_f32_16x16x32_bf16 v[90:93], v[70:73], v[244:247], v[90:93]
	s_setprio 0
	s_setprio 1
	v_mfma_f32_16x16x32_bf16 v[134:137], v[156:159], v[216:219], v[134:137]
	v_mfma_f32_16x16x32_bf16 v[130:133], v[174:177], v[216:219], v[130:133]
	v_mfma_f32_16x16x32_bf16 v[118:121], v[156:159], v[224:227], v[118:121]
	v_mfma_f32_16x16x32_bf16 v[114:117], v[174:177], v[224:227], v[114:117]
	v_mfma_f32_16x16x32_bf16 v[102:105], v[156:159], v[232:235], v[102:105]
	v_mfma_f32_16x16x32_bf16 v[98:101], v[174:177], v[232:235], v[98:101]
	v_mfma_f32_16x16x32_bf16 v[86:89], v[156:159], v[240:243], v[86:89]
	v_mfma_f32_16x16x32_bf16 v[82:85], v[174:177], v[240:243], v[82:85]
	v_mfma_f32_16x16x32_bf16 v[134:137], v[170:173], v[220:223], v[134:137]
	v_mfma_f32_16x16x32_bf16 v[130:133], v[178:181], v[220:223], v[130:133]
	v_mfma_f32_16x16x32_bf16 v[118:121], v[170:173], v[228:231], v[118:121]
	v_mfma_f32_16x16x32_bf16 v[114:117], v[178:181], v[228:231], v[114:117]
	v_mfma_f32_16x16x32_bf16 v[102:105], v[170:173], v[236:239], v[102:105]
	v_mfma_f32_16x16x32_bf16 v[98:101], v[178:181], v[236:239], v[98:101]
	v_mfma_f32_16x16x32_bf16 v[86:89], v[170:173], v[244:247], v[86:89]
	v_mfma_f32_16x16x32_bf16 v[82:85], v[178:181], v[244:247], v[82:85]
	s_setprio 0
	s_barrier
	s_add_i32 s1, s17, s82
	v_lshl_add_u64 v[160:161], s[70:71], 0, v[0:1]
	s_mov_b32 m0, s1
	s_nop 0
	global_load_lds_dwordx4 v[160:161], off
	s_add_i32 m0, s1, 0x2000
	s_add_u32 s10, s70, 0x40000
	v_lshl_add_u64 v[182:183], s[70:71], 0, v[146:147]
	s_addc_u32 s11, s71, 0
	s_add_i32 s0, s0, s82
	global_load_lds_dwordx4 v[182:183], off
	v_lshl_add_u64 v[162:163], s[10:11], 0, v[0:1]
	s_mov_b32 m0, s0
	v_lshl_add_u64 v[164:165], s[72:73], 0, v[150:151]
	global_load_lds_dwordx4 v[162:163], off
	v_lshl_add_u64 v[162:163], s[10:11], 0, v[146:147]
	s_add_i32 m0, s0, 0x2000
	s_nop 0
	global_load_lds_dwordx4 v[162:163], off
	v_lshl_add_u64 v[162:163], s[72:73], 0, v[148:149]
	s_mov_b32 m0, s83
	s_nop 0
	global_load_lds_dwordx4 v[162:163], off
	s_mov_b32 m0, s88
	s_nop 0
	global_load_lds_dwordx4 v[164:165], off
	ds_read_b128 v[216:219], v215 offset:16384
	ds_read_b128 v[220:223], v215 offset:17408
	ds_read_b128 v[224:227], v215 offset:18432
	ds_read_b128 v[228:231], v215 offset:19456
	ds_read_b128 v[232:235], v215 offset:20480
	ds_read_b128 v[236:239], v215 offset:21504
	ds_read_b128 v[240:243], v215 offset:22528
	ds_read_b128 v[244:247], v215 offset:23552
	s_waitcnt vmcnt(8)
	s_waitcnt lgkmcnt(0)
	s_barrier
; #define PG8_STAGE(bufoff, gbase, voff) do { _Pragma("unroll") for (int _i = 0; _i < 2; ++_i) \
;         __builtin_amdgcn_global_load_lds((const unsigned*)((const char*)(gbase) + (voff)[_i]), (LAS unsigned*)(lds + (bufoff) + ldsw + _i * 8192), 16, 0, 0); } while (0)
; #define PG8_LDA(dst, b, h) do { _Pragma("unroll") for (int m = 0; m < 4; ++m) _Pragma("unroll") for (int k = 0; k < 2; ++k) dst[m][k] = *(const LAS bf16x8*)(lds + PG8_SA(b, h) + aoff + m * 2048 + k * 1024); } while (0)
; #define PG8_LDB(dst, b, h) do { _Pragma("unroll") for (int n = 0; n < 2; ++n) _Pragma("unroll") for (int k = 0; k < 2; ++k) dst[n][k] = *(const LAS bf16x8*)(lds + PG8_SB(b, h) + boff + n * 2048 + k * 1024); } while (0)
; #define PG8_MMA(ai, bj, At, Bt) do { __builtin_amdgcn_s_setprio(1); _Pragma("unroll") for (int m = 0; m < 4; ++m) _Pragma("unroll") for (int n = 0; n < 2; ++n) _Pragma("unroll") for (int k = 0; k < 2; ++k) \
;         acc[ai][bj][m][n] = __builtin_amdgcn_mfma_f32_16x16x32_bf16(Bt[n][k], At[m][k], acc[ai][bj][m][n], 0, 0, 0); __builtin_amdgcn_s_setprio(0); } while (0)
; #define PG8_WAIT_V(n) asm volatile("s_waitcnt vmcnt(" #n ")" ::: "memory")
; #define PG8_WAIT_L(n) asm volatile("s_waitcnt lgkmcnt(" #n ")" ::: "memory")
; #define PG8_BAR __builtin_amdgcn_s_barrier()
; #define PG8_SCHED __builtin_amdgcn_sched_barrier(0)
; template <class Epi>
; __device__ __forceinline__ void gemm_phase(LAS unsigned char* lds, const int tid, const Gemm g, const StaticOrder& S, const Epi& E) {
;     ...
;             PG8_WAIT_V(8); PG8_WAIT_L(0); PG8_BAR; PG8_MMA(1, 0, At, B0); PG8_MMA(1, 1, At, B1); PG8_BAR; PG8_SCHED;
;             PG8_LDB(B0, 1, 0); PG8_LDB(B1, 1, 1); PG8_SCHED; PG8_LDA(At, 1, 0); PG8_STAGE(PG8_SA(0, 1), a2 + hstepA, voffA);
;             PG8_WAIT_V(8); PG8_WAIT_L(0); PG8_BAR; PG8_MMA(0, 0, At, B0); PG8_MMA(0, 1, At, B1); PG8_BAR; PG8_SCHED;
	s_setprio 1
	s_waitcnt lgkmcnt(0)
	v_mfma_f32_16x16x32_bf16 v[78:81], v[50:53], v[216:219], v[78:81]
	v_mfma_f32_16x16x32_bf16 v[74:77], v[66:69], v[216:219], v[74:77]
	v_mfma_f32_16x16x32_bf16 v[46:49], v[50:53], v[224:227], v[46:49]
	v_mfma_f32_16x16x32_bf16 v[42:45], v[66:69], v[224:227], v[42:45]
	v_mfma_f32_16x16x32_bf16 v[30:33], v[50:53], v[232:235], v[30:33]
	v_mfma_f32_16x16x32_bf16 v[26:29], v[66:69], v[232:235], v[26:29]
	v_mfma_f32_16x16x32_bf16 v[14:17], v[50:53], v[240:243], v[14:17]
	v_mfma_f32_16x16x32_bf16 v[10:13], v[66:69], v[240:243], v[10:13]
	v_mfma_f32_16x16x32_bf16 v[78:81], v[54:57], v[220:223], v[78:81]
	v_mfma_f32_16x16x32_bf16 v[74:77], v[70:73], v[220:223], v[74:77]
	v_mfma_f32_16x16x32_bf16 v[46:49], v[54:57], v[228:231], v[46:49]
	v_mfma_f32_16x16x32_bf16 v[42:45], v[70:73], v[228:231], v[42:45]
	v_mfma_f32_16x16x32_bf16 v[30:33], v[54:57], v[236:239], v[30:33]
	v_mfma_f32_16x16x32_bf16 v[26:29], v[70:73], v[236:239], v[26:29]
	v_mfma_f32_16x16x32_bf16 v[14:17], v[54:57], v[244:247], v[14:17]
	v_mfma_f32_16x16x32_bf16 v[10:13], v[70:73], v[244:247], v[10:13]
	s_setprio 0
	s_setprio 1
	v_mfma_f32_16x16x32_bf16 v[38:41], v[156:159], v[224:227], v[38:41]
	v_mfma_f32_16x16x32_bf16 v[34:37], v[174:177], v[224:227], v[34:37]
	v_mfma_f32_16x16x32_bf16 v[22:25], v[156:159], v[232:235], v[22:25]
	v_mfma_f32_16x16x32_bf16 v[18:21], v[174:177], v[232:235], v[18:21]
	v_mfma_f32_16x16x32_bf16 v[6:9], v[156:159], v[240:243], v[6:9]
	v_mfma_f32_16x16x32_bf16 v[2:5], v[174:177], v[240:243], v[2:5]
	v_mfma_f32_16x16x32_bf16 v[50:53], v[156:159], v[216:219], v[62:65]
	v_mfma_f32_16x16x32_bf16 v[54:57], v[174:177], v[216:219], v[58:61]
	v_mfma_f32_16x16x32_bf16 v[38:41], v[170:173], v[228:231], v[38:41]
	v_mfma_f32_16x16x32_bf16 v[34:37], v[178:181], v[228:231], v[34:37]
	v_mfma_f32_16x16x32_bf16 v[22:25], v[170:173], v[236:239], v[22:25]
	v_mfma_f32_16x16x32_bf16 v[18:21], v[178:181], v[236:239], v[18:21]
	v_mfma_f32_16x16x32_bf16 v[6:9], v[170:173], v[244:247], v[6:9]
	v_mfma_f32_16x16x32_bf16 v[2:5], v[178:181], v[244:247], v[2:5]
	v_mfma_f32_16x16x32_bf16 v[50:53], v[170:173], v[220:223], v[50:53]
	v_mfma_f32_16x16x32_bf16 v[54:57], v[178:181], v[220:223], v[54:57]
	s_setprio 0
	s_barrier
	s_add_u32 s10, s72, 0x40000
	s_addc_u32 s11, s73, 0
	s_mov_b32 m0, s89
	v_lshl_add_u64 v[206:207], s[10:11], 0, v[148:149]
	global_load_lds_dwordx4 v[206:207], off
	v_lshl_add_u64 v[206:207], s[10:11], 0, v[150:151]
	s_mov_b32 m0, s92
	s_nop 0
	global_load_lds_dwordx4 v[206:207], off
	s_add_i32 s0, 0, 0x18000
	s_add_i32 s1, 0, 0x1c000
	v_add_u32_e32 v70, s0, v202
	v_add_u32_e32 v178, s1, v202
	ds_read_b128 v[58:61], v70
	ds_read_b128 v[62:65], v70 offset:1024
	ds_read_b128 v[66:69], v70 offset:2048
	ds_read_b128 v[70:73], v70 offset:3072
	ds_read_b128 v[156:159], v178
	ds_read_b128 v[170:173], v178 offset:1024
	ds_read_b128 v[174:177], v178 offset:2048
	ds_read_b128 v[178:181], v178 offset:3072
	ds_read_b128 v[216:219], v215 offset:32768
	ds_read_b128 v[220:223], v215 offset:33792
	ds_read_b128 v[224:227], v215 offset:34816
	ds_read_b128 v[228:231], v215 offset:35840
	ds_read_b128 v[232:235], v215 offset:36864
	ds_read_b128 v[236:239], v215 offset:37888
	ds_read_b128 v[240:243], v215 offset:38912
	ds_read_b128 v[244:247], v215 offset:39936
	s_waitcnt vmcnt(8)
	s_waitcnt lgkmcnt(0)
	s_barrier
	s_setprio 1
	s_waitcnt lgkmcnt(0)
	v_mfma_f32_16x16x32_bf16 v[142:145], v[58:61], v[216:219], v[142:145]
	v_mfma_f32_16x16x32_bf16 v[138:141], v[66:69], v[216:219], v[138:141]
	v_mfma_f32_16x16x32_bf16 v[126:129], v[58:61], v[224:227], v[126:129]
	v_mfma_f32_16x16x32_bf16 v[122:125], v[66:69], v[224:227], v[122:125]
	v_mfma_f32_16x16x32_bf16 v[110:113], v[58:61], v[232:235], v[110:113]
	v_mfma_f32_16x16x32_bf16 v[106:109], v[66:69], v[232:235], v[106:109]
	v_mfma_f32_16x16x32_bf16 v[94:97], v[58:61], v[240:243], v[94:97]
	v_mfma_f32_16x16x32_bf16 v[90:93], v[66:69], v[240:243], v[90:93]
	v_mfma_f32_16x16x32_bf16 v[142:145], v[62:65], v[220:223], v[142:145]
	v_mfma_f32_16x16x32_bf16 v[138:141], v[70:73], v[220:223], v[138:141]
	v_mfma_f32_16x16x32_bf16 v[126:129], v[62:65], v[228:231], v[126:129]
	v_mfma_f32_16x16x32_bf16 v[122:125], v[70:73], v[228:231], v[122:125]
	v_mfma_f32_16x16x32_bf16 v[110:113], v[62:65], v[236:239], v[110:113]
	v_mfma_f32_16x16x32_bf16 v[106:109], v[70:73], v[236:239], v[106:109]
	v_mfma_f32_16x16x32_bf16 v[94:97], v[62:65], v[244:247], v[94:97]
	v_mfma_f32_16x16x32_bf16 v[90:93], v[70:73], v[244:247], v[90:93]
	s_setprio 0
	s_setprio 1
	v_mfma_f32_16x16x32_bf16 v[134:137], v[156:159], v[216:219], v[134:137]
	v_mfma_f32_16x16x32_bf16 v[130:133], v[174:177], v[216:219], v[130:133]
	v_mfma_f32_16x16x32_bf16 v[118:121], v[156:159], v[224:227], v[118:121]
	v_mfma_f32_16x16x32_bf16 v[114:117], v[174:177], v[224:227], v[114:117]
	v_mfma_f32_16x16x32_bf16 v[102:105], v[156:159], v[232:235], v[102:105]
	v_mfma_f32_16x16x32_bf16 v[98:101], v[174:177], v[232:235], v[98:101]
	v_mfma_f32_16x16x32_bf16 v[86:89], v[156:159], v[240:243], v[86:89]
	v_mfma_f32_16x16x32_bf16 v[82:85], v[174:177], v[240:243], v[82:85]
	v_mfma_f32_16x16x32_bf16 v[134:137], v[170:173], v[220:223], v[134:137]
	v_mfma_f32_16x16x32_bf16 v[130:133], v[178:181], v[220:223], v[130:133]
	v_mfma_f32_16x16x32_bf16 v[118:121], v[170:173], v[228:231], v[118:121]
	v_mfma_f32_16x16x32_bf16 v[114:117], v[178:181], v[228:231], v[114:117]
	v_mfma_f32_16x16x32_bf16 v[102:105], v[170:173], v[236:239], v[102:105]
	v_mfma_f32_16x16x32_bf16 v[98:101], v[178:181], v[236:239], v[98:101]
	v_mfma_f32_16x16x32_bf16 v[86:89], v[170:173], v[244:247], v[86:89]
	v_mfma_f32_16x16x32_bf16 v[82:85], v[178:181], v[244:247], v[82:85]
	s_setprio 0
	s_barrier
; #define PG8_STAGE(bufoff, gbase, voff) do { _Pragma("unroll") for (int _i = 0; _i < 2; ++_i) \
;         __builtin_amdgcn_global_load_lds((const unsigned*)((const char*)(gbase) + (voff)[_i]), (LAS unsigned*)(lds + (bufoff) + ldsw + _i * 8192), 16, 0, 0); } while (0)
; #define PG8_LDA(dst, b, h) do { _Pragma("unroll") for (int m = 0; m < 4; ++m) _Pragma("unroll") for (int k = 0; k < 2; ++k) dst[m][k] = *(const LAS bf16x8*)(lds + PG8_SA(b, h) + aoff + m * 2048 + k * 1024); } while (0)
; #define PG8_MMA(ai, bj, At, Bt) do { __builtin_amdgcn_s_setprio(1); _Pragma("unroll") for (int m = 0; m < 4; ++m) _Pragma("unroll") for (int n = 0; n < 2; ++n) _Pragma("unroll") for (int k = 0; k < 2; ++k) \
;         acc[ai][bj][m][n] = __builtin_amdgcn_mfma_f32_16x16x32_bf16(Bt[n][k], At[m][k], acc[ai][bj][m][n], 0, 0, 0); __builtin_amdgcn_s_setprio(0); } while (0)
; #define PG8_WAIT_V(n) asm volatile("s_waitcnt vmcnt(" #n ")" ::: "memory")
; #define PG8_WAIT_L(n) asm volatile("s_waitcnt lgkmcnt(" #n ")" ::: "memory")
; #define PG8_BAR __builtin_amdgcn_s_barrier()
; #define PG8_SCHED __builtin_amdgcn_sched_barrier(0)
; template <class Epi>
; __device__ __forceinline__ void gemm_phase(LAS unsigned char* lds, const int tid, const Gemm g, const StaticOrder& S, const Epi& E) {
;     ...
;             PG8_LDA(At, 1, 1); PG8_STAGE(PG8_SB(1, 0), b3, voffB); PG8_STAGE(PG8_SB(1, 1), b3 + hstepB, voffB); PG8_STAGE(PG8_SA(1, 0), a3, voffA);
;             PG8_WAIT_V(8); PG8_WAIT_L(0); PG8_BAR; PG8_MMA(1, 0, At, B0); PG8_MMA(1, 1, At, B1); PG8_BAR; PG8_SCHED;
;         }
	s_add_i32 s0, s0, s82
	v_lshl_add_u64 v[160:161], v[160:161], 0, s[36:37]
	s_mov_b32 m0, s0
	s_nop 0
	global_load_lds_dwordx4 v[160:161], off
	s_add_i32 m0, s0, 0x2000
	s_add_u32 s10, s70, 0x40080
	v_lshl_add_u64 v[160:161], v[182:183], 0, s[36:37]
	s_addc_u32 s11, s71, 0
	s_add_i32 s0, s1, s82
	global_load_lds_dwordx4 v[160:161], off
	v_lshl_add_u64 v[160:161], s[10:11], 0, v[0:1]
	s_mov_b32 m0, s0
	s_nop 0
	global_load_lds_dwordx4 v[160:161], off
	v_lshl_add_u64 v[160:161], s[10:11], 0, v[146:147]
	s_add_i32 m0, s0, 0x2000
	s_nop 0
	global_load_lds_dwordx4 v[160:161], off
	v_lshl_add_u64 v[160:161], v[162:163], 0, s[36:37]
	s_mov_b32 m0, s93
	s_nop 0
	global_load_lds_dwordx4 v[160:161], off
	v_lshl_add_u64 v[160:161], v[164:165], 0, s[36:37]
	s_mov_b32 m0, s74
	s_nop 0
	global_load_lds_dwordx4 v[160:161], off
	ds_read_b128 v[216:219], v215 offset:49152
	ds_read_b128 v[220:223], v215 offset:50176
	ds_read_b128 v[224:227], v215 offset:51200
	ds_read_b128 v[228:231], v215 offset:52224
	ds_read_b128 v[232:235], v215 offset:53248
	ds_read_b128 v[236:239], v215 offset:54272
	ds_read_b128 v[240:243], v215 offset:55296
	ds_read_b128 v[244:247], v215 offset:56320
	s_waitcnt vmcnt(8)
	s_waitcnt lgkmcnt(0)
	s_barrier
	s_setprio 1
	s_waitcnt lgkmcnt(0)
	v_mfma_f32_16x16x32_bf16 v[78:81], v[58:61], v[216:219], v[78:81]
	v_mfma_f32_16x16x32_bf16 v[74:77], v[66:69], v[216:219], v[74:77]
	v_mfma_f32_16x16x32_bf16 v[46:49], v[58:61], v[224:227], v[46:49]
	v_mfma_f32_16x16x32_bf16 v[42:45], v[66:69], v[224:227], v[42:45]
	v_mfma_f32_16x16x32_bf16 v[30:33], v[58:61], v[232:235], v[30:33]
	v_mfma_f32_16x16x32_bf16 v[26:29], v[66:69], v[232:235], v[26:29]
	v_mfma_f32_16x16x32_bf16 v[14:17], v[58:61], v[240:243], v[14:17]
	v_mfma_f32_16x16x32_bf16 v[10:13], v[66:69], v[240:243], v[10:13]
	v_mfma_f32_16x16x32_bf16 v[78:81], v[62:65], v[220:223], v[78:81]
	v_mfma_f32_16x16x32_bf16 v[74:77], v[70:73], v[220:223], v[74:77]
	v_mfma_f32_16x16x32_bf16 v[46:49], v[62:65], v[228:231], v[46:49]
	v_mfma_f32_16x16x32_bf16 v[42:45], v[70:73], v[228:231], v[42:45]
	v_mfma_f32_16x16x32_bf16 v[30:33], v[62:65], v[236:239], v[30:33]
	v_mfma_f32_16x16x32_bf16 v[26:29], v[70:73], v[236:239], v[26:29]
	v_mfma_f32_16x16x32_bf16 v[14:17], v[62:65], v[244:247], v[14:17]
	v_mfma_f32_16x16x32_bf16 v[10:13], v[70:73], v[244:247], v[10:13]
	s_setprio 0
	s_setprio 1
	v_mfma_f32_16x16x32_bf16 v[50:53], v[156:159], v[216:219], v[50:53]
	v_mfma_f32_16x16x32_bf16 v[62:65], v[170:173], v[220:223], v[50:53]
	v_mfma_f32_16x16x32_bf16 v[50:53], v[174:177], v[216:219], v[54:57]
	v_mfma_f32_16x16x32_bf16 v[38:41], v[156:159], v[224:227], v[38:41]
	v_mfma_f32_16x16x32_bf16 v[34:37], v[174:177], v[224:227], v[34:37]
	v_mfma_f32_16x16x32_bf16 v[22:25], v[156:159], v[232:235], v[22:25]
	v_mfma_f32_16x16x32_bf16 v[18:21], v[174:177], v[232:235], v[18:21]
	v_mfma_f32_16x16x32_bf16 v[6:9], v[156:159], v[240:243], v[6:9]
	v_mfma_f32_16x16x32_bf16 v[2:5], v[174:177], v[240:243], v[2:5]
	v_mfma_f32_16x16x32_bf16 v[58:61], v[178:181], v[220:223], v[50:53]
	v_mfma_f32_16x16x32_bf16 v[38:41], v[170:173], v[228:231], v[38:41]
	v_mfma_f32_16x16x32_bf16 v[34:37], v[178:181], v[228:231], v[34:37]
	v_mfma_f32_16x16x32_bf16 v[22:25], v[170:173], v[236:239], v[22:25]
	v_mfma_f32_16x16x32_bf16 v[18:21], v[178:181], v[236:239], v[18:21]
	v_mfma_f32_16x16x32_bf16 v[6:9], v[170:173], v[244:247], v[6:9]
	v_mfma_f32_16x16x32_bf16 v[2:5], v[178:181], v[244:247], v[2:5]
	s_setprio 0
	s_barrier
	s_add_i32 s16, s16, 2
	s_add_u32 s68, s68, 0x100
	s_addc_u32 s69, s69, 0
	s_add_u32 vcc_hi, vcc_hi, 0x100
	s_addc_u32 s76, s76, 0
	s_cmp_gt_u32 s16, 13
	s_cbranch_scc0 .LBB0_414
	s_and_b64 vcc, exec, s[2:3]
	s_cbranch_vccz .LBB0_417
	s_barrier

; #define PG8_STAGE(bufoff, gbase, voff) do { _Pragma("unroll") for (int _i = 0; _i < 2; ++_i) \
;         __builtin_amdgcn_global_load_lds((const unsigned*)((const char*)(gbase) + (voff)[_i]), (LAS unsigned*)(lds + (bufoff) + ldsw + _i * 8192), 16, 0, 0); } while (0)
; #define PG8_LDA(dst, b, h) do { _Pragma("unroll") for (int m = 0; m < 4; ++m) _Pragma("unroll") for (int k = 0; k < 2; ++k) dst[m][k] = *(const LAS bf16x8*)(lds + PG8_SA(b, h) + aoff + m * 2048 + k * 1024); } while (0)
; #define PG8_LDB(dst, b, h) do { _Pragma("unroll") for (int n = 0; n < 2; ++n) _Pragma("unroll") for (int k = 0; k < 2; ++k) dst[n][k] = *(const LAS bf16x8*)(lds + PG8_SB(b, h) + boff + n * 2048 + k * 1024); } while (0)
; #define PG8_MMA(ai, bj, At, Bt) do { __builtin_amdgcn_s_setprio(1); _Pragma("unroll") for (int m = 0; m < 4; ++m) _Pragma("unroll") for (int n = 0; n < 2; ++n) _Pragma("unroll") for (int k = 0; k < 2; ++k) \
;         acc[ai][bj][m][n] = __builtin_amdgcn_mfma_f32_16x16x32_bf16(Bt[n][k], At[m][k], acc[ai][bj][m][n], 0, 0, 0); __builtin_amdgcn_s_setprio(0); } while (0)
; #define PG8_WAIT_V(n) asm volatile("s_waitcnt vmcnt(" #n ")" ::: "memory")
; #define PG8_WAIT_L(n) asm volatile("s_waitcnt lgkmcnt(" #n ")" ::: "memory")
; #define PG8_BAR __builtin_amdgcn_s_barrier()
; #define PG8_SCHED __builtin_amdgcn_sched_barrier(0)
; template <class Epi>
; __device__ __forceinline__ void gemm_phase(LAS unsigned char* lds, const int tid, const Gemm g, const StaticOrder& S, const Epi& E) {
;     ...
;             const bool last = (t == nt - 2);
;             const char* a1 = cA + (size_t)(t + 1) * kstep;
;             const char* a2 = last ? nA : cA + (size_t)(t + 2) * kstep; const char* b2 = last ? nB : cB + (size_t)(t + 2) * kstep;
;             const char* a3 = a2 + kstep; const char* b3 = b2 + kstep;
;             PG8_LDB(B0, 0, 0); PG8_LDB(B1, 0, 1); PG8_SCHED; PG8_LDA(At, 0, 0); PG8_STAGE(PG8_SA(1, 1), a1 + hstepA, voffA);
;             PG8_WAIT_V(8); PG8_WAIT_L(0); PG8_BAR; PG8_MMA(0, 0, At, B0); PG8_MMA(0, 1, At, B1); PG8_BAR; PG8_SCHED;
;             PG8_LDA(At, 0, 1); PG8_STAGE(PG8_SB(0, 0), b2, voffB); PG8_STAGE(PG8_SB(0, 1), b2 + hstepB, voffB); PG8_STAGE(PG8_SA(0, 0), a2, voffA);
.LBB0_945:
	v_lshl_add_u64 v[162:163], s[72:73], 0, v[158:159]
	s_add_i32 m0, s71, 0xc000
	s_nop 0
	global_load_lds_dwordx4 v[162:163], off
	v_lshl_add_u64 v[162:163], s[72:73], 0, v[160:161]
	s_add_i32 m0, s71, 0xe000
	s_nop 0
	global_load_lds_dwordx4 v[162:163], off
	s_add_u32 s30, s72, 0xfffc0080
	s_addc_u32 s31, s73, -1
	s_add_i32 s76, 0, 0x10000
	s_cmp_eq_u32 vcc_hi, 12
	s_cselect_b32 s75, s9, s31
	s_cselect_b32 s74, s27, s30
	v_add_u32_e32 v0, s76, v178
	s_cselect_b32 s31, s7, vcc_lo
	s_cselect_b32 s30, s28, s65
	s_add_i32 s0, 0, 0x14000
	ds_read_b128 v[18:21], v0
	ds_read_b128 v[22:25], v0 offset:1024
	ds_read_b128 v[26:29], v0 offset:2048
	ds_read_b128 v[30:33], v0 offset:3072
	v_add_u32_e32 v0, s0, v178
	ds_read_b128 v[170:173], v0
	ds_read_b128 v[174:177], v0 offset:1024
	ds_read_b128 v[190:193], v0 offset:2048
	ds_read_b128 v[194:197], v0 offset:3072
	ds_read_b128 v[198:201], v189
	ds_read_b128 v[210:213], v189 offset:1024
	ds_read_b128 v[214:217], v189 offset:2048
	ds_read_b128 v[218:221], v189 offset:3072
	ds_read_b128 v[222:225], v189 offset:4096
	ds_read_b128 v[226:229], v189 offset:5120
	ds_read_b128 v[230:233], v189 offset:6144
	ds_read_b128 v[234:237], v189 offset:7168
	s_waitcnt vmcnt(8)
	s_waitcnt lgkmcnt(0)
	s_barrier
	s_setprio 1
	s_waitcnt lgkmcnt(0)
	v_mfma_f32_16x16x32_bf16 v[142:145], v[18:21], v[198:201], v[142:145]
	v_mfma_f32_16x16x32_bf16 v[138:141], v[26:29], v[198:201], v[138:141]
	v_mfma_f32_16x16x32_bf16 v[126:129], v[18:21], v[214:217], v[126:129]
	v_mfma_f32_16x16x32_bf16 v[122:125], v[26:29], v[214:217], v[122:125]
	v_mfma_f32_16x16x32_bf16 v[110:113], v[18:21], v[222:225], v[110:113]
	v_mfma_f32_16x16x32_bf16 v[106:109], v[26:29], v[222:225], v[106:109]
	v_mfma_f32_16x16x32_bf16 v[94:97], v[18:21], v[230:233], v[94:97]
	v_mfma_f32_16x16x32_bf16 v[90:93], v[26:29], v[230:233], v[90:93]
	v_mfma_f32_16x16x32_bf16 v[142:145], v[22:25], v[210:213], v[142:145]
	v_mfma_f32_16x16x32_bf16 v[138:141], v[30:33], v[210:213], v[138:141]
	v_mfma_f32_16x16x32_bf16 v[126:129], v[22:25], v[218:221], v[126:129]
	v_mfma_f32_16x16x32_bf16 v[122:125], v[30:33], v[218:221], v[122:125]
	v_mfma_f32_16x16x32_bf16 v[110:113], v[22:25], v[226:229], v[110:113]
	v_mfma_f32_16x16x32_bf16 v[106:109], v[30:33], v[226:229], v[106:109]
	v_mfma_f32_16x16x32_bf16 v[94:97], v[22:25], v[234:237], v[94:97]
	v_mfma_f32_16x16x32_bf16 v[90:93], v[30:33], v[234:237], v[90:93]
	s_setprio 0
	s_setprio 1
	v_mfma_f32_16x16x32_bf16 v[134:137], v[170:173], v[198:201], v[134:137]
	v_mfma_f32_16x16x32_bf16 v[130:133], v[190:193], v[198:201], v[130:133]
	v_mfma_f32_16x16x32_bf16 v[118:121], v[170:173], v[214:217], v[118:121]
	v_mfma_f32_16x16x32_bf16 v[114:117], v[190:193], v[214:217], v[114:117]
	v_mfma_f32_16x16x32_bf16 v[102:105], v[170:173], v[222:225], v[102:105]
	v_mfma_f32_16x16x32_bf16 v[98:101], v[190:193], v[222:225], v[98:101]
	v_mfma_f32_16x16x32_bf16 v[86:89], v[170:173], v[230:233], v[86:89]
	v_mfma_f32_16x16x32_bf16 v[82:85], v[190:193], v[230:233], v[82:85]
	v_mfma_f32_16x16x32_bf16 v[134:137], v[174:177], v[210:213], v[134:137]
	v_mfma_f32_16x16x32_bf16 v[130:133], v[194:197], v[210:213], v[130:133]
	v_mfma_f32_16x16x32_bf16 v[118:121], v[174:177], v[218:221], v[118:121]
	v_mfma_f32_16x16x32_bf16 v[114:117], v[194:197], v[218:221], v[114:117]
	v_mfma_f32_16x16x32_bf16 v[102:105], v[174:177], v[226:229], v[102:105]
	v_mfma_f32_16x16x32_bf16 v[98:101], v[194:197], v[226:229], v[98:101]
	v_mfma_f32_16x16x32_bf16 v[86:89], v[174:177], v[234:237], v[86:89]
	v_mfma_f32_16x16x32_bf16 v[82:85], v[194:197], v[234:237], v[82:85]
	s_setprio 0
	s_barrier
	s_add_i32 s1, s76, s93
	v_lshl_add_u64 v[162:163], s[30:31], 0, v[150:151]
	s_mov_b32 m0, s1
	s_nop 0
	global_load_lds_dwordx4 v[162:163], off
	s_add_i32 m0, s1, 0x2000
	s_add_u32 s76, s30, 0x40000
	v_lshl_add_u64 v[164:165], s[30:31], 0, v[154:155]
	s_addc_u32 s77, s31, 0
	s_add_i32 s0, s0, s93
	global_load_lds_dwordx4 v[164:165], off
	v_lshl_add_u64 v[202:203], s[76:77], 0, v[150:151]
	s_mov_b32 m0, s0
	v_lshl_add_u64 v[206:207], s[74:75], 0, v[152:153]
	global_load_lds_dwordx4 v[202:203], off
	v_lshl_add_u64 v[202:203], s[76:77], 0, v[154:155]
	s_add_i32 m0, s0, 0x2000
	s_nop 0
	global_load_lds_dwordx4 v[202:203], off
	v_lshl_add_u64 v[202:203], s[74:75], 0, v[148:149]
	s_mov_b32 m0, s71
	s_nop 0
	global_load_lds_dwordx4 v[202:203], off
	s_mov_b32 m0, s88
	s_nop 0
	global_load_lds_dwordx4 v[206:207], off
	ds_read_b128 v[198:201], v189 offset:16384
	ds_read_b128 v[210:213], v189 offset:17408
	ds_read_b128 v[214:217], v189 offset:18432
	ds_read_b128 v[218:221], v189 offset:19456
	ds_read_b128 v[222:225], v189 offset:20480
	ds_read_b128 v[226:229], v189 offset:21504
	ds_read_b128 v[230:233], v189 offset:22528
	ds_read_b128 v[234:237], v189 offset:23552
	s_waitcnt vmcnt(8)
	s_waitcnt lgkmcnt(0)
	s_barrier
; #define PG8_STAGE(bufoff, gbase, voff) do { _Pragma("unroll") for (int _i = 0; _i < 2; ++_i) \
;         __builtin_amdgcn_global_load_lds((const unsigned*)((const char*)(gbase) + (voff)[_i]), (LAS unsigned*)(lds + (bufoff) + ldsw + _i * 8192), 16, 0, 0); } while (0)
; #define PG8_LDA(dst, b, h) do { _Pragma("unroll") for (int m = 0; m < 4; ++m) _Pragma("unroll") for (int k = 0; k < 2; ++k) dst[m][k] = *(const LAS bf16x8*)(lds + PG8_SA(b, h) + aoff + m * 2048 + k * 1024); } while (0)
; #define PG8_LDB(dst, b, h) do { _Pragma("unroll") for (int n = 0; n < 2; ++n) _Pragma("unroll") for (int k = 0; k < 2; ++k) dst[n][k] = *(const LAS bf16x8*)(lds + PG8_SB(b, h) + boff + n * 2048 + k * 1024); } while (0)
; #define PG8_MMA(ai, bj, At, Bt) do { __builtin_amdgcn_s_setprio(1); _Pragma("unroll") for (int m = 0; m < 4; ++m) _Pragma("unroll") for (int n = 0; n < 2; ++n) _Pragma("unroll") for (int k = 0; k < 2; ++k) \
;         acc[ai][bj][m][n] = __builtin_amdgcn_mfma_f32_16x16x32_bf16(Bt[n][k], At[m][k], acc[ai][bj][m][n], 0, 0, 0); __builtin_amdgcn_s_setprio(0); } while (0)
; #define PG8_WAIT_V(n) asm volatile("s_waitcnt vmcnt(" #n ")" ::: "memory")
; #define PG8_WAIT_L(n) asm volatile("s_waitcnt lgkmcnt(" #n ")" ::: "memory")
; #define PG8_BAR __builtin_amdgcn_s_barrier()
; #define PG8_SCHED __builtin_amdgcn_sched_barrier(0)
; template <class Epi>
; __device__ __forceinline__ void gemm_phase(LAS unsigned char* lds, const int tid, const Gemm g, const StaticOrder& S, const Epi& E) {
;     ...
;             PG8_WAIT_V(8); PG8_WAIT_L(0); PG8_BAR; PG8_MMA(1, 0, At, B0); PG8_MMA(1, 1, At, B1); PG8_BAR; PG8_SCHED;
;             PG8_LDB(B0, 1, 0); PG8_LDB(B1, 1, 1); PG8_SCHED; PG8_LDA(At, 1, 0); PG8_STAGE(PG8_SA(0, 1), a2 + hstepA, voffA);
;             PG8_WAIT_V(8); PG8_WAIT_L(0); PG8_BAR; PG8_MMA(0, 0, At, B0); PG8_MMA(0, 1, At, B1); PG8_BAR; PG8_SCHED;
	s_setprio 1
	s_waitcnt lgkmcnt(0)
	v_mfma_f32_16x16x32_bf16 v[78:81], v[18:21], v[198:201], v[78:81]
	v_mfma_f32_16x16x32_bf16 v[74:77], v[26:29], v[198:201], v[74:77]
	v_mfma_f32_16x16x32_bf16 v[62:65], v[18:21], v[214:217], v[62:65]
	v_mfma_f32_16x16x32_bf16 v[58:61], v[26:29], v[214:217], v[58:61]
	v_mfma_f32_16x16x32_bf16 v[46:49], v[18:21], v[222:225], v[46:49]
	v_mfma_f32_16x16x32_bf16 v[42:45], v[26:29], v[222:225], v[42:45]
	v_mfma_f32_16x16x32_bf16 v[14:17], v[18:21], v[230:233], v[14:17]
	v_mfma_f32_16x16x32_bf16 v[10:13], v[26:29], v[230:233], v[10:13]
	v_mfma_f32_16x16x32_bf16 v[78:81], v[22:25], v[210:213], v[78:81]
	v_mfma_f32_16x16x32_bf16 v[74:77], v[30:33], v[210:213], v[74:77]
	v_mfma_f32_16x16x32_bf16 v[62:65], v[22:25], v[218:221], v[62:65]
	v_mfma_f32_16x16x32_bf16 v[58:61], v[30:33], v[218:221], v[58:61]
	v_mfma_f32_16x16x32_bf16 v[46:49], v[22:25], v[226:229], v[46:49]
	v_mfma_f32_16x16x32_bf16 v[42:45], v[30:33], v[226:229], v[42:45]
	v_mfma_f32_16x16x32_bf16 v[14:17], v[22:25], v[234:237], v[14:17]
	v_mfma_f32_16x16x32_bf16 v[10:13], v[30:33], v[234:237], v[10:13]
	s_setprio 0
	s_setprio 1
	v_mfma_f32_16x16x32_bf16 v[38:41], v[170:173], v[222:225], v[38:41]
	v_mfma_f32_16x16x32_bf16 v[34:37], v[190:193], v[222:225], v[34:37]
	v_mfma_f32_16x16x32_bf16 v[6:9], v[170:173], v[230:233], v[6:9]
	v_mfma_f32_16x16x32_bf16 v[2:5], v[190:193], v[230:233], v[2:5]
	v_mfma_f32_16x16x32_bf16 v[18:21], v[170:173], v[198:201], v[70:73]
	v_mfma_f32_16x16x32_bf16 v[22:25], v[190:193], v[198:201], v[66:69]
	v_mfma_f32_16x16x32_bf16 v[26:29], v[170:173], v[214:217], v[54:57]
	v_mfma_f32_16x16x32_bf16 v[30:33], v[190:193], v[214:217], v[50:53]
	v_mfma_f32_16x16x32_bf16 v[38:41], v[174:177], v[226:229], v[38:41]
	v_mfma_f32_16x16x32_bf16 v[34:37], v[194:197], v[226:229], v[34:37]
	v_mfma_f32_16x16x32_bf16 v[6:9], v[174:177], v[234:237], v[6:9]
	v_mfma_f32_16x16x32_bf16 v[2:5], v[194:197], v[234:237], v[2:5]
	v_mfma_f32_16x16x32_bf16 v[18:21], v[174:177], v[210:213], v[18:21]
	v_mfma_f32_16x16x32_bf16 v[22:25], v[194:197], v[210:213], v[22:25]
	v_mfma_f32_16x16x32_bf16 v[26:29], v[174:177], v[218:221], v[26:29]
	v_mfma_f32_16x16x32_bf16 v[30:33], v[194:197], v[218:221], v[30:33]
	s_setprio 0
	s_barrier
	s_add_u32 s74, s74, 0x40000
	s_addc_u32 s75, s75, 0
	s_mov_b32 m0, s83
	v_lshl_add_u64 v[238:239], s[74:75], 0, v[148:149]
	global_load_lds_dwordx4 v[238:239], off
	v_lshl_add_u64 v[238:239], s[74:75], 0, v[152:153]
	s_mov_b32 m0, s16
	s_nop 0
	global_load_lds_dwordx4 v[238:239], off
	s_add_i32 s0, 0, 0x18000
	v_add_u32_e32 v0, s0, v178
	s_add_i32 s1, 0, 0x1c000
	ds_read_b128 v[50:53], v0
	ds_read_b128 v[54:57], v0 offset:1024
	ds_read_b128 v[66:69], v0 offset:2048
	ds_read_b128 v[70:73], v0 offset:3072
	v_add_u32_e32 v0, s1, v178
	ds_read_b128 v[170:173], v0
	ds_read_b128 v[174:177], v0 offset:1024
	ds_read_b128 v[190:193], v0 offset:2048
	ds_read_b128 v[194:197], v0 offset:3072
	ds_read_b128 v[198:201], v189 offset:32768
	ds_read_b128 v[210:213], v189 offset:33792
	ds_read_b128 v[214:217], v189 offset:34816
	ds_read_b128 v[218:221], v189 offset:35840
	ds_read_b128 v[222:225], v189 offset:36864
	ds_read_b128 v[226:229], v189 offset:37888
	ds_read_b128 v[230:233], v189 offset:38912
	ds_read_b128 v[234:237], v189 offset:39936
	s_waitcnt vmcnt(8)
	s_waitcnt lgkmcnt(0)
	s_barrier
	s_setprio 1
	s_waitcnt lgkmcnt(0)
	v_mfma_f32_16x16x32_bf16 v[142:145], v[50:53], v[198:201], v[142:145]
	v_mfma_f32_16x16x32_bf16 v[138:141], v[66:69], v[198:201], v[138:141]
	v_mfma_f32_16x16x32_bf16 v[126:129], v[50:53], v[214:217], v[126:129]
	v_mfma_f32_16x16x32_bf16 v[122:125], v[66:69], v[214:217], v[122:125]
	v_mfma_f32_16x16x32_bf16 v[110:113], v[50:53], v[222:225], v[110:113]
	v_mfma_f32_16x16x32_bf16 v[106:109], v[66:69], v[222:225], v[106:109]
	v_mfma_f32_16x16x32_bf16 v[94:97], v[50:53], v[230:233], v[94:97]
	v_mfma_f32_16x16x32_bf16 v[90:93], v[66:69], v[230:233], v[90:93]
	v_mfma_f32_16x16x32_bf16 v[142:145], v[54:57], v[210:213], v[142:145]
	v_mfma_f32_16x16x32_bf16 v[138:141], v[70:73], v[210:213], v[138:141]
	v_mfma_f32_16x16x32_bf16 v[126:129], v[54:57], v[218:221], v[126:129]
	v_mfma_f32_16x16x32_bf16 v[122:125], v[70:73], v[218:221], v[122:125]
	v_mfma_f32_16x16x32_bf16 v[110:113], v[54:57], v[226:229], v[110:113]
	v_mfma_f32_16x16x32_bf16 v[106:109], v[70:73], v[226:229], v[106:109]
	v_mfma_f32_16x16x32_bf16 v[94:97], v[54:57], v[234:237], v[94:97]
	v_mfma_f32_16x16x32_bf16 v[90:93], v[70:73], v[234:237], v[90:93]
	s_setprio 0
	s_setprio 1
	v_mfma_f32_16x16x32_bf16 v[134:137], v[170:173], v[198:201], v[134:137]
	v_mfma_f32_16x16x32_bf16 v[130:133], v[190:193], v[198:201], v[130:133]
	v_mfma_f32_16x16x32_bf16 v[118:121], v[170:173], v[214:217], v[118:121]
	v_mfma_f32_16x16x32_bf16 v[114:117], v[190:193], v[214:217], v[114:117]
	v_mfma_f32_16x16x32_bf16 v[102:105], v[170:173], v[222:225], v[102:105]
	v_mfma_f32_16x16x32_bf16 v[98:101], v[190:193], v[222:225], v[98:101]
	v_mfma_f32_16x16x32_bf16 v[86:89], v[170:173], v[230:233], v[86:89]
	v_mfma_f32_16x16x32_bf16 v[82:85], v[190:193], v[230:233], v[82:85]
	v_mfma_f32_16x16x32_bf16 v[134:137], v[174:177], v[210:213], v[134:137]
	v_mfma_f32_16x16x32_bf16 v[130:133], v[194:197], v[210:213], v[130:133]
	v_mfma_f32_16x16x32_bf16 v[118:121], v[174:177], v[218:221], v[118:121]
	v_mfma_f32_16x16x32_bf16 v[114:117], v[194:197], v[218:221], v[114:117]
	v_mfma_f32_16x16x32_bf16 v[102:105], v[174:177], v[226:229], v[102:105]
	v_mfma_f32_16x16x32_bf16 v[98:101], v[194:197], v[226:229], v[98:101]
	v_mfma_f32_16x16x32_bf16 v[86:89], v[174:177], v[234:237], v[86:89]
	v_mfma_f32_16x16x32_bf16 v[82:85], v[194:197], v[234:237], v[82:85]
	s_setprio 0
	s_barrier
; #define PG8_STAGE(bufoff, gbase, voff) do { _Pragma("unroll") for (int _i = 0; _i < 2; ++_i) \
;         __builtin_amdgcn_global_load_lds((const unsigned*)((const char*)(gbase) + (voff)[_i]), (LAS unsigned*)(lds + (bufoff) + ldsw + _i * 8192), 16, 0, 0); } while (0)
; #define PG8_LDA(dst, b, h) do { _Pragma("unroll") for (int m = 0; m < 4; ++m) _Pragma("unroll") for (int k = 0; k < 2; ++k) dst[m][k] = *(const LAS bf16x8*)(lds + PG8_SA(b, h) + aoff + m * 2048 + k * 1024); } while (0)
; #define PG8_MMA(ai, bj, At, Bt) do { __builtin_amdgcn_s_setprio(1); _Pragma("unroll") for (int m = 0; m < 4; ++m) _Pragma("unroll") for (int n = 0; n < 2; ++n) _Pragma("unroll") for (int k = 0; k < 2; ++k) \
;         acc[ai][bj][m][n] = __builtin_amdgcn_mfma_f32_16x16x32_bf16(Bt[n][k], At[m][k], acc[ai][bj][m][n], 0, 0, 0); __builtin_amdgcn_s_setprio(0); } while (0)
; #define PG8_WAIT_V(n) asm volatile("s_waitcnt vmcnt(" #n ")" ::: "memory")
; #define PG8_WAIT_L(n) asm volatile("s_waitcnt lgkmcnt(" #n ")" ::: "memory")
; #define PG8_BAR __builtin_amdgcn_s_barrier()
; #define PG8_SCHED __builtin_amdgcn_sched_barrier(0)
; template <class Epi>
; __device__ __forceinline__ void gemm_phase(LAS unsigned char* lds, const int tid, const Gemm g, const StaticOrder& S, const Epi& E) {
;     ...
;             PG8_LDA(At, 1, 1); PG8_STAGE(PG8_SB(1, 0), b3, voffB); PG8_STAGE(PG8_SB(1, 1), b3 + hstepB, voffB); PG8_STAGE(PG8_SA(1, 0), a3, voffA);
;             PG8_WAIT_V(8); PG8_WAIT_L(0); PG8_BAR; PG8_MMA(1, 0, At, B0); PG8_MMA(1, 1, At, B1); PG8_BAR; PG8_SCHED;
;         }
	s_add_i32 s0, s0, s93
	v_lshl_add_u64 v[162:163], v[162:163], 0, s[36:37]
	s_mov_b32 m0, s0
	s_nop 0
	global_load_lds_dwordx4 v[162:163], off
	s_add_i32 m0, s0, 0x2000
	s_add_u32 s30, s30, 0x40080
	v_lshl_add_u64 v[162:163], v[164:165], 0, s[36:37]
	s_addc_u32 s31, s31, 0
	s_add_i32 s0, s1, s93
	global_load_lds_dwordx4 v[162:163], off
	v_lshl_add_u64 v[162:163], s[30:31], 0, v[150:151]
	s_mov_b32 m0, s0
	s_nop 0
	global_load_lds_dwordx4 v[162:163], off
	v_lshl_add_u64 v[162:163], s[30:31], 0, v[154:155]
	s_add_i32 m0, s0, 0x2000
	s_nop 0
	global_load_lds_dwordx4 v[162:163], off
	v_lshl_add_u64 v[162:163], v[202:203], 0, s[36:37]
	s_mov_b32 m0, s92
	s_nop 0
	global_load_lds_dwordx4 v[162:163], off
	v_lshl_add_u64 v[162:163], v[206:207], 0, s[36:37]
	s_mov_b32 m0, s89
	s_nop 0
	global_load_lds_dwordx4 v[162:163], off
	ds_read_b128 v[198:201], v189 offset:49152
	ds_read_b128 v[210:213], v189 offset:50176
	ds_read_b128 v[214:217], v189 offset:51200
	ds_read_b128 v[218:221], v189 offset:52224
	ds_read_b128 v[222:225], v189 offset:53248
	ds_read_b128 v[226:229], v189 offset:54272
	ds_read_b128 v[230:233], v189 offset:55296
	ds_read_b128 v[234:237], v189 offset:56320
	s_waitcnt vmcnt(8)
	s_waitcnt lgkmcnt(0)
	s_barrier
	s_setprio 1
	s_waitcnt lgkmcnt(0)
	v_mfma_f32_16x16x32_bf16 v[78:81], v[50:53], v[198:201], v[78:81]
	v_mfma_f32_16x16x32_bf16 v[74:77], v[66:69], v[198:201], v[74:77]
	v_mfma_f32_16x16x32_bf16 v[62:65], v[50:53], v[214:217], v[62:65]
	v_mfma_f32_16x16x32_bf16 v[58:61], v[66:69], v[214:217], v[58:61]
	v_mfma_f32_16x16x32_bf16 v[46:49], v[50:53], v[222:225], v[46:49]
	v_mfma_f32_16x16x32_bf16 v[42:45], v[66:69], v[222:225], v[42:45]
	v_mfma_f32_16x16x32_bf16 v[14:17], v[50:53], v[230:233], v[14:17]
	v_mfma_f32_16x16x32_bf16 v[10:13], v[66:69], v[230:233], v[10:13]
	v_mfma_f32_16x16x32_bf16 v[78:81], v[54:57], v[210:213], v[78:81]
	v_mfma_f32_16x16x32_bf16 v[74:77], v[70:73], v[210:213], v[74:77]
	v_mfma_f32_16x16x32_bf16 v[62:65], v[54:57], v[218:221], v[62:65]
	v_mfma_f32_16x16x32_bf16 v[58:61], v[70:73], v[218:221], v[58:61]
	v_mfma_f32_16x16x32_bf16 v[46:49], v[54:57], v[226:229], v[46:49]
	v_mfma_f32_16x16x32_bf16 v[42:45], v[70:73], v[226:229], v[42:45]
	v_mfma_f32_16x16x32_bf16 v[14:17], v[54:57], v[234:237], v[14:17]
	v_mfma_f32_16x16x32_bf16 v[10:13], v[70:73], v[234:237], v[10:13]
	s_setprio 0
	s_setprio 1
	v_mfma_f32_16x16x32_bf16 v[18:21], v[170:173], v[198:201], v[18:21]
	v_mfma_f32_16x16x32_bf16 v[70:73], v[174:177], v[210:213], v[18:21]
	v_mfma_f32_16x16x32_bf16 v[18:21], v[190:193], v[198:201], v[22:25]
	v_mfma_f32_16x16x32_bf16 v[66:69], v[194:197], v[210:213], v[18:21]
	v_mfma_f32_16x16x32_bf16 v[18:21], v[170:173], v[214:217], v[26:29]
	v_mfma_f32_16x16x32_bf16 v[54:57], v[174:177], v[218:221], v[18:21]
	v_mfma_f32_16x16x32_bf16 v[18:21], v[190:193], v[214:217], v[30:33]
	v_mfma_f32_16x16x32_bf16 v[50:53], v[194:197], v[218:221], v[18:21]
	v_mfma_f32_16x16x32_bf16 v[18:21], v[170:173], v[222:225], v[38:41]
	v_mfma_f32_16x16x32_bf16 v[38:41], v[174:177], v[226:229], v[18:21]
	v_mfma_f32_16x16x32_bf16 v[18:21], v[190:193], v[222:225], v[34:37]
	v_mfma_f32_16x16x32_bf16 v[6:9], v[170:173], v[230:233], v[6:9]
	v_mfma_f32_16x16x32_bf16 v[2:5], v[190:193], v[230:233], v[2:5]
	v_mfma_f32_16x16x32_bf16 v[34:37], v[194:197], v[226:229], v[18:21]
	v_mfma_f32_16x16x32_bf16 v[6:9], v[174:177], v[234:237], v[6:9]
	v_mfma_f32_16x16x32_bf16 v[2:5], v[194:197], v[234:237], v[2:5]
	s_setprio 0
	s_barrier
	s_add_i32 vcc_hi, vcc_hi, 2
	s_add_u32 s72, s72, 0x100
	s_addc_u32 s73, s73, 0
	s_add_u32 s65, s65, 0x100
	s_addc_u32 vcc_lo, vcc_lo, 0
	s_cmp_gt_u32 vcc_hi, 13
	s_cbranch_scc0 .LBB0_945
	s_and_b64 vcc, exec, s[4:5]
	s_cbranch_vccz .LBB0_948
	s_barrier

; #define PG8_STAGE(bufoff, gbase, voff) do { _Pragma("unroll") for (int _i = 0; _i < 2; ++_i) \
;         __builtin_amdgcn_global_load_lds((const unsigned*)((const char*)(gbase) + (voff)[_i]), (LAS unsigned*)(lds + (bufoff) + ldsw + _i * 8192), 16, 0, 0); } while (0)
; #define PG8_LDA(dst, b, h) do { _Pragma("unroll") for (int m = 0; m < 4; ++m) _Pragma("unroll") for (int k = 0; k < 2; ++k) dst[m][k] = *(const LAS bf16x8*)(lds + PG8_SA(b, h) + aoff + m * 2048 + k * 1024); } while (0)
; #define PG8_LDB(dst, b, h) do { _Pragma("unroll") for (int n = 0; n < 2; ++n) _Pragma("unroll") for (int k = 0; k < 2; ++k) dst[n][k] = *(const LAS bf16x8*)(lds + PG8_SB(b, h) + boff + n * 2048 + k * 1024); } while (0)
; #define PG8_MMA(ai, bj, At, Bt) do { __builtin_amdgcn_s_setprio(1); _Pragma("unroll") for (int m = 0; m < 4; ++m) _Pragma("unroll") for (int n = 0; n < 2; ++n) _Pragma("unroll") for (int k = 0; k < 2; ++k) \
;         acc[ai][bj][m][n] = __builtin_amdgcn_mfma_f32_16x16x32_bf16(Bt[n][k], At[m][k], acc[ai][bj][m][n], 0, 0, 0); __builtin_amdgcn_s_setprio(0); } while (0)
; #define PG8_WAIT_V(n) asm volatile("s_waitcnt vmcnt(" #n ")" ::: "memory")
; #define PG8_WAIT_L(n) asm volatile("s_waitcnt lgkmcnt(" #n ")" ::: "memory")
; #define PG8_BAR __builtin_amdgcn_s_barrier()
; #define PG8_SCHED __builtin_amdgcn_sched_barrier(0)
; template <class Epi>
; __device__ __forceinline__ void gemm_phase(LAS unsigned char* lds, const int tid, const Gemm g, const StaticOrder& S, const Epi& E) {
;     ...
;             const bool last = (t == nt - 2);
;             const char* a1 = cA + (size_t)(t + 1) * kstep;
;             const char* a2 = last ? nA : cA + (size_t)(t + 2) * kstep; const char* b2 = last ? nB : cB + (size_t)(t + 2) * kstep;
;             const char* a3 = a2 + kstep; const char* b3 = b2 + kstep;
;             PG8_LDB(B0, 0, 0); PG8_LDB(B1, 0, 1); PG8_SCHED; PG8_LDA(At, 0, 0); PG8_STAGE(PG8_SA(1, 1), a1 + hstepA, voffA);
;             PG8_WAIT_V(8); PG8_WAIT_L(0); PG8_BAR; PG8_MMA(0, 0, At, B0); PG8_MMA(0, 1, At, B1); PG8_BAR; PG8_SCHED;
;             PG8_LDA(At, 0, 1); PG8_STAGE(PG8_SB(0, 0), b2, voffB); PG8_STAGE(PG8_SB(0, 1), b2 + hstepB, voffB); PG8_STAGE(PG8_SA(0, 0), a2, voffA);
.LBB0_1284:
	v_lshl_add_u64 v[144:145], s[66:67], 0, v[136:137]
	s_add_i32 m0, s71, 0xc000
	s_nop 0
	global_load_lds_dwordx4 v[144:145], off
	v_lshl_add_u64 v[144:145], s[66:67], 0, v[138:139]
	s_add_i32 m0, s71, 0xe000
	s_nop 0
	global_load_lds_dwordx4 v[144:145], off
	s_add_u32 s2, s66, 0xfff80080
	s_addc_u32 s3, s67, -1
	s_add_i32 vcc_hi, 0, 0x10000
	s_cmp_eq_u32 vcc_lo, 12
	s_cselect_b32 s69, s11, s3
	s_cselect_b32 s68, s88, s2
	v_add_u32_e32 v144, vcc_hi, v171
	s_cselect_b32 s31, s9, s93
	s_cselect_b32 s30, s89, s92
	s_add_i32 s0, 0, 0x14000
	ds_read_b128 v[140:143], v144
	ds_read_b128 v[176:179], v144 offset:1024
	ds_read_b128 v[180:183], v144 offset:2048
	ds_read_b128 v[184:187], v144 offset:3072
	v_add_u32_e32 v144, s0, v171
	ds_read_b128 v[188:191], v144
	ds_read_b128 v[192:195], v144 offset:1024
	ds_read_b128 v[196:199], v144 offset:2048
	ds_read_b128 v[200:203], v144 offset:3072
	ds_read_b128 v[210:213], v174
	ds_read_b128 v[214:217], v174 offset:1024
	ds_read_b128 v[218:221], v174 offset:2048
	ds_read_b128 v[222:225], v174 offset:3072
	ds_read_b128 v[226:229], v174 offset:4096
	ds_read_b128 v[230:233], v174 offset:5120
	ds_read_b128 v[234:237], v174 offset:6144
	ds_read_b128 v[238:241], v174 offset:7168
	s_waitcnt vmcnt(8)
	s_waitcnt lgkmcnt(0)
	s_barrier
	s_setprio 1
	s_waitcnt lgkmcnt(0)
	v_mfma_f32_16x16x32_bf16 v[126:129], v[140:143], v[210:213], v[126:129]
	v_mfma_f32_16x16x32_bf16 v[122:125], v[180:183], v[210:213], v[122:125]
	v_mfma_f32_16x16x32_bf16 v[118:121], v[140:143], v[218:221], v[118:121]
	v_mfma_f32_16x16x32_bf16 v[110:113], v[180:183], v[218:221], v[110:113]
	v_mfma_f32_16x16x32_bf16 v[94:97], v[140:143], v[226:229], v[94:97]
	v_mfma_f32_16x16x32_bf16 v[90:93], v[180:183], v[226:229], v[90:93]
	v_mfma_f32_16x16x32_bf16 v[86:89], v[140:143], v[234:237], v[86:89]
	v_mfma_f32_16x16x32_bf16 v[78:81], v[180:183], v[234:237], v[78:81]
	v_mfma_f32_16x16x32_bf16 v[126:129], v[176:179], v[214:217], v[126:129]
	v_mfma_f32_16x16x32_bf16 v[122:125], v[184:187], v[214:217], v[122:125]
	v_mfma_f32_16x16x32_bf16 v[118:121], v[176:179], v[222:225], v[118:121]
	v_mfma_f32_16x16x32_bf16 v[110:113], v[184:187], v[222:225], v[110:113]
	v_mfma_f32_16x16x32_bf16 v[94:97], v[176:179], v[230:233], v[94:97]
	v_mfma_f32_16x16x32_bf16 v[90:93], v[184:187], v[230:233], v[90:93]
	v_mfma_f32_16x16x32_bf16 v[86:89], v[176:179], v[238:241], v[86:89]
	v_mfma_f32_16x16x32_bf16 v[78:81], v[184:187], v[238:241], v[78:81]
	s_setprio 0
	s_setprio 1
	v_mfma_f32_16x16x32_bf16 v[114:117], v[188:191], v[210:213], v[114:117]
	v_mfma_f32_16x16x32_bf16 v[106:109], v[196:199], v[210:213], v[106:109]
	v_mfma_f32_16x16x32_bf16 v[102:105], v[188:191], v[218:221], v[102:105]
	v_mfma_f32_16x16x32_bf16 v[98:101], v[196:199], v[218:221], v[98:101]
	v_mfma_f32_16x16x32_bf16 v[82:85], v[188:191], v[226:229], v[82:85]
	v_mfma_f32_16x16x32_bf16 v[74:77], v[196:199], v[226:229], v[74:77]
	v_mfma_f32_16x16x32_bf16 v[70:73], v[188:191], v[234:237], v[70:73]
	v_mfma_f32_16x16x32_bf16 v[66:69], v[196:199], v[234:237], v[66:69]
	v_mfma_f32_16x16x32_bf16 v[114:117], v[192:195], v[214:217], v[114:117]
	v_mfma_f32_16x16x32_bf16 v[106:109], v[200:203], v[214:217], v[106:109]
	v_mfma_f32_16x16x32_bf16 v[102:105], v[192:195], v[222:225], v[102:105]
	v_mfma_f32_16x16x32_bf16 v[98:101], v[200:203], v[222:225], v[98:101]
	v_mfma_f32_16x16x32_bf16 v[82:85], v[192:195], v[230:233], v[82:85]
	v_mfma_f32_16x16x32_bf16 v[74:77], v[200:203], v[230:233], v[74:77]
	v_mfma_f32_16x16x32_bf16 v[70:73], v[192:195], v[238:241], v[70:73]
	v_mfma_f32_16x16x32_bf16 v[66:69], v[200:203], v[238:241], v[66:69]
	s_setprio 0
	s_barrier
	s_add_i32 s1, vcc_hi, s28
	v_lshl_add_u64 v[144:145], s[30:31], 0, v[0:1]
	s_mov_b32 m0, s1
	s_nop 0
	global_load_lds_dwordx4 v[144:145], off
	s_add_i32 m0, s1, 0x2000
	s_add_u32 s2, s30, 0x40000
	v_lshl_add_u64 v[162:163], s[30:31], 0, v[130:131]
	s_addc_u32 s3, s31, 0
	s_add_i32 s0, s0, s28
	global_load_lds_dwordx4 v[162:163], off
	v_lshl_add_u64 v[164:165], s[2:3], 0, v[0:1]
	s_mov_b32 m0, s0
	v_lshl_add_u64 v[206:207], s[68:69], 0, v[132:133]
	global_load_lds_dwordx4 v[164:165], off
	v_lshl_add_u64 v[164:165], s[2:3], 0, v[130:131]
	s_add_i32 m0, s0, 0x2000
	s_nop 0
	global_load_lds_dwordx4 v[164:165], off
	v_lshl_add_u64 v[164:165], s[68:69], 0, v[134:135]
	s_mov_b32 m0, s71
	s_nop 0
	global_load_lds_dwordx4 v[164:165], off
	s_mov_b32 m0, s72
	s_nop 0
	global_load_lds_dwordx4 v[206:207], off
	ds_read_b128 v[210:213], v174 offset:16384
	ds_read_b128 v[214:217], v174 offset:17408
	ds_read_b128 v[218:221], v174 offset:18432
	ds_read_b128 v[222:225], v174 offset:19456
	ds_read_b128 v[226:229], v174 offset:20480
	ds_read_b128 v[230:233], v174 offset:21504
	ds_read_b128 v[234:237], v174 offset:22528
	ds_read_b128 v[238:241], v174 offset:23552
	s_waitcnt vmcnt(8)
	s_waitcnt lgkmcnt(0)
	s_barrier
; #define PG8_STAGE(bufoff, gbase, voff) do { _Pragma("unroll") for (int _i = 0; _i < 2; ++_i) \
;         __builtin_amdgcn_global_load_lds((const unsigned*)((const char*)(gbase) + (voff)[_i]), (LAS unsigned*)(lds + (bufoff) + ldsw + _i * 8192), 16, 0, 0); } while (0)
; #define PG8_LDA(dst, b, h) do { _Pragma("unroll") for (int m = 0; m < 4; ++m) _Pragma("unroll") for (int k = 0; k < 2; ++k) dst[m][k] = *(const LAS bf16x8*)(lds + PG8_SA(b, h) + aoff + m * 2048 + k * 1024); } while (0)
; #define PG8_LDB(dst, b, h) do { _Pragma("unroll") for (int n = 0; n < 2; ++n) _Pragma("unroll") for (int k = 0; k < 2; ++k) dst[n][k] = *(const LAS bf16x8*)(lds + PG8_SB(b, h) + boff + n * 2048 + k * 1024); } while (0)
; #define PG8_MMA(ai, bj, At, Bt) do { __builtin_amdgcn_s_setprio(1); _Pragma("unroll") for (int m = 0; m < 4; ++m) _Pragma("unroll") for (int n = 0; n < 2; ++n) _Pragma("unroll") for (int k = 0; k < 2; ++k) \
;         acc[ai][bj][m][n] = __builtin_amdgcn_mfma_f32_16x16x32_bf16(Bt[n][k], At[m][k], acc[ai][bj][m][n], 0, 0, 0); __builtin_amdgcn_s_setprio(0); } while (0)
; #define PG8_WAIT_V(n) asm volatile("s_waitcnt vmcnt(" #n ")" ::: "memory")
; #define PG8_WAIT_L(n) asm volatile("s_waitcnt lgkmcnt(" #n ")" ::: "memory")
; #define PG8_BAR __builtin_amdgcn_s_barrier()
; #define PG8_SCHED __builtin_amdgcn_sched_barrier(0)
; template <class Epi>
; __device__ __forceinline__ void gemm_phase(LAS unsigned char* lds, const int tid, const Gemm g, const StaticOrder& S, const Epi& E) {
;     ...
;             PG8_WAIT_V(8); PG8_WAIT_L(0); PG8_BAR; PG8_MMA(1, 0, At, B0); PG8_MMA(1, 1, At, B1); PG8_BAR; PG8_SCHED;
;             PG8_LDB(B0, 1, 0); PG8_LDB(B1, 1, 1); PG8_SCHED; PG8_LDA(At, 1, 0); PG8_STAGE(PG8_SA(0, 1), a2 + hstepA, voffA);
;             PG8_WAIT_V(8); PG8_WAIT_L(0); PG8_BAR; PG8_MMA(0, 0, At, B0); PG8_MMA(0, 1, At, B1); PG8_BAR; PG8_SCHED;
	s_setprio 1
	s_waitcnt lgkmcnt(0)
	v_mfma_f32_16x16x32_bf16 v[62:65], v[140:143], v[210:213], v[62:65]
	v_mfma_f32_16x16x32_bf16 v[58:61], v[180:183], v[210:213], v[58:61]
	v_mfma_f32_16x16x32_bf16 v[54:57], v[140:143], v[218:221], v[54:57]
	v_mfma_f32_16x16x32_bf16 v[46:49], v[180:183], v[218:221], v[46:49]
	v_mfma_f32_16x16x32_bf16 v[30:33], v[140:143], v[226:229], v[30:33]
	v_mfma_f32_16x16x32_bf16 v[26:29], v[180:183], v[226:229], v[26:29]
	v_mfma_f32_16x16x32_bf16 v[22:25], v[140:143], v[234:237], v[22:25]
	v_mfma_f32_16x16x32_bf16 v[14:17], v[180:183], v[234:237], v[14:17]
	v_mfma_f32_16x16x32_bf16 v[62:65], v[176:179], v[214:217], v[62:65]
	v_mfma_f32_16x16x32_bf16 v[58:61], v[184:187], v[214:217], v[58:61]
	v_mfma_f32_16x16x32_bf16 v[54:57], v[176:179], v[222:225], v[54:57]
	v_mfma_f32_16x16x32_bf16 v[46:49], v[184:187], v[222:225], v[46:49]
	v_mfma_f32_16x16x32_bf16 v[30:33], v[176:179], v[230:233], v[30:33]
	v_mfma_f32_16x16x32_bf16 v[26:29], v[184:187], v[230:233], v[26:29]
	v_mfma_f32_16x16x32_bf16 v[22:25], v[176:179], v[238:241], v[22:25]
	v_mfma_f32_16x16x32_bf16 v[14:17], v[184:187], v[238:241], v[14:17]
	s_setprio 0
	s_setprio 1
	v_mfma_f32_16x16x32_bf16 v[50:53], v[188:191], v[210:213], v[50:53]
	v_mfma_f32_16x16x32_bf16 v[42:45], v[196:199], v[210:213], v[42:45]
	v_mfma_f32_16x16x32_bf16 v[38:41], v[188:191], v[218:221], v[38:41]
	v_mfma_f32_16x16x32_bf16 v[34:37], v[196:199], v[218:221], v[34:37]
	v_mfma_f32_16x16x32_bf16 v[18:21], v[188:191], v[226:229], v[18:21]
	v_mfma_f32_16x16x32_bf16 v[10:13], v[196:199], v[226:229], v[10:13]
	v_mfma_f32_16x16x32_bf16 v[6:9], v[188:191], v[234:237], v[6:9]
	v_mfma_f32_16x16x32_bf16 v[2:5], v[196:199], v[234:237], v[2:5]
	v_mfma_f32_16x16x32_bf16 v[50:53], v[192:195], v[214:217], v[50:53]
	v_mfma_f32_16x16x32_bf16 v[42:45], v[200:203], v[214:217], v[42:45]
	v_mfma_f32_16x16x32_bf16 v[38:41], v[192:195], v[222:225], v[38:41]
	v_mfma_f32_16x16x32_bf16 v[34:37], v[200:203], v[222:225], v[34:37]
	v_mfma_f32_16x16x32_bf16 v[18:21], v[192:195], v[230:233], v[18:21]
	v_mfma_f32_16x16x32_bf16 v[10:13], v[200:203], v[230:233], v[10:13]
	v_mfma_f32_16x16x32_bf16 v[6:9], v[192:195], v[238:241], v[6:9]
	v_mfma_f32_16x16x32_bf16 v[2:5], v[200:203], v[238:241], v[2:5]
	s_setprio 0
	s_barrier
	s_add_u32 s2, s68, 0x80000
	s_addc_u32 s3, s69, 0
	s_mov_b32 m0, s73
	v_lshl_add_u64 v[242:243], s[2:3], 0, v[134:135]
	global_load_lds_dwordx4 v[242:243], off
	v_lshl_add_u64 v[242:243], s[2:3], 0, v[132:133]
	s_mov_b32 m0, s74
	s_nop 0
	global_load_lds_dwordx4 v[242:243], off
	s_add_i32 s0, 0, 0x18000
	v_add_u32_e32 v175, s0, v171
	s_add_i32 s1, 0, 0x1c000
	ds_read_b128 v[140:143], v175
	ds_read_b128 v[176:179], v175 offset:1024
	ds_read_b128 v[180:183], v175 offset:2048
	ds_read_b128 v[184:187], v175 offset:3072
	v_add_u32_e32 v175, s1, v171
	ds_read_b128 v[188:191], v175
	ds_read_b128 v[192:195], v175 offset:1024
	ds_read_b128 v[196:199], v175 offset:2048
	ds_read_b128 v[200:203], v175 offset:3072
	ds_read_b128 v[210:213], v174 offset:32768
	ds_read_b128 v[214:217], v174 offset:33792
	ds_read_b128 v[218:221], v174 offset:34816
	ds_read_b128 v[222:225], v174 offset:35840
	ds_read_b128 v[226:229], v174 offset:36864
	ds_read_b128 v[230:233], v174 offset:37888
	ds_read_b128 v[234:237], v174 offset:38912
	ds_read_b128 v[238:241], v174 offset:39936
	s_waitcnt vmcnt(8)
	s_waitcnt lgkmcnt(0)
	s_barrier
	s_setprio 1
	s_waitcnt lgkmcnt(0)
	v_mfma_f32_16x16x32_bf16 v[126:129], v[140:143], v[210:213], v[126:129]
	v_mfma_f32_16x16x32_bf16 v[122:125], v[180:183], v[210:213], v[122:125]
	v_mfma_f32_16x16x32_bf16 v[118:121], v[140:143], v[218:221], v[118:121]
	v_mfma_f32_16x16x32_bf16 v[110:113], v[180:183], v[218:221], v[110:113]
	v_mfma_f32_16x16x32_bf16 v[94:97], v[140:143], v[226:229], v[94:97]
	v_mfma_f32_16x16x32_bf16 v[90:93], v[180:183], v[226:229], v[90:93]
	v_mfma_f32_16x16x32_bf16 v[86:89], v[140:143], v[234:237], v[86:89]
	v_mfma_f32_16x16x32_bf16 v[78:81], v[180:183], v[234:237], v[78:81]
	v_mfma_f32_16x16x32_bf16 v[126:129], v[176:179], v[214:217], v[126:129]
	v_mfma_f32_16x16x32_bf16 v[122:125], v[184:187], v[214:217], v[122:125]
	v_mfma_f32_16x16x32_bf16 v[118:121], v[176:179], v[222:225], v[118:121]
	v_mfma_f32_16x16x32_bf16 v[110:113], v[184:187], v[222:225], v[110:113]
	v_mfma_f32_16x16x32_bf16 v[94:97], v[176:179], v[230:233], v[94:97]
	v_mfma_f32_16x16x32_bf16 v[90:93], v[184:187], v[230:233], v[90:93]
	v_mfma_f32_16x16x32_bf16 v[86:89], v[176:179], v[238:241], v[86:89]
	v_mfma_f32_16x16x32_bf16 v[78:81], v[184:187], v[238:241], v[78:81]
	s_setprio 0
	s_setprio 1
	v_mfma_f32_16x16x32_bf16 v[114:117], v[188:191], v[210:213], v[114:117]
	v_mfma_f32_16x16x32_bf16 v[106:109], v[196:199], v[210:213], v[106:109]
	v_mfma_f32_16x16x32_bf16 v[102:105], v[188:191], v[218:221], v[102:105]
	v_mfma_f32_16x16x32_bf16 v[98:101], v[196:199], v[218:221], v[98:101]
	v_mfma_f32_16x16x32_bf16 v[82:85], v[188:191], v[226:229], v[82:85]
	v_mfma_f32_16x16x32_bf16 v[74:77], v[196:199], v[226:229], v[74:77]
	v_mfma_f32_16x16x32_bf16 v[70:73], v[188:191], v[234:237], v[70:73]
	v_mfma_f32_16x16x32_bf16 v[66:69], v[196:199], v[234:237], v[66:69]
	v_mfma_f32_16x16x32_bf16 v[114:117], v[192:195], v[214:217], v[114:117]
	v_mfma_f32_16x16x32_bf16 v[106:109], v[200:203], v[214:217], v[106:109]
	v_mfma_f32_16x16x32_bf16 v[102:105], v[192:195], v[222:225], v[102:105]
	v_mfma_f32_16x16x32_bf16 v[98:101], v[200:203], v[222:225], v[98:101]
	v_mfma_f32_16x16x32_bf16 v[82:85], v[192:195], v[230:233], v[82:85]
	v_mfma_f32_16x16x32_bf16 v[74:77], v[200:203], v[230:233], v[74:77]
	v_mfma_f32_16x16x32_bf16 v[70:73], v[192:195], v[238:241], v[70:73]
	v_mfma_f32_16x16x32_bf16 v[66:69], v[200:203], v[238:241], v[66:69]
	s_setprio 0
	s_barrier
; #define PG8_STAGE(bufoff, gbase, voff) do { _Pragma("unroll") for (int _i = 0; _i < 2; ++_i) \
;         __builtin_amdgcn_global_load_lds((const unsigned*)((const char*)(gbase) + (voff)[_i]), (LAS unsigned*)(lds + (bufoff) + ldsw + _i * 8192), 16, 0, 0); } while (0)
; #define PG8_LDA(dst, b, h) do { _Pragma("unroll") for (int m = 0; m < 4; ++m) _Pragma("unroll") for (int k = 0; k < 2; ++k) dst[m][k] = *(const LAS bf16x8*)(lds + PG8_SA(b, h) + aoff + m * 2048 + k * 1024); } while (0)
; #define PG8_MMA(ai, bj, At, Bt) do { __builtin_amdgcn_s_setprio(1); _Pragma("unroll") for (int m = 0; m < 4; ++m) _Pragma("unroll") for (int n = 0; n < 2; ++n) _Pragma("unroll") for (int k = 0; k < 2; ++k) \
;         acc[ai][bj][m][n] = __builtin_amdgcn_mfma_f32_16x16x32_bf16(Bt[n][k], At[m][k], acc[ai][bj][m][n], 0, 0, 0); __builtin_amdgcn_s_setprio(0); } while (0)
; #define PG8_WAIT_V(n) asm volatile("s_waitcnt vmcnt(" #n ")" ::: "memory")
; #define PG8_WAIT_L(n) asm volatile("s_waitcnt lgkmcnt(" #n ")" ::: "memory")
; #define PG8_BAR __builtin_amdgcn_s_barrier()
; #define PG8_SCHED __builtin_amdgcn_sched_barrier(0)
; template <class Epi>
; __device__ __forceinline__ void gemm_phase(LAS unsigned char* lds, const int tid, const Gemm g, const StaticOrder& S, const Epi& E) {
;     ...
;             PG8_LDA(At, 1, 1); PG8_STAGE(PG8_SB(1, 0), b3, voffB); PG8_STAGE(PG8_SB(1, 1), b3 + hstepB, voffB); PG8_STAGE(PG8_SA(1, 0), a3, voffA);
;             PG8_WAIT_V(8); PG8_WAIT_L(0); PG8_BAR; PG8_MMA(1, 0, At, B0); PG8_MMA(1, 1, At, B1); PG8_BAR; PG8_SCHED;
;         }
	s_add_i32 s0, s0, s28
	v_lshl_add_u64 v[144:145], v[144:145], 0, s[36:37]
	s_mov_b32 m0, s0
	s_nop 0
	global_load_lds_dwordx4 v[144:145], off
	s_add_i32 m0, s0, 0x2000
	s_add_u32 s2, s30, 0x40080
	v_lshl_add_u64 v[144:145], v[162:163], 0, s[36:37]
	s_addc_u32 s3, s31, 0
	s_add_i32 s0, s1, s28
	global_load_lds_dwordx4 v[144:145], off
	v_lshl_add_u64 v[144:145], s[2:3], 0, v[0:1]
	s_mov_b32 m0, s0
	s_nop 0
	global_load_lds_dwordx4 v[144:145], off
	v_lshl_add_u64 v[144:145], s[2:3], 0, v[130:131]
	s_add_i32 m0, s0, 0x2000
	s_nop 0
	global_load_lds_dwordx4 v[144:145], off
	v_lshl_add_u64 v[144:145], v[164:165], 0, s[36:37]
	s_mov_b32 m0, s75
	s_nop 0
	global_load_lds_dwordx4 v[144:145], off
	v_lshl_add_u64 v[144:145], v[206:207], 0, s[36:37]
	s_mov_b32 m0, s76
	s_nop 0
	global_load_lds_dwordx4 v[144:145], off
	ds_read_b128 v[210:213], v174 offset:49152
	ds_read_b128 v[214:217], v174 offset:50176
	ds_read_b128 v[218:221], v174 offset:51200
	ds_read_b128 v[222:225], v174 offset:52224
	ds_read_b128 v[226:229], v174 offset:53248
	ds_read_b128 v[230:233], v174 offset:54272
	ds_read_b128 v[234:237], v174 offset:55296
	ds_read_b128 v[238:241], v174 offset:56320
	s_waitcnt vmcnt(8)
	s_waitcnt lgkmcnt(0)
	s_barrier
	s_setprio 1
	s_waitcnt lgkmcnt(0)
	v_mfma_f32_16x16x32_bf16 v[62:65], v[140:143], v[210:213], v[62:65]
	v_mfma_f32_16x16x32_bf16 v[58:61], v[180:183], v[210:213], v[58:61]
	v_mfma_f32_16x16x32_bf16 v[54:57], v[140:143], v[218:221], v[54:57]
	v_mfma_f32_16x16x32_bf16 v[46:49], v[180:183], v[218:221], v[46:49]
	v_mfma_f32_16x16x32_bf16 v[30:33], v[140:143], v[226:229], v[30:33]
	v_mfma_f32_16x16x32_bf16 v[26:29], v[180:183], v[226:229], v[26:29]
	v_mfma_f32_16x16x32_bf16 v[22:25], v[140:143], v[234:237], v[22:25]
	v_mfma_f32_16x16x32_bf16 v[14:17], v[180:183], v[234:237], v[14:17]
	v_mfma_f32_16x16x32_bf16 v[62:65], v[176:179], v[214:217], v[62:65]
	v_mfma_f32_16x16x32_bf16 v[58:61], v[184:187], v[214:217], v[58:61]
	v_mfma_f32_16x16x32_bf16 v[54:57], v[176:179], v[222:225], v[54:57]
	v_mfma_f32_16x16x32_bf16 v[46:49], v[184:187], v[222:225], v[46:49]
	v_mfma_f32_16x16x32_bf16 v[30:33], v[176:179], v[230:233], v[30:33]
	v_mfma_f32_16x16x32_bf16 v[26:29], v[184:187], v[230:233], v[26:29]
	v_mfma_f32_16x16x32_bf16 v[22:25], v[176:179], v[238:241], v[22:25]
	v_mfma_f32_16x16x32_bf16 v[14:17], v[184:187], v[238:241], v[14:17]
	s_setprio 0
	s_setprio 1
	v_mfma_f32_16x16x32_bf16 v[50:53], v[188:191], v[210:213], v[50:53]
	v_mfma_f32_16x16x32_bf16 v[42:45], v[196:199], v[210:213], v[42:45]
	v_mfma_f32_16x16x32_bf16 v[38:41], v[188:191], v[218:221], v[38:41]
	v_mfma_f32_16x16x32_bf16 v[34:37], v[196:199], v[218:221], v[34:37]
	v_mfma_f32_16x16x32_bf16 v[18:21], v[188:191], v[226:229], v[18:21]
	v_mfma_f32_16x16x32_bf16 v[10:13], v[196:199], v[226:229], v[10:13]
	v_mfma_f32_16x16x32_bf16 v[6:9], v[188:191], v[234:237], v[6:9]
	v_mfma_f32_16x16x32_bf16 v[2:5], v[196:199], v[234:237], v[2:5]
	v_mfma_f32_16x16x32_bf16 v[50:53], v[192:195], v[214:217], v[50:53]
	v_mfma_f32_16x16x32_bf16 v[42:45], v[200:203], v[214:217], v[42:45]
	v_mfma_f32_16x16x32_bf16 v[38:41], v[192:195], v[222:225], v[38:41]
	v_mfma_f32_16x16x32_bf16 v[34:37], v[200:203], v[222:225], v[34:37]
	v_mfma_f32_16x16x32_bf16 v[18:21], v[192:195], v[230:233], v[18:21]
	v_mfma_f32_16x16x32_bf16 v[10:13], v[200:203], v[230:233], v[10:13]
	v_mfma_f32_16x16x32_bf16 v[6:9], v[192:195], v[238:241], v[6:9]
	v_mfma_f32_16x16x32_bf16 v[2:5], v[200:203], v[238:241], v[2:5]
	s_setprio 0
	s_barrier
	s_add_i32 vcc_lo, vcc_lo, 2
	s_add_u32 s66, s66, 0x100
	s_addc_u32 s67, s67, 0
	s_add_u32 s92, s92, 0x100
	s_addc_u32 s93, s93, 0
	s_cmp_gt_u32 vcc_lo, 13
	s_cbranch_scc0 .LBB0_1284
	s_and_b64 vcc, exec, s[6:7]
	s_mov_b32 s92, 0x2c000
	s_mov_b32 s93, 0x2e000
	s_cbranch_vccz .LBB0_1287
	s_barrier

; #define PG8_STAGE(bufoff, gbase, voff) do { _Pragma("unroll") for (int _i = 0; _i < 2; ++_i) \
;         __builtin_amdgcn_global_load_lds((const unsigned*)((const char*)(gbase) + (voff)[_i]), (LAS unsigned*)(lds + (bufoff) + ldsw + _i * 8192), 16, 0, 0); } while (0)
; #define PG8_LDA(dst, b, h) do { _Pragma("unroll") for (int m = 0; m < 4; ++m) _Pragma("unroll") for (int k = 0; k < 2; ++k) dst[m][k] = *(const LAS bf16x8*)(lds + PG8_SA(b, h) + aoff + m * 2048 + k * 1024); } while (0)
; #define PG8_LDB(dst, b, h) do { _Pragma("unroll") for (int n = 0; n < 2; ++n) _Pragma("unroll") for (int k = 0; k < 2; ++k) dst[n][k] = *(const LAS bf16x8*)(lds + PG8_SB(b, h) + boff + n * 2048 + k * 1024); } while (0)
; #define PG8_MMA(ai, bj, At, Bt) do { __builtin_amdgcn_s_setprio(1); _Pragma("unroll") for (int m = 0; m < 4; ++m) _Pragma("unroll") for (int n = 0; n < 2; ++n) _Pragma("unroll") for (int k = 0; k < 2; ++k) \
;         acc[ai][bj][m][n] = __builtin_amdgcn_mfma_f32_16x16x32_bf16(Bt[n][k], At[m][k], acc[ai][bj][m][n], 0, 0, 0); __builtin_amdgcn_s_setprio(0); } while (0)
; #define PG8_WAIT_V(n) asm volatile("s_waitcnt vmcnt(" #n ")" ::: "memory")
; #define PG8_WAIT_L(n) asm volatile("s_waitcnt lgkmcnt(" #n ")" ::: "memory")
; #define PG8_BAR __builtin_amdgcn_s_barrier()
; #define PG8_SCHED __builtin_amdgcn_sched_barrier(0)
; template <class Epi>
; __device__ __forceinline__ void gemm_phase(LAS unsigned char* lds, const int tid, const Gemm g, const StaticOrder& S, const Epi& E) {
;     ...
;             const bool last = (t == nt - 2);
;             const char* a1 = cA + (size_t)(t + 1) * kstep;
;             const char* a2 = last ? nA : cA + (size_t)(t + 2) * kstep; const char* b2 = last ? nB : cB + (size_t)(t + 2) * kstep;
;             const char* a3 = a2 + kstep; const char* b3 = b2 + kstep;
;             PG8_LDB(B0, 0, 0); PG8_LDB(B1, 0, 1); PG8_SCHED; PG8_LDA(At, 0, 0); PG8_STAGE(PG8_SA(1, 1), a1 + hstepA, voffA);
;             PG8_WAIT_V(8); PG8_WAIT_L(0); PG8_BAR; PG8_MMA(0, 0, At, B0); PG8_MMA(0, 1, At, B1); PG8_BAR; PG8_SCHED;
;             PG8_LDA(At, 0, 1); PG8_STAGE(PG8_SB(0, 0), b2, voffB); PG8_STAGE(PG8_SB(0, 1), b2 + hstepB, voffB); PG8_STAGE(PG8_SA(0, 0), a2, voffA);
.LBB0_1333:
	v_lshl_add_u64 v[162:163], s[66:67], 0, v[154:155]
	s_add_i32 m0, s71, 0xc000
	s_nop 0
	global_load_lds_dwordx4 v[162:163], off
	v_lshl_add_u64 v[162:163], s[66:67], 0, v[156:157]
	s_add_i32 m0, s71, 0xe000
	s_nop 0
	global_load_lds_dwordx4 v[162:163], off
	s_add_u32 s0, s66, 0xfff80080
	s_addc_u32 s1, s67, -1
	s_add_i32 s2, 0, 0x10000
	s_cmp_eq_u32 vcc_lo, 12
	s_cselect_b32 s69, s11, s1
	s_cselect_b32 s68, s88, s0
	s_cselect_b32 s31, s9, s93
	s_cselect_b32 s30, s89, s92
	s_add_i32 s0, 0, 0x14000
	v_add_u32_e32 v142, s2, v189
	v_add_u32_e32 v162, s0, v189
	ds_read_b128 v[130:133], v142
	ds_read_b128 v[134:137], v142 offset:1024
	ds_read_b128 v[138:141], v142 offset:2048
	ds_read_b128 v[142:145], v142 offset:3072
	ds_read_b128 v[158:161], v162
	ds_read_b128 v[192:195], v162 offset:1024
	ds_read_b128 v[196:199], v162 offset:2048
	ds_read_b128 v[200:203], v162 offset:3072
	ds_read_b128 v[210:213], v191
	ds_read_b128 v[214:217], v191 offset:1024
	ds_read_b128 v[218:221], v191 offset:2048
	ds_read_b128 v[222:225], v191 offset:3072
	ds_read_b128 v[226:229], v191 offset:4096
	ds_read_b128 v[230:233], v191 offset:5120
	ds_read_b128 v[234:237], v191 offset:6144
	ds_read_b128 v[238:241], v191 offset:7168
	s_waitcnt vmcnt(8)
	s_waitcnt lgkmcnt(0)
	s_barrier
	s_setprio 1
	s_waitcnt lgkmcnt(0)
	v_mfma_f32_16x16x32_bf16 v[126:129], v[130:133], v[210:213], v[126:129]
	v_mfma_f32_16x16x32_bf16 v[122:125], v[138:141], v[210:213], v[122:125]
	v_mfma_f32_16x16x32_bf16 v[110:113], v[130:133], v[218:221], v[110:113]
	v_mfma_f32_16x16x32_bf16 v[106:109], v[138:141], v[218:221], v[106:109]
	v_mfma_f32_16x16x32_bf16 v[94:97], v[130:133], v[226:229], v[94:97]
	v_mfma_f32_16x16x32_bf16 v[90:93], v[138:141], v[226:229], v[90:93]
	v_mfma_f32_16x16x32_bf16 v[78:81], v[130:133], v[234:237], v[78:81]
	v_mfma_f32_16x16x32_bf16 v[74:77], v[138:141], v[234:237], v[74:77]
	v_mfma_f32_16x16x32_bf16 v[126:129], v[134:137], v[214:217], v[126:129]
	v_mfma_f32_16x16x32_bf16 v[122:125], v[142:145], v[214:217], v[122:125]
	v_mfma_f32_16x16x32_bf16 v[110:113], v[134:137], v[222:225], v[110:113]
	v_mfma_f32_16x16x32_bf16 v[106:109], v[142:145], v[222:225], v[106:109]
	v_mfma_f32_16x16x32_bf16 v[94:97], v[134:137], v[230:233], v[94:97]
	v_mfma_f32_16x16x32_bf16 v[90:93], v[142:145], v[230:233], v[90:93]
	v_mfma_f32_16x16x32_bf16 v[78:81], v[134:137], v[238:241], v[78:81]
	v_mfma_f32_16x16x32_bf16 v[74:77], v[142:145], v[238:241], v[74:77]
	s_setprio 0
	s_setprio 1
	v_mfma_f32_16x16x32_bf16 v[118:121], v[158:161], v[210:213], v[118:121]
	v_mfma_f32_16x16x32_bf16 v[114:117], v[196:199], v[210:213], v[114:117]
	v_mfma_f32_16x16x32_bf16 v[102:105], v[158:161], v[218:221], v[102:105]
	v_mfma_f32_16x16x32_bf16 v[98:101], v[196:199], v[218:221], v[98:101]
	v_mfma_f32_16x16x32_bf16 v[86:89], v[158:161], v[226:229], v[86:89]
	v_mfma_f32_16x16x32_bf16 v[82:85], v[196:199], v[226:229], v[82:85]
	v_mfma_f32_16x16x32_bf16 v[70:73], v[158:161], v[234:237], v[70:73]
	v_mfma_f32_16x16x32_bf16 v[66:69], v[196:199], v[234:237], v[66:69]
	v_mfma_f32_16x16x32_bf16 v[118:121], v[192:195], v[214:217], v[118:121]
	v_mfma_f32_16x16x32_bf16 v[114:117], v[200:203], v[214:217], v[114:117]
	v_mfma_f32_16x16x32_bf16 v[102:105], v[192:195], v[222:225], v[102:105]
	v_mfma_f32_16x16x32_bf16 v[98:101], v[200:203], v[222:225], v[98:101]
	v_mfma_f32_16x16x32_bf16 v[86:89], v[192:195], v[230:233], v[86:89]
	v_mfma_f32_16x16x32_bf16 v[82:85], v[200:203], v[230:233], v[82:85]
	v_mfma_f32_16x16x32_bf16 v[70:73], v[192:195], v[238:241], v[70:73]
	v_mfma_f32_16x16x32_bf16 v[66:69], v[200:203], v[238:241], v[66:69]
	s_setprio 0
	s_barrier
	s_add_i32 s1, s2, s28
	v_lshl_add_u64 v[162:163], s[30:31], 0, v[0:1]
	s_mov_b32 m0, s1
	s_nop 0
	global_load_lds_dwordx4 v[162:163], off
	s_add_i32 m0, s1, 0x2000
	s_add_u32 s2, s30, 0x40000
	v_lshl_add_u64 v[164:165], s[30:31], 0, v[148:149]
	s_addc_u32 s3, s31, 0
	s_add_i32 s0, s0, s28
	global_load_lds_dwordx4 v[164:165], off
	v_lshl_add_u64 v[170:171], s[2:3], 0, v[0:1]
	s_mov_b32 m0, s0
	v_lshl_add_u64 v[206:207], s[68:69], 0, v[150:151]
	global_load_lds_dwordx4 v[170:171], off
	v_lshl_add_u64 v[170:171], s[2:3], 0, v[148:149]
	s_add_i32 m0, s0, 0x2000
	s_nop 0
	global_load_lds_dwordx4 v[170:171], off
	v_lshl_add_u64 v[170:171], s[68:69], 0, v[152:153]
	s_mov_b32 m0, s71
	s_nop 0
	global_load_lds_dwordx4 v[170:171], off
	s_mov_b32 m0, s72
	s_nop 0
	global_load_lds_dwordx4 v[206:207], off
	ds_read_b128 v[210:213], v191 offset:16384
	ds_read_b128 v[214:217], v191 offset:17408
	ds_read_b128 v[218:221], v191 offset:18432
	ds_read_b128 v[222:225], v191 offset:19456
	ds_read_b128 v[226:229], v191 offset:20480
	ds_read_b128 v[230:233], v191 offset:21504
	ds_read_b128 v[234:237], v191 offset:22528
	ds_read_b128 v[238:241], v191 offset:23552
	s_waitcnt vmcnt(8)
	s_waitcnt lgkmcnt(0)
	s_barrier
; #define PG8_STAGE(bufoff, gbase, voff) do { _Pragma("unroll") for (int _i = 0; _i < 2; ++_i) \
;         __builtin_amdgcn_global_load_lds((const unsigned*)((const char*)(gbase) + (voff)[_i]), (LAS unsigned*)(lds + (bufoff) + ldsw + _i * 8192), 16, 0, 0); } while (0)
; #define PG8_LDA(dst, b, h) do { _Pragma("unroll") for (int m = 0; m < 4; ++m) _Pragma("unroll") for (int k = 0; k < 2; ++k) dst[m][k] = *(const LAS bf16x8*)(lds + PG8_SA(b, h) + aoff + m * 2048 + k * 1024); } while (0)
; #define PG8_LDB(dst, b, h) do { _Pragma("unroll") for (int n = 0; n < 2; ++n) _Pragma("unroll") for (int k = 0; k < 2; ++k) dst[n][k] = *(const LAS bf16x8*)(lds + PG8_SB(b, h) + boff + n * 2048 + k * 1024); } while (0)
; #define PG8_MMA(ai, bj, At, Bt) do { __builtin_amdgcn_s_setprio(1); _Pragma("unroll") for (int m = 0; m < 4; ++m) _Pragma("unroll") for (int n = 0; n < 2; ++n) _Pragma("unroll") for (int k = 0; k < 2; ++k) \
;         acc[ai][bj][m][n] = __builtin_amdgcn_mfma_f32_16x16x32_bf16(Bt[n][k], At[m][k], acc[ai][bj][m][n], 0, 0, 0); __builtin_amdgcn_s_setprio(0); } while (0)
; #define PG8_WAIT_V(n) asm volatile("s_waitcnt vmcnt(" #n ")" ::: "memory")
; #define PG8_WAIT_L(n) asm volatile("s_waitcnt lgkmcnt(" #n ")" ::: "memory")
; #define PG8_BAR __builtin_amdgcn_s_barrier()
; #define PG8_SCHED __builtin_amdgcn_sched_barrier(0)
; template <class Epi>
; __device__ __forceinline__ void gemm_phase(LAS unsigned char* lds, const int tid, const Gemm g, const StaticOrder& S, const Epi& E) {
;     ...
;             PG8_WAIT_V(8); PG8_WAIT_L(0); PG8_BAR; PG8_MMA(1, 0, At, B0); PG8_MMA(1, 1, At, B1); PG8_BAR; PG8_SCHED;
;             PG8_LDB(B0, 1, 0); PG8_LDB(B1, 1, 1); PG8_SCHED; PG8_LDA(At, 1, 0); PG8_STAGE(PG8_SA(0, 1), a2 + hstepA, voffA);
;             PG8_WAIT_V(8); PG8_WAIT_L(0); PG8_BAR; PG8_MMA(0, 0, At, B0); PG8_MMA(0, 1, At, B1); PG8_BAR; PG8_SCHED;
	s_setprio 1
	s_waitcnt lgkmcnt(0)
	v_mfma_f32_16x16x32_bf16 v[62:65], v[130:133], v[210:213], v[62:65]
	v_mfma_f32_16x16x32_bf16 v[58:61], v[138:141], v[210:213], v[58:61]
	v_mfma_f32_16x16x32_bf16 v[46:49], v[130:133], v[218:221], v[46:49]
	v_mfma_f32_16x16x32_bf16 v[42:45], v[138:141], v[218:221], v[42:45]
	v_mfma_f32_16x16x32_bf16 v[30:33], v[130:133], v[226:229], v[30:33]
	v_mfma_f32_16x16x32_bf16 v[26:29], v[138:141], v[226:229], v[26:29]
	v_mfma_f32_16x16x32_bf16 v[14:17], v[130:133], v[234:237], v[14:17]
	v_mfma_f32_16x16x32_bf16 v[10:13], v[138:141], v[234:237], v[10:13]
	v_mfma_f32_16x16x32_bf16 v[62:65], v[134:137], v[214:217], v[62:65]
	v_mfma_f32_16x16x32_bf16 v[58:61], v[142:145], v[214:217], v[58:61]
	v_mfma_f32_16x16x32_bf16 v[46:49], v[134:137], v[222:225], v[46:49]
	v_mfma_f32_16x16x32_bf16 v[42:45], v[142:145], v[222:225], v[42:45]
	v_mfma_f32_16x16x32_bf16 v[30:33], v[134:137], v[230:233], v[30:33]
	v_mfma_f32_16x16x32_bf16 v[26:29], v[142:145], v[230:233], v[26:29]
	v_mfma_f32_16x16x32_bf16 v[14:17], v[134:137], v[238:241], v[14:17]
	v_mfma_f32_16x16x32_bf16 v[10:13], v[142:145], v[238:241], v[10:13]
	s_setprio 0
	s_setprio 1
	v_mfma_f32_16x16x32_bf16 v[54:57], v[158:161], v[210:213], v[54:57]
	v_mfma_f32_16x16x32_bf16 v[50:53], v[196:199], v[210:213], v[50:53]
	v_mfma_f32_16x16x32_bf16 v[38:41], v[158:161], v[218:221], v[38:41]
	v_mfma_f32_16x16x32_bf16 v[34:37], v[196:199], v[218:221], v[34:37]
	v_mfma_f32_16x16x32_bf16 v[22:25], v[158:161], v[226:229], v[22:25]
	v_mfma_f32_16x16x32_bf16 v[18:21], v[196:199], v[226:229], v[18:21]
	v_mfma_f32_16x16x32_bf16 v[6:9], v[158:161], v[234:237], v[6:9]
	v_mfma_f32_16x16x32_bf16 v[2:5], v[196:199], v[234:237], v[2:5]
	v_mfma_f32_16x16x32_bf16 v[54:57], v[192:195], v[214:217], v[54:57]
	v_mfma_f32_16x16x32_bf16 v[50:53], v[200:203], v[214:217], v[50:53]
	v_mfma_f32_16x16x32_bf16 v[38:41], v[192:195], v[222:225], v[38:41]
	v_mfma_f32_16x16x32_bf16 v[34:37], v[200:203], v[222:225], v[34:37]
	v_mfma_f32_16x16x32_bf16 v[22:25], v[192:195], v[230:233], v[22:25]
	v_mfma_f32_16x16x32_bf16 v[18:21], v[200:203], v[230:233], v[18:21]
	v_mfma_f32_16x16x32_bf16 v[6:9], v[192:195], v[238:241], v[6:9]
	v_mfma_f32_16x16x32_bf16 v[2:5], v[200:203], v[238:241], v[2:5]
	s_setprio 0
	s_barrier
	s_add_u32 s2, s68, 0x80000
	s_addc_u32 s3, s69, 0
	s_mov_b32 m0, s73
	v_lshl_add_u64 v[242:243], s[2:3], 0, v[152:153]
	global_load_lds_dwordx4 v[242:243], off
	v_lshl_add_u64 v[242:243], s[2:3], 0, v[150:151]
	s_mov_b32 m0, s74
	s_nop 0
	global_load_lds_dwordx4 v[242:243], off
	s_add_i32 s0, 0, 0x18000
	s_add_i32 s1, 0, 0x1c000
	v_add_u32_e32 v142, s0, v189
	v_add_u32_e32 v200, s1, v189
	ds_read_b128 v[130:133], v142
	ds_read_b128 v[134:137], v142 offset:1024
	ds_read_b128 v[138:141], v142 offset:2048
	ds_read_b128 v[142:145], v142 offset:3072
	ds_read_b128 v[158:161], v200
	ds_read_b128 v[192:195], v200 offset:1024
	ds_read_b128 v[196:199], v200 offset:2048
	ds_read_b128 v[200:203], v200 offset:3072
	ds_read_b128 v[210:213], v191 offset:32768
	ds_read_b128 v[214:217], v191 offset:33792
	ds_read_b128 v[218:221], v191 offset:34816
	ds_read_b128 v[222:225], v191 offset:35840
	ds_read_b128 v[226:229], v191 offset:36864
	ds_read_b128 v[230:233], v191 offset:37888
	ds_read_b128 v[234:237], v191 offset:38912
	ds_read_b128 v[238:241], v191 offset:39936
	s_waitcnt vmcnt(8)
	s_waitcnt lgkmcnt(0)
	s_barrier
	s_setprio 1
	s_waitcnt lgkmcnt(0)
	v_mfma_f32_16x16x32_bf16 v[126:129], v[130:133], v[210:213], v[126:129]
	v_mfma_f32_16x16x32_bf16 v[122:125], v[138:141], v[210:213], v[122:125]
	v_mfma_f32_16x16x32_bf16 v[110:113], v[130:133], v[218:221], v[110:113]
	v_mfma_f32_16x16x32_bf16 v[106:109], v[138:141], v[218:221], v[106:109]
	v_mfma_f32_16x16x32_bf16 v[94:97], v[130:133], v[226:229], v[94:97]
	v_mfma_f32_16x16x32_bf16 v[90:93], v[138:141], v[226:229], v[90:93]
	v_mfma_f32_16x16x32_bf16 v[78:81], v[130:133], v[234:237], v[78:81]
	v_mfma_f32_16x16x32_bf16 v[74:77], v[138:141], v[234:237], v[74:77]
	v_mfma_f32_16x16x32_bf16 v[126:129], v[134:137], v[214:217], v[126:129]
	v_mfma_f32_16x16x32_bf16 v[122:125], v[142:145], v[214:217], v[122:125]
	v_mfma_f32_16x16x32_bf16 v[110:113], v[134:137], v[222:225], v[110:113]
	v_mfma_f32_16x16x32_bf16 v[106:109], v[142:145], v[222:225], v[106:109]
	v_mfma_f32_16x16x32_bf16 v[94:97], v[134:137], v[230:233], v[94:97]
	v_mfma_f32_16x16x32_bf16 v[90:93], v[142:145], v[230:233], v[90:93]
	v_mfma_f32_16x16x32_bf16 v[78:81], v[134:137], v[238:241], v[78:81]
	v_mfma_f32_16x16x32_bf16 v[74:77], v[142:145], v[238:241], v[74:77]
	s_setprio 0
	s_setprio 1
	v_mfma_f32_16x16x32_bf16 v[118:121], v[158:161], v[210:213], v[118:121]
	v_mfma_f32_16x16x32_bf16 v[114:117], v[196:199], v[210:213], v[114:117]
	v_mfma_f32_16x16x32_bf16 v[102:105], v[158:161], v[218:221], v[102:105]
	v_mfma_f32_16x16x32_bf16 v[98:101], v[196:199], v[218:221], v[98:101]
	v_mfma_f32_16x16x32_bf16 v[86:89], v[158:161], v[226:229], v[86:89]
	v_mfma_f32_16x16x32_bf16 v[82:85], v[196:199], v[226:229], v[82:85]
	v_mfma_f32_16x16x32_bf16 v[70:73], v[158:161], v[234:237], v[70:73]
	v_mfma_f32_16x16x32_bf16 v[66:69], v[196:199], v[234:237], v[66:69]
	v_mfma_f32_16x16x32_bf16 v[118:121], v[192:195], v[214:217], v[118:121]
	v_mfma_f32_16x16x32_bf16 v[114:117], v[200:203], v[214:217], v[114:117]
	v_mfma_f32_16x16x32_bf16 v[102:105], v[192:195], v[222:225], v[102:105]
	v_mfma_f32_16x16x32_bf16 v[98:101], v[200:203], v[222:225], v[98:101]
	v_mfma_f32_16x16x32_bf16 v[86:89], v[192:195], v[230:233], v[86:89]
	v_mfma_f32_16x16x32_bf16 v[82:85], v[200:203], v[230:233], v[82:85]
	v_mfma_f32_16x16x32_bf16 v[70:73], v[192:195], v[238:241], v[70:73]
	v_mfma_f32_16x16x32_bf16 v[66:69], v[200:203], v[238:241], v[66:69]
	s_setprio 0
	s_barrier
; #define PG8_STAGE(bufoff, gbase, voff) do { _Pragma("unroll") for (int _i = 0; _i < 2; ++_i) \
;         __builtin_amdgcn_global_load_lds((const unsigned*)((const char*)(gbase) + (voff)[_i]), (LAS unsigned*)(lds + (bufoff) + ldsw + _i * 8192), 16, 0, 0); } while (0)
; #define PG8_LDA(dst, b, h) do { _Pragma("unroll") for (int m = 0; m < 4; ++m) _Pragma("unroll") for (int k = 0; k < 2; ++k) dst[m][k] = *(const LAS bf16x8*)(lds + PG8_SA(b, h) + aoff + m * 2048 + k * 1024); } while (0)
; #define PG8_MMA(ai, bj, At, Bt) do { __builtin_amdgcn_s_setprio(1); _Pragma("unroll") for (int m = 0; m < 4; ++m) _Pragma("unroll") for (int n = 0; n < 2; ++n) _Pragma("unroll") for (int k = 0; k < 2; ++k) \
;         acc[ai][bj][m][n] = __builtin_amdgcn_mfma_f32_16x16x32_bf16(Bt[n][k], At[m][k], acc[ai][bj][m][n], 0, 0, 0); __builtin_amdgcn_s_setprio(0); } while (0)
; #define PG8_WAIT_V(n) asm volatile("s_waitcnt vmcnt(" #n ")" ::: "memory")
; #define PG8_WAIT_L(n) asm volatile("s_waitcnt lgkmcnt(" #n ")" ::: "memory")
; #define PG8_BAR __builtin_amdgcn_s_barrier()
; #define PG8_SCHED __builtin_amdgcn_sched_barrier(0)
; template <class Epi>
; __device__ __forceinline__ void gemm_phase(LAS unsigned char* lds, const int tid, const Gemm g, const StaticOrder& S, const Epi& E) {
;     ...
;             PG8_LDA(At, 1, 1); PG8_STAGE(PG8_SB(1, 0), b3, voffB); PG8_STAGE(PG8_SB(1, 1), b3 + hstepB, voffB); PG8_STAGE(PG8_SA(1, 0), a3, voffA);
;             PG8_WAIT_V(8); PG8_WAIT_L(0); PG8_BAR; PG8_MMA(1, 0, At, B0); PG8_MMA(1, 1, At, B1); PG8_BAR; PG8_SCHED;
;         }
	s_add_i32 s0, s0, s28
	v_lshl_add_u64 v[162:163], v[162:163], 0, s[36:37]
	s_mov_b32 m0, s0
	s_nop 0
	global_load_lds_dwordx4 v[162:163], off
	s_add_i32 m0, s0, 0x2000
	s_add_u32 s2, s30, 0x40080
	v_lshl_add_u64 v[162:163], v[164:165], 0, s[36:37]
	s_addc_u32 s3, s31, 0
	s_add_i32 s0, s1, s28
	global_load_lds_dwordx4 v[162:163], off
	v_lshl_add_u64 v[162:163], s[2:3], 0, v[0:1]
	s_mov_b32 m0, s0
	s_nop 0
	global_load_lds_dwordx4 v[162:163], off
	v_lshl_add_u64 v[162:163], s[2:3], 0, v[148:149]
	s_add_i32 m0, s0, 0x2000
	s_nop 0
	global_load_lds_dwordx4 v[162:163], off
	v_lshl_add_u64 v[162:163], v[170:171], 0, s[36:37]
	s_mov_b32 m0, s75
	s_nop 0
	global_load_lds_dwordx4 v[162:163], off
	v_lshl_add_u64 v[162:163], v[206:207], 0, s[36:37]
	s_mov_b32 m0, s76
	s_nop 0
	global_load_lds_dwordx4 v[162:163], off
	ds_read_b128 v[210:213], v191 offset:49152
	ds_read_b128 v[214:217], v191 offset:50176
	ds_read_b128 v[218:221], v191 offset:51200
	ds_read_b128 v[222:225], v191 offset:52224
	ds_read_b128 v[226:229], v191 offset:53248
	ds_read_b128 v[230:233], v191 offset:54272
	ds_read_b128 v[234:237], v191 offset:55296
	ds_read_b128 v[238:241], v191 offset:56320
	s_waitcnt vmcnt(8)
	s_waitcnt lgkmcnt(0)
	s_barrier
	s_setprio 1
	s_waitcnt lgkmcnt(0)
	v_mfma_f32_16x16x32_bf16 v[62:65], v[130:133], v[210:213], v[62:65]
	v_mfma_f32_16x16x32_bf16 v[58:61], v[138:141], v[210:213], v[58:61]
	v_mfma_f32_16x16x32_bf16 v[46:49], v[130:133], v[218:221], v[46:49]
	v_mfma_f32_16x16x32_bf16 v[42:45], v[138:141], v[218:221], v[42:45]
	v_mfma_f32_16x16x32_bf16 v[30:33], v[130:133], v[226:229], v[30:33]
	v_mfma_f32_16x16x32_bf16 v[26:29], v[138:141], v[226:229], v[26:29]
	v_mfma_f32_16x16x32_bf16 v[14:17], v[130:133], v[234:237], v[14:17]
	v_mfma_f32_16x16x32_bf16 v[10:13], v[138:141], v[234:237], v[10:13]
	v_mfma_f32_16x16x32_bf16 v[62:65], v[134:137], v[214:217], v[62:65]
	v_mfma_f32_16x16x32_bf16 v[58:61], v[142:145], v[214:217], v[58:61]
	v_mfma_f32_16x16x32_bf16 v[46:49], v[134:137], v[222:225], v[46:49]
	v_mfma_f32_16x16x32_bf16 v[42:45], v[142:145], v[222:225], v[42:45]
	v_mfma_f32_16x16x32_bf16 v[30:33], v[134:137], v[230:233], v[30:33]
	v_mfma_f32_16x16x32_bf16 v[26:29], v[142:145], v[230:233], v[26:29]
	v_mfma_f32_16x16x32_bf16 v[14:17], v[134:137], v[238:241], v[14:17]
	v_mfma_f32_16x16x32_bf16 v[10:13], v[142:145], v[238:241], v[10:13]
	s_setprio 0
	s_setprio 1
	v_mfma_f32_16x16x32_bf16 v[54:57], v[158:161], v[210:213], v[54:57]
	v_mfma_f32_16x16x32_bf16 v[50:53], v[196:199], v[210:213], v[50:53]
	v_mfma_f32_16x16x32_bf16 v[38:41], v[158:161], v[218:221], v[38:41]
	v_mfma_f32_16x16x32_bf16 v[34:37], v[196:199], v[218:221], v[34:37]
	v_mfma_f32_16x16x32_bf16 v[22:25], v[158:161], v[226:229], v[22:25]
	v_mfma_f32_16x16x32_bf16 v[18:21], v[196:199], v[226:229], v[18:21]
	v_mfma_f32_16x16x32_bf16 v[6:9], v[158:161], v[234:237], v[6:9]
	v_mfma_f32_16x16x32_bf16 v[2:5], v[196:199], v[234:237], v[2:5]
	v_mfma_f32_16x16x32_bf16 v[54:57], v[192:195], v[214:217], v[54:57]
	v_mfma_f32_16x16x32_bf16 v[50:53], v[200:203], v[214:217], v[50:53]
	v_mfma_f32_16x16x32_bf16 v[38:41], v[192:195], v[222:225], v[38:41]
	v_mfma_f32_16x16x32_bf16 v[34:37], v[200:203], v[222:225], v[34:37]
	v_mfma_f32_16x16x32_bf16 v[22:25], v[192:195], v[230:233], v[22:25]
	v_mfma_f32_16x16x32_bf16 v[18:21], v[200:203], v[230:233], v[18:21]
	v_mfma_f32_16x16x32_bf16 v[6:9], v[192:195], v[238:241], v[6:9]
	v_mfma_f32_16x16x32_bf16 v[2:5], v[200:203], v[238:241], v[2:5]
	s_setprio 0
	s_barrier
	s_add_i32 vcc_lo, vcc_lo, 2
	s_add_u32 s66, s66, 0x100
	s_addc_u32 s67, s67, 0
	s_add_u32 s92, s92, 0x100
	s_addc_u32 s93, s93, 0
	s_cmp_gt_u32 vcc_lo, 13
	s_cbranch_scc0 .LBB0_1333
	s_and_b64 vcc, exec, s[6:7]
	s_cbranch_vccz .LBB0_1336
	s_barrier

; #define PG8_STAGE(bufoff, gbase, voff) do { _Pragma("unroll") for (int _i = 0; _i < 2; ++_i) \
;         __builtin_amdgcn_global_load_lds((const unsigned*)((const char*)(gbase) + (voff)[_i]), (LAS unsigned*)(lds + (bufoff) + ldsw + _i * 8192), 16, 0, 0); } while (0)
; #define PG8_LDA(dst, b, h) do { _Pragma("unroll") for (int m = 0; m < 4; ++m) _Pragma("unroll") for (int k = 0; k < 2; ++k) dst[m][k] = *(const LAS bf16x8*)(lds + PG8_SA(b, h) + aoff + m * 2048 + k * 1024); } while (0)
; #define PG8_LDB(dst, b, h) do { _Pragma("unroll") for (int n = 0; n < 2; ++n) _Pragma("unroll") for (int k = 0; k < 2; ++k) dst[n][k] = *(const LAS bf16x8*)(lds + PG8_SB(b, h) + boff + n * 2048 + k * 1024); } while (0)
; #define PG8_MMA(ai, bj, At, Bt) do { __builtin_amdgcn_s_setprio(1); _Pragma("unroll") for (int m = 0; m < 4; ++m) _Pragma("unroll") for (int n = 0; n < 2; ++n) _Pragma("unroll") for (int k = 0; k < 2; ++k) \
;         acc[ai][bj][m][n] = __builtin_amdgcn_mfma_f32_16x16x32_bf16(Bt[n][k], At[m][k], acc[ai][bj][m][n], 0, 0, 0); __builtin_amdgcn_s_setprio(0); } while (0)
; #define PG8_WAIT_V(n) asm volatile("s_waitcnt vmcnt(" #n ")" ::: "memory")
; #define PG8_WAIT_L(n) asm volatile("s_waitcnt lgkmcnt(" #n ")" ::: "memory")
; #define PG8_BAR __builtin_amdgcn_s_barrier()
; #define PG8_SCHED __builtin_amdgcn_sched_barrier(0)
; template <class Epi>
; __device__ __forceinline__ void gemm_phase(LAS unsigned char* lds, const int tid, const Gemm g, const StaticOrder& S, const Epi& E) {
;     ...
;             const bool last = (t == nt - 2);
;             const char* a1 = cA + (size_t)(t + 1) * kstep;
;             const char* a2 = last ? nA : cA + (size_t)(t + 2) * kstep; const char* b2 = last ? nB : cB + (size_t)(t + 2) * kstep;
;             const char* a3 = a2 + kstep; const char* b3 = b2 + kstep;
;             PG8_LDB(B0, 0, 0); PG8_LDB(B1, 0, 1); PG8_SCHED; PG8_LDA(At, 0, 0); PG8_STAGE(PG8_SA(1, 1), a1 + hstepA, voffA);
;             PG8_WAIT_V(8); PG8_WAIT_L(0); PG8_BAR; PG8_MMA(0, 0, At, B0); PG8_MMA(0, 1, At, B1); PG8_BAR; PG8_SCHED;
;             PG8_LDA(At, 0, 1); PG8_STAGE(PG8_SB(0, 0), b2, voffB); PG8_STAGE(PG8_SB(0, 1), b2 + hstepB, voffB); PG8_STAGE(PG8_SA(0, 0), a2, voffA);
.LBB0_1487:
	v_lshl_add_u64 v[162:163], s[68:69], 0, v[176:177]
	s_add_i32 m0, s1, 0xc000
	s_nop 0
	global_load_lds_dwordx4 v[162:163], off
	v_lshl_add_u64 v[162:163], s[68:69], 0, v[178:179]
	s_add_i32 m0, s1, 0xe000
	s_nop 0
	global_load_lds_dwordx4 v[162:163], off
	s_add_u32 s27, s68, 0xfffc0080
	s_addc_u32 s30, s69, -1
	s_add_i32 s62, 0, 0x10000
	s_cmp_eq_u32 s26, 12
	s_cselect_b32 vcc_hi, s28, s30
	s_cselect_b32 vcc_lo, s71, s27
	s_cselect_b32 s31, s5, s83
	s_cselect_b32 s30, s73, s75
	s_add_i32 s27, 0, 0x14000
	v_add_u32_e32 v142, s62, v216
	v_add_u32_e32 v158, s27, v216
	ds_read_b128 v[130:133], v142
	ds_read_b128 v[134:137], v142 offset:1024
	ds_read_b128 v[138:141], v142 offset:2048
	ds_read_b128 v[142:145], v142 offset:3072
	ds_read_b128 v[146:149], v158
	ds_read_b128 v[150:153], v158 offset:1024
	ds_read_b128 v[154:157], v158 offset:2048
	ds_read_b128 v[158:161], v158 offset:3072
	ds_read_b128 v[180:183], v218
	ds_read_b128 v[184:187], v218 offset:1024
	ds_read_b128 v[220:223], v218 offset:2048
	ds_read_b128 v[224:227], v218 offset:3072
	ds_read_b128 v[228:231], v218 offset:4096
	ds_read_b128 v[232:235], v218 offset:5120
	ds_read_b128 v[236:239], v218 offset:6144
	ds_read_b128 v[240:243], v218 offset:7168
	s_waitcnt vmcnt(8)
	s_waitcnt lgkmcnt(0)
	s_barrier
	s_setprio 1
	s_waitcnt lgkmcnt(0)
	v_mfma_f32_16x16x32_bf16 v[126:129], v[130:133], v[180:183], v[126:129]
	v_mfma_f32_16x16x32_bf16 v[122:125], v[138:141], v[180:183], v[122:125]
	v_mfma_f32_16x16x32_bf16 v[110:113], v[130:133], v[220:223], v[110:113]
	v_mfma_f32_16x16x32_bf16 v[106:109], v[138:141], v[220:223], v[106:109]
	v_mfma_f32_16x16x32_bf16 v[94:97], v[130:133], v[228:231], v[94:97]
	v_mfma_f32_16x16x32_bf16 v[90:93], v[138:141], v[228:231], v[90:93]
	v_mfma_f32_16x16x32_bf16 v[78:81], v[130:133], v[236:239], v[78:81]
	v_mfma_f32_16x16x32_bf16 v[74:77], v[138:141], v[236:239], v[74:77]
	v_mfma_f32_16x16x32_bf16 v[126:129], v[134:137], v[184:187], v[126:129]
	v_mfma_f32_16x16x32_bf16 v[122:125], v[142:145], v[184:187], v[122:125]
	v_mfma_f32_16x16x32_bf16 v[110:113], v[134:137], v[224:227], v[110:113]
	v_mfma_f32_16x16x32_bf16 v[106:109], v[142:145], v[224:227], v[106:109]
	v_mfma_f32_16x16x32_bf16 v[94:97], v[134:137], v[232:235], v[94:97]
	v_mfma_f32_16x16x32_bf16 v[90:93], v[142:145], v[232:235], v[90:93]
	v_mfma_f32_16x16x32_bf16 v[78:81], v[134:137], v[240:243], v[78:81]
	v_mfma_f32_16x16x32_bf16 v[74:77], v[142:145], v[240:243], v[74:77]
	s_setprio 0
	s_setprio 1
	v_mfma_f32_16x16x32_bf16 v[118:121], v[146:149], v[180:183], v[118:121]
	v_mfma_f32_16x16x32_bf16 v[114:117], v[154:157], v[180:183], v[114:117]
	v_mfma_f32_16x16x32_bf16 v[102:105], v[146:149], v[220:223], v[102:105]
	v_mfma_f32_16x16x32_bf16 v[98:101], v[154:157], v[220:223], v[98:101]
	v_mfma_f32_16x16x32_bf16 v[86:89], v[146:149], v[228:231], v[86:89]
	v_mfma_f32_16x16x32_bf16 v[82:85], v[154:157], v[228:231], v[82:85]
	v_mfma_f32_16x16x32_bf16 v[70:73], v[146:149], v[236:239], v[70:73]
	v_mfma_f32_16x16x32_bf16 v[66:69], v[154:157], v[236:239], v[66:69]
	v_mfma_f32_16x16x32_bf16 v[118:121], v[150:153], v[184:187], v[118:121]
	v_mfma_f32_16x16x32_bf16 v[114:117], v[158:161], v[184:187], v[114:117]
	v_mfma_f32_16x16x32_bf16 v[102:105], v[150:153], v[224:227], v[102:105]
	v_mfma_f32_16x16x32_bf16 v[98:101], v[158:161], v[224:227], v[98:101]
	v_mfma_f32_16x16x32_bf16 v[86:89], v[150:153], v[232:235], v[86:89]
	v_mfma_f32_16x16x32_bf16 v[82:85], v[158:161], v[232:235], v[82:85]
	v_mfma_f32_16x16x32_bf16 v[70:73], v[150:153], v[240:243], v[70:73]
	v_mfma_f32_16x16x32_bf16 v[66:69], v[158:161], v[240:243], v[66:69]
	s_setprio 0
	s_barrier
	s_add_i32 s62, s62, s0
	v_lshl_add_u64 v[162:163], s[30:31], 0, v[0:1]
	s_mov_b32 m0, s62
	s_nop 0
	global_load_lds_dwordx4 v[162:163], off
	s_add_i32 m0, s62, 0x2000
	s_add_u32 s62, s30, 0x40000
	v_lshl_add_u64 v[164:165], s[30:31], 0, v[170:171]
	s_addc_u32 s63, s31, 0
	s_add_i32 s27, s27, s0
	global_load_lds_dwordx4 v[164:165], off
	v_lshl_add_u64 v[206:207], s[62:63], 0, v[0:1]
	s_mov_b32 m0, s27
	v_lshl_add_u64 v[244:245], vcc, 0, v[174:175]
	global_load_lds_dwordx4 v[206:207], off
	v_lshl_add_u64 v[206:207], s[62:63], 0, v[170:171]
	s_add_i32 m0, s27, 0x2000
	s_nop 0
	global_load_lds_dwordx4 v[206:207], off
	v_lshl_add_u64 v[206:207], vcc, 0, v[172:173]
	s_mov_b32 m0, s1
	s_nop 0
	global_load_lds_dwordx4 v[206:207], off
	s_mov_b32 m0, s2
	s_nop 0
	global_load_lds_dwordx4 v[244:245], off
	ds_read_b128 v[180:183], v218 offset:16384
	ds_read_b128 v[184:187], v218 offset:17408
	ds_read_b128 v[220:223], v218 offset:18432
	ds_read_b128 v[224:227], v218 offset:19456
	ds_read_b128 v[228:231], v218 offset:20480
	ds_read_b128 v[232:235], v218 offset:21504
	ds_read_b128 v[236:239], v218 offset:22528
	ds_read_b128 v[240:243], v218 offset:23552
	s_waitcnt vmcnt(8)
	s_waitcnt lgkmcnt(0)
	s_barrier
; #define PG8_STAGE(bufoff, gbase, voff) do { _Pragma("unroll") for (int _i = 0; _i < 2; ++_i) \
;         __builtin_amdgcn_global_load_lds((const unsigned*)((const char*)(gbase) + (voff)[_i]), (LAS unsigned*)(lds + (bufoff) + ldsw + _i * 8192), 16, 0, 0); } while (0)
; #define PG8_LDA(dst, b, h) do { _Pragma("unroll") for (int m = 0; m < 4; ++m) _Pragma("unroll") for (int k = 0; k < 2; ++k) dst[m][k] = *(const LAS bf16x8*)(lds + PG8_SA(b, h) + aoff + m * 2048 + k * 1024); } while (0)
; #define PG8_LDB(dst, b, h) do { _Pragma("unroll") for (int n = 0; n < 2; ++n) _Pragma("unroll") for (int k = 0; k < 2; ++k) dst[n][k] = *(const LAS bf16x8*)(lds + PG8_SB(b, h) + boff + n * 2048 + k * 1024); } while (0)
; #define PG8_MMA(ai, bj, At, Bt) do { __builtin_amdgcn_s_setprio(1); _Pragma("unroll") for (int m = 0; m < 4; ++m) _Pragma("unroll") for (int n = 0; n < 2; ++n) _Pragma("unroll") for (int k = 0; k < 2; ++k) \
;         acc[ai][bj][m][n] = __builtin_amdgcn_mfma_f32_16x16x32_bf16(Bt[n][k], At[m][k], acc[ai][bj][m][n], 0, 0, 0); __builtin_amdgcn_s_setprio(0); } while (0)
; #define PG8_WAIT_V(n) asm volatile("s_waitcnt vmcnt(" #n ")" ::: "memory")
; #define PG8_WAIT_L(n) asm volatile("s_waitcnt lgkmcnt(" #n ")" ::: "memory")
; #define PG8_BAR __builtin_amdgcn_s_barrier()
; #define PG8_SCHED __builtin_amdgcn_sched_barrier(0)
; template <class Epi>
; __device__ __forceinline__ void gemm_phase(LAS unsigned char* lds, const int tid, const Gemm g, const StaticOrder& S, const Epi& E) {
;     ...
;             PG8_WAIT_V(8); PG8_WAIT_L(0); PG8_BAR; PG8_MMA(1, 0, At, B0); PG8_MMA(1, 1, At, B1); PG8_BAR; PG8_SCHED;
;             PG8_LDB(B0, 1, 0); PG8_LDB(B1, 1, 1); PG8_SCHED; PG8_LDA(At, 1, 0); PG8_STAGE(PG8_SA(0, 1), a2 + hstepA, voffA);
;             PG8_WAIT_V(8); PG8_WAIT_L(0); PG8_BAR; PG8_MMA(0, 0, At, B0); PG8_MMA(0, 1, At, B1); PG8_BAR; PG8_SCHED;
	s_setprio 1
	s_waitcnt lgkmcnt(0)
	v_mfma_f32_16x16x32_bf16 v[62:65], v[130:133], v[180:183], v[62:65]
	v_mfma_f32_16x16x32_bf16 v[58:61], v[138:141], v[180:183], v[58:61]
	v_mfma_f32_16x16x32_bf16 v[46:49], v[130:133], v[220:223], v[46:49]
	v_mfma_f32_16x16x32_bf16 v[42:45], v[138:141], v[220:223], v[42:45]
	v_mfma_f32_16x16x32_bf16 v[30:33], v[130:133], v[228:231], v[30:33]
	v_mfma_f32_16x16x32_bf16 v[26:29], v[138:141], v[228:231], v[26:29]
	v_mfma_f32_16x16x32_bf16 v[14:17], v[130:133], v[236:239], v[14:17]
	v_mfma_f32_16x16x32_bf16 v[10:13], v[138:141], v[236:239], v[10:13]
	v_mfma_f32_16x16x32_bf16 v[62:65], v[134:137], v[184:187], v[62:65]
	v_mfma_f32_16x16x32_bf16 v[58:61], v[142:145], v[184:187], v[58:61]
	v_mfma_f32_16x16x32_bf16 v[46:49], v[134:137], v[224:227], v[46:49]
	v_mfma_f32_16x16x32_bf16 v[42:45], v[142:145], v[224:227], v[42:45]
	v_mfma_f32_16x16x32_bf16 v[30:33], v[134:137], v[232:235], v[30:33]
	v_mfma_f32_16x16x32_bf16 v[26:29], v[142:145], v[232:235], v[26:29]
	v_mfma_f32_16x16x32_bf16 v[14:17], v[134:137], v[240:243], v[14:17]
	v_mfma_f32_16x16x32_bf16 v[10:13], v[142:145], v[240:243], v[10:13]
	s_setprio 0
	s_setprio 1
	v_mfma_f32_16x16x32_bf16 v[54:57], v[146:149], v[180:183], v[54:57]
	v_mfma_f32_16x16x32_bf16 v[50:53], v[154:157], v[180:183], v[50:53]
	v_mfma_f32_16x16x32_bf16 v[38:41], v[146:149], v[220:223], v[38:41]
	v_mfma_f32_16x16x32_bf16 v[34:37], v[154:157], v[220:223], v[34:37]
	v_mfma_f32_16x16x32_bf16 v[22:25], v[146:149], v[228:231], v[22:25]
	v_mfma_f32_16x16x32_bf16 v[18:21], v[154:157], v[228:231], v[18:21]
	v_mfma_f32_16x16x32_bf16 v[6:9], v[146:149], v[236:239], v[6:9]
	v_mfma_f32_16x16x32_bf16 v[2:5], v[154:157], v[236:239], v[2:5]
	v_mfma_f32_16x16x32_bf16 v[54:57], v[150:153], v[184:187], v[54:57]
	v_mfma_f32_16x16x32_bf16 v[50:53], v[158:161], v[184:187], v[50:53]
	v_mfma_f32_16x16x32_bf16 v[38:41], v[150:153], v[224:227], v[38:41]
	v_mfma_f32_16x16x32_bf16 v[34:37], v[158:161], v[224:227], v[34:37]
	v_mfma_f32_16x16x32_bf16 v[22:25], v[150:153], v[232:235], v[22:25]
	v_mfma_f32_16x16x32_bf16 v[18:21], v[158:161], v[232:235], v[18:21]
	v_mfma_f32_16x16x32_bf16 v[6:9], v[150:153], v[240:243], v[6:9]
	v_mfma_f32_16x16x32_bf16 v[2:5], v[158:161], v[240:243], v[2:5]
	s_setprio 0
	s_barrier
	s_add_u32 s62, vcc_lo, 0x40000
	s_addc_u32 s63, vcc_hi, 0
	s_mov_b32 m0, s3
	v_lshl_add_u64 v[246:247], s[62:63], 0, v[172:173]
	global_load_lds_dwordx4 v[246:247], off
	v_lshl_add_u64 v[246:247], s[62:63], 0, v[174:175]
	s_mov_b32 m0, s16
	s_nop 0
	global_load_lds_dwordx4 v[246:247], off
	s_add_i32 s27, 0, 0x18000
	s_add_i32 s17, 0, 0x1c000
	v_add_u32_e32 v142, s27, v216
	v_add_u32_e32 v158, s17, v216
	ds_read_b128 v[130:133], v142
	ds_read_b128 v[134:137], v142 offset:1024
	ds_read_b128 v[138:141], v142 offset:2048
	ds_read_b128 v[142:145], v142 offset:3072
	ds_read_b128 v[146:149], v158
	ds_read_b128 v[150:153], v158 offset:1024
	ds_read_b128 v[154:157], v158 offset:2048
	ds_read_b128 v[158:161], v158 offset:3072
	ds_read_b128 v[180:183], v218 offset:32768
	ds_read_b128 v[184:187], v218 offset:33792
	ds_read_b128 v[220:223], v218 offset:34816
	ds_read_b128 v[224:227], v218 offset:35840
	ds_read_b128 v[228:231], v218 offset:36864
	ds_read_b128 v[232:235], v218 offset:37888
	ds_read_b128 v[236:239], v218 offset:38912
	ds_read_b128 v[240:243], v218 offset:39936
	s_waitcnt vmcnt(8)
	s_waitcnt lgkmcnt(0)
	s_barrier
	s_setprio 1
	s_waitcnt lgkmcnt(0)
	v_mfma_f32_16x16x32_bf16 v[126:129], v[130:133], v[180:183], v[126:129]
	v_mfma_f32_16x16x32_bf16 v[122:125], v[138:141], v[180:183], v[122:125]
	v_mfma_f32_16x16x32_bf16 v[110:113], v[130:133], v[220:223], v[110:113]
	v_mfma_f32_16x16x32_bf16 v[106:109], v[138:141], v[220:223], v[106:109]
	v_mfma_f32_16x16x32_bf16 v[94:97], v[130:133], v[228:231], v[94:97]
	v_mfma_f32_16x16x32_bf16 v[90:93], v[138:141], v[228:231], v[90:93]
	v_mfma_f32_16x16x32_bf16 v[78:81], v[130:133], v[236:239], v[78:81]
	v_mfma_f32_16x16x32_bf16 v[74:77], v[138:141], v[236:239], v[74:77]
	v_mfma_f32_16x16x32_bf16 v[126:129], v[134:137], v[184:187], v[126:129]
	v_mfma_f32_16x16x32_bf16 v[122:125], v[142:145], v[184:187], v[122:125]
	v_mfma_f32_16x16x32_bf16 v[110:113], v[134:137], v[224:227], v[110:113]
	v_mfma_f32_16x16x32_bf16 v[106:109], v[142:145], v[224:227], v[106:109]
	v_mfma_f32_16x16x32_bf16 v[94:97], v[134:137], v[232:235], v[94:97]
	v_mfma_f32_16x16x32_bf16 v[90:93], v[142:145], v[232:235], v[90:93]
	v_mfma_f32_16x16x32_bf16 v[78:81], v[134:137], v[240:243], v[78:81]
	v_mfma_f32_16x16x32_bf16 v[74:77], v[142:145], v[240:243], v[74:77]
	s_setprio 0
	s_setprio 1
	v_mfma_f32_16x16x32_bf16 v[118:121], v[146:149], v[180:183], v[118:121]
	v_mfma_f32_16x16x32_bf16 v[114:117], v[154:157], v[180:183], v[114:117]
	v_mfma_f32_16x16x32_bf16 v[102:105], v[146:149], v[220:223], v[102:105]
	v_mfma_f32_16x16x32_bf16 v[98:101], v[154:157], v[220:223], v[98:101]
	v_mfma_f32_16x16x32_bf16 v[86:89], v[146:149], v[228:231], v[86:89]
	v_mfma_f32_16x16x32_bf16 v[82:85], v[154:157], v[228:231], v[82:85]
	v_mfma_f32_16x16x32_bf16 v[70:73], v[146:149], v[236:239], v[70:73]
	v_mfma_f32_16x16x32_bf16 v[66:69], v[154:157], v[236:239], v[66:69]
	v_mfma_f32_16x16x32_bf16 v[118:121], v[150:153], v[184:187], v[118:121]
	v_mfma_f32_16x16x32_bf16 v[114:117], v[158:161], v[184:187], v[114:117]
	v_mfma_f32_16x16x32_bf16 v[102:105], v[150:153], v[224:227], v[102:105]
	v_mfma_f32_16x16x32_bf16 v[98:101], v[158:161], v[224:227], v[98:101]
	v_mfma_f32_16x16x32_bf16 v[86:89], v[150:153], v[232:235], v[86:89]
	v_mfma_f32_16x16x32_bf16 v[82:85], v[158:161], v[232:235], v[82:85]
	v_mfma_f32_16x16x32_bf16 v[70:73], v[150:153], v[240:243], v[70:73]
	v_mfma_f32_16x16x32_bf16 v[66:69], v[158:161], v[240:243], v[66:69]
	s_setprio 0
	s_barrier
; #define PG8_STAGE(bufoff, gbase, voff) do { _Pragma("unroll") for (int _i = 0; _i < 2; ++_i) \
;         __builtin_amdgcn_global_load_lds((const unsigned*)((const char*)(gbase) + (voff)[_i]), (LAS unsigned*)(lds + (bufoff) + ldsw + _i * 8192), 16, 0, 0); } while (0)
; #define PG8_LDA(dst, b, h) do { _Pragma("unroll") for (int m = 0; m < 4; ++m) _Pragma("unroll") for (int k = 0; k < 2; ++k) dst[m][k] = *(const LAS bf16x8*)(lds + PG8_SA(b, h) + aoff + m * 2048 + k * 1024); } while (0)
; #define PG8_MMA(ai, bj, At, Bt) do { __builtin_amdgcn_s_setprio(1); _Pragma("unroll") for (int m = 0; m < 4; ++m) _Pragma("unroll") for (int n = 0; n < 2; ++n) _Pragma("unroll") for (int k = 0; k < 2; ++k) \
;         acc[ai][bj][m][n] = __builtin_amdgcn_mfma_f32_16x16x32_bf16(Bt[n][k], At[m][k], acc[ai][bj][m][n], 0, 0, 0); __builtin_amdgcn_s_setprio(0); } while (0)
; #define PG8_WAIT_V(n) asm volatile("s_waitcnt vmcnt(" #n ")" ::: "memory")
; #define PG8_WAIT_L(n) asm volatile("s_waitcnt lgkmcnt(" #n ")" ::: "memory")
; #define PG8_BAR __builtin_amdgcn_s_barrier()
; #define PG8_SCHED __builtin_amdgcn_sched_barrier(0)
; template <class Epi>
; __device__ __forceinline__ void gemm_phase(LAS unsigned char* lds, const int tid, const Gemm g, const StaticOrder& S, const Epi& E) {
;     ...
;             PG8_LDA(At, 1, 1); PG8_STAGE(PG8_SB(1, 0), b3, voffB); PG8_STAGE(PG8_SB(1, 1), b3 + hstepB, voffB); PG8_STAGE(PG8_SA(1, 0), a3, voffA);
;             PG8_WAIT_V(8); PG8_WAIT_L(0); PG8_BAR; PG8_MMA(1, 0, At, B0); PG8_MMA(1, 1, At, B1); PG8_BAR; PG8_SCHED;
;         }
	s_add_i32 s27, s27, s0
	v_lshl_add_u64 v[162:163], v[162:163], 0, s[36:37]
	s_mov_b32 m0, s27
	s_nop 0
	global_load_lds_dwordx4 v[162:163], off
	s_add_i32 m0, s27, 0x2000
	s_add_u32 s30, s30, 0x40080
	v_lshl_add_u64 v[162:163], v[164:165], 0, s[36:37]
	s_addc_u32 s31, s31, 0
	s_add_i32 s17, s17, s0
	global_load_lds_dwordx4 v[162:163], off
	v_lshl_add_u64 v[162:163], s[30:31], 0, v[0:1]
	s_mov_b32 m0, s17
	s_nop 0
	global_load_lds_dwordx4 v[162:163], off
	v_lshl_add_u64 v[162:163], s[30:31], 0, v[170:171]
	s_add_i32 m0, s17, 0x2000
	s_nop 0
	global_load_lds_dwordx4 v[162:163], off
	v_lshl_add_u64 v[162:163], v[206:207], 0, s[36:37]
	s_mov_b32 m0, s10
	s_nop 0
	global_load_lds_dwordx4 v[162:163], off
	v_lshl_add_u64 v[162:163], v[244:245], 0, s[36:37]
	s_mov_b32 m0, s11
	s_nop 0
	global_load_lds_dwordx4 v[162:163], off
	ds_read_b128 v[180:183], v218 offset:49152
	ds_read_b128 v[184:187], v218 offset:50176
	ds_read_b128 v[220:223], v218 offset:51200
	ds_read_b128 v[224:227], v218 offset:52224
	ds_read_b128 v[228:231], v218 offset:53248
	ds_read_b128 v[232:235], v218 offset:54272
	ds_read_b128 v[236:239], v218 offset:55296
	ds_read_b128 v[240:243], v218 offset:56320
	s_waitcnt vmcnt(8)
	s_waitcnt lgkmcnt(0)
	s_barrier
	s_setprio 1
	s_waitcnt lgkmcnt(0)
	v_mfma_f32_16x16x32_bf16 v[62:65], v[130:133], v[180:183], v[62:65]
	v_mfma_f32_16x16x32_bf16 v[58:61], v[138:141], v[180:183], v[58:61]
	v_mfma_f32_16x16x32_bf16 v[46:49], v[130:133], v[220:223], v[46:49]
	v_mfma_f32_16x16x32_bf16 v[42:45], v[138:141], v[220:223], v[42:45]
	v_mfma_f32_16x16x32_bf16 v[30:33], v[130:133], v[228:231], v[30:33]
	v_mfma_f32_16x16x32_bf16 v[26:29], v[138:141], v[228:231], v[26:29]
	v_mfma_f32_16x16x32_bf16 v[14:17], v[130:133], v[236:239], v[14:17]
	v_mfma_f32_16x16x32_bf16 v[10:13], v[138:141], v[236:239], v[10:13]
	v_mfma_f32_16x16x32_bf16 v[62:65], v[134:137], v[184:187], v[62:65]
	v_mfma_f32_16x16x32_bf16 v[58:61], v[142:145], v[184:187], v[58:61]
	v_mfma_f32_16x16x32_bf16 v[46:49], v[134:137], v[224:227], v[46:49]
	v_mfma_f32_16x16x32_bf16 v[42:45], v[142:145], v[224:227], v[42:45]
	v_mfma_f32_16x16x32_bf16 v[30:33], v[134:137], v[232:235], v[30:33]
	v_mfma_f32_16x16x32_bf16 v[26:29], v[142:145], v[232:235], v[26:29]
	v_mfma_f32_16x16x32_bf16 v[14:17], v[134:137], v[240:243], v[14:17]
	v_mfma_f32_16x16x32_bf16 v[10:13], v[142:145], v[240:243], v[10:13]
	s_setprio 0
	s_setprio 1
	v_mfma_f32_16x16x32_bf16 v[54:57], v[146:149], v[180:183], v[54:57]
	v_mfma_f32_16x16x32_bf16 v[50:53], v[154:157], v[180:183], v[50:53]
	v_mfma_f32_16x16x32_bf16 v[38:41], v[146:149], v[220:223], v[38:41]
	v_mfma_f32_16x16x32_bf16 v[34:37], v[154:157], v[220:223], v[34:37]
	v_mfma_f32_16x16x32_bf16 v[22:25], v[146:149], v[228:231], v[22:25]
	v_mfma_f32_16x16x32_bf16 v[18:21], v[154:157], v[228:231], v[18:21]
	v_mfma_f32_16x16x32_bf16 v[6:9], v[146:149], v[236:239], v[6:9]
	v_mfma_f32_16x16x32_bf16 v[2:5], v[154:157], v[236:239], v[2:5]
	v_mfma_f32_16x16x32_bf16 v[54:57], v[150:153], v[184:187], v[54:57]
	v_mfma_f32_16x16x32_bf16 v[50:53], v[158:161], v[184:187], v[50:53]
	v_mfma_f32_16x16x32_bf16 v[38:41], v[150:153], v[224:227], v[38:41]
	v_mfma_f32_16x16x32_bf16 v[34:37], v[158:161], v[224:227], v[34:37]
	v_mfma_f32_16x16x32_bf16 v[22:25], v[150:153], v[232:235], v[22:25]
	v_mfma_f32_16x16x32_bf16 v[18:21], v[158:161], v[232:235], v[18:21]
	v_mfma_f32_16x16x32_bf16 v[6:9], v[150:153], v[240:243], v[6:9]
	v_mfma_f32_16x16x32_bf16 v[2:5], v[158:161], v[240:243], v[2:5]
	s_setprio 0
	s_barrier
	s_add_i32 s26, s26, 2
	s_add_u32 s68, s68, 0x100
	s_addc_u32 s69, s69, 0
	s_add_u32 s75, s75, 0x100
	s_addc_u32 s83, s83, 0
	s_cmp_gt_u32 s26, 13
	s_cbranch_scc0 .LBB0_1487
	v_readlane_b32 s26, v255, 55
	v_readlane_b32 s27, v255, 56
	s_and_b64 vcc, exec, s[26:27]
	s_cbranch_vccz .LBB0_1490
	s_barrier

; #define PG8_STAGE(bufoff, gbase, voff) do { _Pragma("unroll") for (int _i = 0; _i < 2; ++_i) \
;         __builtin_amdgcn_global_load_lds((const unsigned*)((const char*)(gbase) + (voff)[_i]), (LAS unsigned*)(lds + (bufoff) + ldsw + _i * 8192), 16, 0, 0); } while (0)
; #define PG8_LDA(dst, b, h) do { _Pragma("unroll") for (int m = 0; m < 4; ++m) _Pragma("unroll") for (int k = 0; k < 2; ++k) dst[m][k] = *(const LAS bf16x8*)(lds + PG8_SA(b, h) + aoff + m * 2048 + k * 1024); } while (0)
; #define PG8_LDB(dst, b, h) do { _Pragma("unroll") for (int n = 0; n < 2; ++n) _Pragma("unroll") for (int k = 0; k < 2; ++k) dst[n][k] = *(const LAS bf16x8*)(lds + PG8_SB(b, h) + boff + n * 2048 + k * 1024); } while (0)
; #define PG8_MMA(ai, bj, At, Bt) do { __builtin_amdgcn_s_setprio(1); _Pragma("unroll") for (int m = 0; m < 4; ++m) _Pragma("unroll") for (int n = 0; n < 2; ++n) _Pragma("unroll") for (int k = 0; k < 2; ++k) \
;         acc[ai][bj][m][n] = __builtin_amdgcn_mfma_f32_16x16x32_bf16(Bt[n][k], At[m][k], acc[ai][bj][m][n], 0, 0, 0); __builtin_amdgcn_s_setprio(0); } while (0)
; #define PG8_WAIT_V(n) asm volatile("s_waitcnt vmcnt(" #n ")" ::: "memory")
; #define PG8_WAIT_L(n) asm volatile("s_waitcnt lgkmcnt(" #n ")" ::: "memory")
; #define PG8_BAR __builtin_amdgcn_s_barrier()
; #define PG8_SCHED __builtin_amdgcn_sched_barrier(0)
; template <class Epi>
; __device__ __forceinline__ void gemm_phase(LAS unsigned char* lds, const int tid, const Gemm g, const StaticOrder& S, const Epi& E) {
;     ...
;             const bool last = (t == nt - 2);
;             const char* a1 = cA + (size_t)(t + 1) * kstep;
;             const char* a2 = last ? nA : cA + (size_t)(t + 2) * kstep; const char* b2 = last ? nB : cB + (size_t)(t + 2) * kstep;
;             const char* a3 = a2 + kstep; const char* b3 = b2 + kstep;
;             PG8_LDB(B0, 0, 0); PG8_LDB(B1, 0, 1); PG8_SCHED; PG8_LDA(At, 0, 0); PG8_STAGE(PG8_SA(1, 1), a1 + hstepA, voffA);
;             PG8_WAIT_V(8); PG8_WAIT_L(0); PG8_BAR; PG8_MMA(0, 0, At, B0); PG8_MMA(0, 1, At, B1); PG8_BAR; PG8_SCHED;
;             PG8_LDA(At, 0, 1); PG8_STAGE(PG8_SB(0, 0), b2, voffB); PG8_STAGE(PG8_SB(0, 1), b2 + hstepB, voffB); PG8_STAGE(PG8_SA(0, 0), a2, voffA);
.LBB0_1912:
	v_lshl_add_u64 v[162:163], s[82:83], 0, v[152:153]
	s_add_i32 m0, s66, 0xc000
	s_nop 0
	global_load_lds_dwordx4 v[162:163], off
	v_lshl_add_u64 v[162:163], s[82:83], 0, v[154:155]
	s_add_i32 m0, s66, 0xe000
	s_nop 0
	global_load_lds_dwordx4 v[162:163], off
	s_add_u32 s30, s82, 0xfffc0080
	s_addc_u32 s31, s83, -1
	s_add_i32 s92, 0, 0x10000
	s_cmp_eq_u32 s17, 12
	s_cselect_b32 s89, s7, s31
	s_cselect_b32 s88, s65, s30
	s_cselect_b32 s31, s5, s27
	s_cselect_b32 s30, vcc_lo, vcc_hi
	s_add_i32 s11, 0, 0x14000
	v_add_u32_e32 v110, s92, v158
	v_add_u32_e32 v162, s11, v158
	ds_read_b128 v[98:101], v110
	ds_read_b128 v[102:105], v110 offset:1024
	ds_read_b128 v[106:109], v110 offset:2048
	ds_read_b128 v[110:113], v110 offset:3072
	ds_read_b128 v[174:177], v162
	ds_read_b128 v[178:181], v162 offset:1024
	ds_read_b128 v[182:185], v162 offset:2048
	ds_read_b128 v[186:189], v162 offset:3072
	ds_read_b128 v[190:193], v172
	ds_read_b128 v[194:197], v172 offset:1024
	ds_read_b128 v[198:201], v172 offset:2048
	ds_read_b128 v[210:213], v172 offset:3072
	ds_read_b128 v[214:217], v172 offset:4096
	ds_read_b128 v[218:221], v172 offset:5120
	ds_read_b128 v[222:225], v172 offset:6144
	ds_read_b128 v[226:229], v172 offset:7168
	s_waitcnt vmcnt(8)
	s_waitcnt lgkmcnt(0)
	s_barrier
	s_setprio 1
	s_waitcnt lgkmcnt(0)
	v_mfma_f32_16x16x32_bf16 v[142:145], v[98:101], v[190:193], v[142:145]
	v_mfma_f32_16x16x32_bf16 v[138:141], v[106:109], v[190:193], v[138:141]
	v_mfma_f32_16x16x32_bf16 v[134:137], v[98:101], v[198:201], v[134:137]
	v_mfma_f32_16x16x32_bf16 v[130:133], v[106:109], v[198:201], v[130:133]
	v_mfma_f32_16x16x32_bf16 v[94:97], v[98:101], v[214:217], v[94:97]
	v_mfma_f32_16x16x32_bf16 v[90:93], v[106:109], v[214:217], v[90:93]
	v_mfma_f32_16x16x32_bf16 v[78:81], v[98:101], v[222:225], v[78:81]
	v_mfma_f32_16x16x32_bf16 v[74:77], v[106:109], v[222:225], v[74:77]
	v_mfma_f32_16x16x32_bf16 v[142:145], v[102:105], v[194:197], v[142:145]
	v_mfma_f32_16x16x32_bf16 v[138:141], v[110:113], v[194:197], v[138:141]
	v_mfma_f32_16x16x32_bf16 v[134:137], v[102:105], v[210:213], v[134:137]
	v_mfma_f32_16x16x32_bf16 v[130:133], v[110:113], v[210:213], v[130:133]
	v_mfma_f32_16x16x32_bf16 v[94:97], v[102:105], v[218:221], v[94:97]
	v_mfma_f32_16x16x32_bf16 v[90:93], v[110:113], v[218:221], v[90:93]
	v_mfma_f32_16x16x32_bf16 v[78:81], v[102:105], v[226:229], v[78:81]
	v_mfma_f32_16x16x32_bf16 v[74:77], v[110:113], v[226:229], v[74:77]
	s_setprio 0
	s_setprio 1
	v_mfma_f32_16x16x32_bf16 v[126:129], v[174:177], v[190:193], v[126:129]
	v_mfma_f32_16x16x32_bf16 v[122:125], v[182:185], v[190:193], v[122:125]
	v_mfma_f32_16x16x32_bf16 v[118:121], v[174:177], v[198:201], v[118:121]
	v_mfma_f32_16x16x32_bf16 v[114:117], v[182:185], v[198:201], v[114:117]
	v_mfma_f32_16x16x32_bf16 v[86:89], v[174:177], v[214:217], v[86:89]
	v_mfma_f32_16x16x32_bf16 v[82:85], v[182:185], v[214:217], v[82:85]
	v_mfma_f32_16x16x32_bf16 v[70:73], v[174:177], v[222:225], v[70:73]
	v_mfma_f32_16x16x32_bf16 v[66:69], v[182:185], v[222:225], v[66:69]
	v_mfma_f32_16x16x32_bf16 v[126:129], v[178:181], v[194:197], v[126:129]
	v_mfma_f32_16x16x32_bf16 v[122:125], v[186:189], v[194:197], v[122:125]
	v_mfma_f32_16x16x32_bf16 v[118:121], v[178:181], v[210:213], v[118:121]
	v_mfma_f32_16x16x32_bf16 v[114:117], v[186:189], v[210:213], v[114:117]
	v_mfma_f32_16x16x32_bf16 v[86:89], v[178:181], v[218:221], v[86:89]
	v_mfma_f32_16x16x32_bf16 v[82:85], v[186:189], v[218:221], v[82:85]
	v_mfma_f32_16x16x32_bf16 v[70:73], v[178:181], v[226:229], v[70:73]
	v_mfma_f32_16x16x32_bf16 v[66:69], v[186:189], v[226:229], v[66:69]
	s_setprio 0
	s_barrier
	s_add_i32 s92, s92, s28
	v_lshl_add_u64 v[162:163], s[30:31], 0, v[0:1]
	s_mov_b32 m0, s92
	s_nop 0
	global_load_lds_dwordx4 v[162:163], off
	s_add_i32 m0, s92, 0x2000
	s_add_u32 s92, s30, 0x40000
	v_lshl_add_u64 v[164:165], s[30:31], 0, v[146:147]
	s_addc_u32 s93, s31, 0
	s_add_i32 s11, s11, s28
	global_load_lds_dwordx4 v[164:165], off
	v_lshl_add_u64 v[202:203], s[92:93], 0, v[0:1]
	s_mov_b32 m0, s11
	v_lshl_add_u64 v[206:207], s[88:89], 0, v[148:149]
	global_load_lds_dwordx4 v[202:203], off
	v_lshl_add_u64 v[202:203], s[92:93], 0, v[146:147]
	s_add_i32 m0, s11, 0x2000
	s_nop 0
	global_load_lds_dwordx4 v[202:203], off
	v_lshl_add_u64 v[202:203], s[88:89], 0, v[150:151]
	s_mov_b32 m0, s66
	s_nop 0
	global_load_lds_dwordx4 v[202:203], off
	s_mov_b32 m0, s67
	s_nop 0
	global_load_lds_dwordx4 v[206:207], off
	ds_read_b128 v[190:193], v172 offset:16384
	ds_read_b128 v[194:197], v172 offset:17408
	ds_read_b128 v[198:201], v172 offset:18432
	ds_read_b128 v[210:213], v172 offset:19456
	ds_read_b128 v[214:217], v172 offset:20480
	ds_read_b128 v[218:221], v172 offset:21504
	ds_read_b128 v[222:225], v172 offset:22528
	ds_read_b128 v[226:229], v172 offset:23552
	s_waitcnt vmcnt(8)
	s_waitcnt lgkmcnt(0)
	s_barrier
; #define PG8_STAGE(bufoff, gbase, voff) do { _Pragma("unroll") for (int _i = 0; _i < 2; ++_i) \
;         __builtin_amdgcn_global_load_lds((const unsigned*)((const char*)(gbase) + (voff)[_i]), (LAS unsigned*)(lds + (bufoff) + ldsw + _i * 8192), 16, 0, 0); } while (0)
; #define PG8_LDA(dst, b, h) do { _Pragma("unroll") for (int m = 0; m < 4; ++m) _Pragma("unroll") for (int k = 0; k < 2; ++k) dst[m][k] = *(const LAS bf16x8*)(lds + PG8_SA(b, h) + aoff + m * 2048 + k * 1024); } while (0)
; #define PG8_LDB(dst, b, h) do { _Pragma("unroll") for (int n = 0; n < 2; ++n) _Pragma("unroll") for (int k = 0; k < 2; ++k) dst[n][k] = *(const LAS bf16x8*)(lds + PG8_SB(b, h) + boff + n * 2048 + k * 1024); } while (0)
; #define PG8_MMA(ai, bj, At, Bt) do { __builtin_amdgcn_s_setprio(1); _Pragma("unroll") for (int m = 0; m < 4; ++m) _Pragma("unroll") for (int n = 0; n < 2; ++n) _Pragma("unroll") for (int k = 0; k < 2; ++k) \
;         acc[ai][bj][m][n] = __builtin_amdgcn_mfma_f32_16x16x32_bf16(Bt[n][k], At[m][k], acc[ai][bj][m][n], 0, 0, 0); __builtin_amdgcn_s_setprio(0); } while (0)
; #define PG8_WAIT_V(n) asm volatile("s_waitcnt vmcnt(" #n ")" ::: "memory")
; #define PG8_WAIT_L(n) asm volatile("s_waitcnt lgkmcnt(" #n ")" ::: "memory")
; #define PG8_BAR __builtin_amdgcn_s_barrier()
; #define PG8_SCHED __builtin_amdgcn_sched_barrier(0)
; template <class Epi>
; __device__ __forceinline__ void gemm_phase(LAS unsigned char* lds, const int tid, const Gemm g, const StaticOrder& S, const Epi& E) {
;     ...
;             PG8_WAIT_V(8); PG8_WAIT_L(0); PG8_BAR; PG8_MMA(1, 0, At, B0); PG8_MMA(1, 1, At, B1); PG8_BAR; PG8_SCHED;
;             PG8_LDB(B0, 1, 0); PG8_LDB(B1, 1, 1); PG8_SCHED; PG8_LDA(At, 1, 0); PG8_STAGE(PG8_SA(0, 1), a2 + hstepA, voffA);
;             PG8_WAIT_V(8); PG8_WAIT_L(0); PG8_BAR; PG8_MMA(0, 0, At, B0); PG8_MMA(0, 1, At, B1); PG8_BAR; PG8_SCHED;
	s_setprio 1
	s_waitcnt lgkmcnt(0)
	v_mfma_f32_16x16x32_bf16 v[62:65], v[98:101], v[190:193], v[62:65]
	v_mfma_f32_16x16x32_bf16 v[58:61], v[106:109], v[190:193], v[58:61]
	v_mfma_f32_16x16x32_bf16 v[54:57], v[98:101], v[198:201], v[54:57]
	v_mfma_f32_16x16x32_bf16 v[46:49], v[106:109], v[198:201], v[46:49]
	v_mfma_f32_16x16x32_bf16 v[30:33], v[98:101], v[214:217], v[30:33]
	v_mfma_f32_16x16x32_bf16 v[26:29], v[106:109], v[214:217], v[26:29]
	v_mfma_f32_16x16x32_bf16 v[22:25], v[98:101], v[222:225], v[22:25]
	v_mfma_f32_16x16x32_bf16 v[14:17], v[106:109], v[222:225], v[14:17]
	v_mfma_f32_16x16x32_bf16 v[62:65], v[102:105], v[194:197], v[62:65]
	v_mfma_f32_16x16x32_bf16 v[58:61], v[110:113], v[194:197], v[58:61]
	v_mfma_f32_16x16x32_bf16 v[54:57], v[102:105], v[210:213], v[54:57]
	v_mfma_f32_16x16x32_bf16 v[46:49], v[110:113], v[210:213], v[46:49]
	v_mfma_f32_16x16x32_bf16 v[30:33], v[102:105], v[218:221], v[30:33]
	v_mfma_f32_16x16x32_bf16 v[26:29], v[110:113], v[218:221], v[26:29]
	v_mfma_f32_16x16x32_bf16 v[22:25], v[102:105], v[226:229], v[22:25]
	v_mfma_f32_16x16x32_bf16 v[14:17], v[110:113], v[226:229], v[14:17]
	s_setprio 0
	s_setprio 1
	v_mfma_f32_16x16x32_bf16 v[50:53], v[174:177], v[190:193], v[50:53]
	v_mfma_f32_16x16x32_bf16 v[42:45], v[182:185], v[190:193], v[42:45]
	v_mfma_f32_16x16x32_bf16 v[38:41], v[174:177], v[198:201], v[38:41]
	v_mfma_f32_16x16x32_bf16 v[34:37], v[182:185], v[198:201], v[34:37]
	v_mfma_f32_16x16x32_bf16 v[18:21], v[174:177], v[214:217], v[18:21]
	v_mfma_f32_16x16x32_bf16 v[10:13], v[182:185], v[214:217], v[10:13]
	v_mfma_f32_16x16x32_bf16 v[6:9], v[174:177], v[222:225], v[6:9]
	v_mfma_f32_16x16x32_bf16 v[2:5], v[182:185], v[222:225], v[2:5]
	v_mfma_f32_16x16x32_bf16 v[50:53], v[178:181], v[194:197], v[50:53]
	v_mfma_f32_16x16x32_bf16 v[42:45], v[186:189], v[194:197], v[42:45]
	v_mfma_f32_16x16x32_bf16 v[38:41], v[178:181], v[210:213], v[38:41]
	v_mfma_f32_16x16x32_bf16 v[34:37], v[186:189], v[210:213], v[34:37]
	v_mfma_f32_16x16x32_bf16 v[18:21], v[178:181], v[218:221], v[18:21]
	v_mfma_f32_16x16x32_bf16 v[10:13], v[186:189], v[218:221], v[10:13]
	v_mfma_f32_16x16x32_bf16 v[6:9], v[178:181], v[226:229], v[6:9]
	v_mfma_f32_16x16x32_bf16 v[2:5], v[186:189], v[226:229], v[2:5]
	s_setprio 0
	s_barrier
	s_add_u32 s88, s88, 0x40000
	s_addc_u32 s89, s89, 0
	s_mov_b32 m0, s70
	v_lshl_add_u64 v[230:231], s[88:89], 0, v[150:151]
	global_load_lds_dwordx4 v[230:231], off
	v_lshl_add_u64 v[230:231], s[88:89], 0, v[148:149]
	s_mov_b32 m0, s71
	s_nop 0
	global_load_lds_dwordx4 v[230:231], off
	s_add_i32 s11, 0, 0x18000
	s_add_i32 s92, 0, 0x1c000
	v_add_u32_e32 v110, s11, v158
	v_add_u32_e32 v173, s92, v158
	ds_read_b128 v[98:101], v110
	ds_read_b128 v[102:105], v110 offset:1024
	ds_read_b128 v[106:109], v110 offset:2048
	ds_read_b128 v[110:113], v110 offset:3072
	ds_read_b128 v[174:177], v173
	ds_read_b128 v[178:181], v173 offset:1024
	ds_read_b128 v[182:185], v173 offset:2048
	ds_read_b128 v[186:189], v173 offset:3072
	ds_read_b128 v[190:193], v172 offset:32768
	ds_read_b128 v[194:197], v172 offset:33792
	ds_read_b128 v[198:201], v172 offset:34816
	ds_read_b128 v[210:213], v172 offset:35840
	ds_read_b128 v[214:217], v172 offset:36864
	ds_read_b128 v[218:221], v172 offset:37888
	ds_read_b128 v[222:225], v172 offset:38912
	ds_read_b128 v[226:229], v172 offset:39936
	s_waitcnt vmcnt(8)
	s_waitcnt lgkmcnt(0)
	s_barrier
	s_setprio 1
	s_waitcnt lgkmcnt(0)
	v_mfma_f32_16x16x32_bf16 v[142:145], v[98:101], v[190:193], v[142:145]
	v_mfma_f32_16x16x32_bf16 v[138:141], v[106:109], v[190:193], v[138:141]
	v_mfma_f32_16x16x32_bf16 v[134:137], v[98:101], v[198:201], v[134:137]
	v_mfma_f32_16x16x32_bf16 v[130:133], v[106:109], v[198:201], v[130:133]
	v_mfma_f32_16x16x32_bf16 v[94:97], v[98:101], v[214:217], v[94:97]
	v_mfma_f32_16x16x32_bf16 v[90:93], v[106:109], v[214:217], v[90:93]
	v_mfma_f32_16x16x32_bf16 v[78:81], v[98:101], v[222:225], v[78:81]
	v_mfma_f32_16x16x32_bf16 v[74:77], v[106:109], v[222:225], v[74:77]
	v_mfma_f32_16x16x32_bf16 v[142:145], v[102:105], v[194:197], v[142:145]
	v_mfma_f32_16x16x32_bf16 v[138:141], v[110:113], v[194:197], v[138:141]
	v_mfma_f32_16x16x32_bf16 v[134:137], v[102:105], v[210:213], v[134:137]
	v_mfma_f32_16x16x32_bf16 v[130:133], v[110:113], v[210:213], v[130:133]
	v_mfma_f32_16x16x32_bf16 v[94:97], v[102:105], v[218:221], v[94:97]
	v_mfma_f32_16x16x32_bf16 v[90:93], v[110:113], v[218:221], v[90:93]
	v_mfma_f32_16x16x32_bf16 v[78:81], v[102:105], v[226:229], v[78:81]
	v_mfma_f32_16x16x32_bf16 v[74:77], v[110:113], v[226:229], v[74:77]
	s_setprio 0
	s_setprio 1
	v_mfma_f32_16x16x32_bf16 v[126:129], v[174:177], v[190:193], v[126:129]
	v_mfma_f32_16x16x32_bf16 v[122:125], v[182:185], v[190:193], v[122:125]
	v_mfma_f32_16x16x32_bf16 v[118:121], v[174:177], v[198:201], v[118:121]
	v_mfma_f32_16x16x32_bf16 v[114:117], v[182:185], v[198:201], v[114:117]
	v_mfma_f32_16x16x32_bf16 v[86:89], v[174:177], v[214:217], v[86:89]
	v_mfma_f32_16x16x32_bf16 v[82:85], v[182:185], v[214:217], v[82:85]
	v_mfma_f32_16x16x32_bf16 v[70:73], v[174:177], v[222:225], v[70:73]
	v_mfma_f32_16x16x32_bf16 v[66:69], v[182:185], v[222:225], v[66:69]
	v_mfma_f32_16x16x32_bf16 v[126:129], v[178:181], v[194:197], v[126:129]
	v_mfma_f32_16x16x32_bf16 v[122:125], v[186:189], v[194:197], v[122:125]
	v_mfma_f32_16x16x32_bf16 v[118:121], v[178:181], v[210:213], v[118:121]
	v_mfma_f32_16x16x32_bf16 v[114:117], v[186:189], v[210:213], v[114:117]
	v_mfma_f32_16x16x32_bf16 v[86:89], v[178:181], v[218:221], v[86:89]
	v_mfma_f32_16x16x32_bf16 v[82:85], v[186:189], v[218:221], v[82:85]
	v_mfma_f32_16x16x32_bf16 v[70:73], v[178:181], v[226:229], v[70:73]
	v_mfma_f32_16x16x32_bf16 v[66:69], v[186:189], v[226:229], v[66:69]
	s_setprio 0
	s_barrier
; #define PG8_STAGE(bufoff, gbase, voff) do { _Pragma("unroll") for (int _i = 0; _i < 2; ++_i) \
;         __builtin_amdgcn_global_load_lds((const unsigned*)((const char*)(gbase) + (voff)[_i]), (LAS unsigned*)(lds + (bufoff) + ldsw + _i * 8192), 16, 0, 0); } while (0)
; #define PG8_LDA(dst, b, h) do { _Pragma("unroll") for (int m = 0; m < 4; ++m) _Pragma("unroll") for (int k = 0; k < 2; ++k) dst[m][k] = *(const LAS bf16x8*)(lds + PG8_SA(b, h) + aoff + m * 2048 + k * 1024); } while (0)
; #define PG8_MMA(ai, bj, At, Bt) do { __builtin_amdgcn_s_setprio(1); _Pragma("unroll") for (int m = 0; m < 4; ++m) _Pragma("unroll") for (int n = 0; n < 2; ++n) _Pragma("unroll") for (int k = 0; k < 2; ++k) \
;         acc[ai][bj][m][n] = __builtin_amdgcn_mfma_f32_16x16x32_bf16(Bt[n][k], At[m][k], acc[ai][bj][m][n], 0, 0, 0); __builtin_amdgcn_s_setprio(0); } while (0)
; #define PG8_WAIT_V(n) asm volatile("s_waitcnt vmcnt(" #n ")" ::: "memory")
; #define PG8_WAIT_L(n) asm volatile("s_waitcnt lgkmcnt(" #n ")" ::: "memory")
; #define PG8_BAR __builtin_amdgcn_s_barrier()
; #define PG8_SCHED __builtin_amdgcn_sched_barrier(0)
; template <class Epi>
; __device__ __forceinline__ void gemm_phase(LAS unsigned char* lds, const int tid, const Gemm g, const StaticOrder& S, const Epi& E) {
;     ...
;             PG8_LDA(At, 1, 1); PG8_STAGE(PG8_SB(1, 0), b3, voffB); PG8_STAGE(PG8_SB(1, 1), b3 + hstepB, voffB); PG8_STAGE(PG8_SA(1, 0), a3, voffA);
;             PG8_WAIT_V(8); PG8_WAIT_L(0); PG8_BAR; PG8_MMA(1, 0, At, B0); PG8_MMA(1, 1, At, B1); PG8_BAR; PG8_SCHED;
;         }
	s_add_i32 s11, s11, s28
	v_lshl_add_u64 v[162:163], v[162:163], 0, s[36:37]
	s_mov_b32 m0, s11
	s_nop 0
	global_load_lds_dwordx4 v[162:163], off
	s_add_i32 m0, s11, 0x2000
	s_add_u32 s30, s30, 0x40080
	v_lshl_add_u64 v[162:163], v[164:165], 0, s[36:37]
	s_addc_u32 s31, s31, 0
	s_add_i32 s11, s92, s28
	global_load_lds_dwordx4 v[162:163], off
	v_lshl_add_u64 v[162:163], s[30:31], 0, v[0:1]
	s_mov_b32 m0, s11
	s_nop 0
	global_load_lds_dwordx4 v[162:163], off
	v_lshl_add_u64 v[162:163], s[30:31], 0, v[146:147]
	s_add_i32 m0, s11, 0x2000
	s_nop 0
	global_load_lds_dwordx4 v[162:163], off
	v_lshl_add_u64 v[162:163], v[202:203], 0, s[36:37]
	s_mov_b32 m0, s72
	s_nop 0
	global_load_lds_dwordx4 v[162:163], off
	v_lshl_add_u64 v[162:163], v[206:207], 0, s[36:37]
	s_mov_b32 m0, s73
	s_nop 0
	global_load_lds_dwordx4 v[162:163], off
	ds_read_b128 v[190:193], v172 offset:49152
	ds_read_b128 v[194:197], v172 offset:50176
	ds_read_b128 v[198:201], v172 offset:51200
	ds_read_b128 v[210:213], v172 offset:52224
	ds_read_b128 v[214:217], v172 offset:53248
	ds_read_b128 v[218:221], v172 offset:54272
	ds_read_b128 v[222:225], v172 offset:55296
	ds_read_b128 v[226:229], v172 offset:56320
	s_waitcnt vmcnt(8)
	s_waitcnt lgkmcnt(0)
	s_barrier
	s_setprio 1
	s_waitcnt lgkmcnt(0)
	v_mfma_f32_16x16x32_bf16 v[62:65], v[98:101], v[190:193], v[62:65]
	v_mfma_f32_16x16x32_bf16 v[58:61], v[106:109], v[190:193], v[58:61]
	v_mfma_f32_16x16x32_bf16 v[54:57], v[98:101], v[198:201], v[54:57]
	v_mfma_f32_16x16x32_bf16 v[46:49], v[106:109], v[198:201], v[46:49]
	v_mfma_f32_16x16x32_bf16 v[30:33], v[98:101], v[214:217], v[30:33]
	v_mfma_f32_16x16x32_bf16 v[26:29], v[106:109], v[214:217], v[26:29]
	v_mfma_f32_16x16x32_bf16 v[22:25], v[98:101], v[222:225], v[22:25]
	v_mfma_f32_16x16x32_bf16 v[14:17], v[106:109], v[222:225], v[14:17]
	v_mfma_f32_16x16x32_bf16 v[62:65], v[102:105], v[194:197], v[62:65]
	v_mfma_f32_16x16x32_bf16 v[58:61], v[110:113], v[194:197], v[58:61]
	v_mfma_f32_16x16x32_bf16 v[54:57], v[102:105], v[210:213], v[54:57]
	v_mfma_f32_16x16x32_bf16 v[46:49], v[110:113], v[210:213], v[46:49]
	v_mfma_f32_16x16x32_bf16 v[30:33], v[102:105], v[218:221], v[30:33]
	v_mfma_f32_16x16x32_bf16 v[26:29], v[110:113], v[218:221], v[26:29]
	v_mfma_f32_16x16x32_bf16 v[22:25], v[102:105], v[226:229], v[22:25]
	v_mfma_f32_16x16x32_bf16 v[14:17], v[110:113], v[226:229], v[14:17]
	s_setprio 0
	s_setprio 1
	v_mfma_f32_16x16x32_bf16 v[50:53], v[174:177], v[190:193], v[50:53]
	v_mfma_f32_16x16x32_bf16 v[42:45], v[182:185], v[190:193], v[42:45]
	v_mfma_f32_16x16x32_bf16 v[38:41], v[174:177], v[198:201], v[38:41]
	v_mfma_f32_16x16x32_bf16 v[34:37], v[182:185], v[198:201], v[34:37]
	v_mfma_f32_16x16x32_bf16 v[18:21], v[174:177], v[214:217], v[18:21]
	v_mfma_f32_16x16x32_bf16 v[10:13], v[182:185], v[214:217], v[10:13]
	v_mfma_f32_16x16x32_bf16 v[6:9], v[174:177], v[222:225], v[6:9]
	v_mfma_f32_16x16x32_bf16 v[2:5], v[182:185], v[222:225], v[2:5]
	v_mfma_f32_16x16x32_bf16 v[50:53], v[178:181], v[194:197], v[50:53]
	v_mfma_f32_16x16x32_bf16 v[42:45], v[186:189], v[194:197], v[42:45]
	v_mfma_f32_16x16x32_bf16 v[38:41], v[178:181], v[210:213], v[38:41]
	v_mfma_f32_16x16x32_bf16 v[34:37], v[186:189], v[210:213], v[34:37]
	v_mfma_f32_16x16x32_bf16 v[18:21], v[178:181], v[218:221], v[18:21]
	v_mfma_f32_16x16x32_bf16 v[10:13], v[186:189], v[218:221], v[10:13]
	v_mfma_f32_16x16x32_bf16 v[6:9], v[178:181], v[226:229], v[6:9]
	v_mfma_f32_16x16x32_bf16 v[2:5], v[186:189], v[226:229], v[2:5]
	s_setprio 0
	s_barrier
	s_add_i32 s17, s17, 2
	s_add_u32 s82, s82, 0x100
	s_addc_u32 s83, s83, 0
	s_add_u32 vcc_hi, vcc_hi, 0x100
	s_addc_u32 s27, s27, 0
	s_cmp_gt_u32 s17, 13
	s_cbranch_scc0 .LBB0_1912
	s_and_b64 vcc, exec, s[2:3]
	s_cbranch_vccz .LBB0_1915
	s_barrier

; #define PG8_STAGE(bufoff, gbase, voff) do { _Pragma("unroll") for (int _i = 0; _i < 2; ++_i) \
;         __builtin_amdgcn_global_load_lds((const unsigned*)((const char*)(gbase) + (voff)[_i]), (LAS unsigned*)(lds + (bufoff) + ldsw + _i * 8192), 16, 0, 0); } while (0)
; #define PG8_LDA(dst, b, h) do { _Pragma("unroll") for (int m = 0; m < 4; ++m) _Pragma("unroll") for (int k = 0; k < 2; ++k) dst[m][k] = *(const LAS bf16x8*)(lds + PG8_SA(b, h) + aoff + m * 2048 + k * 1024); } while (0)
; #define PG8_LDB(dst, b, h) do { _Pragma("unroll") for (int n = 0; n < 2; ++n) _Pragma("unroll") for (int k = 0; k < 2; ++k) dst[n][k] = *(const LAS bf16x8*)(lds + PG8_SB(b, h) + boff + n * 2048 + k * 1024); } while (0)
; #define PG8_MMA(ai, bj, At, Bt) do { __builtin_amdgcn_s_setprio(1); _Pragma("unroll") for (int m = 0; m < 4; ++m) _Pragma("unroll") for (int n = 0; n < 2; ++n) _Pragma("unroll") for (int k = 0; k < 2; ++k) \
;         acc[ai][bj][m][n] = __builtin_amdgcn_mfma_f32_16x16x32_bf16(Bt[n][k], At[m][k], acc[ai][bj][m][n], 0, 0, 0); __builtin_amdgcn_s_setprio(0); } while (0)
; #define PG8_WAIT_V(n) asm volatile("s_waitcnt vmcnt(" #n ")" ::: "memory")
; #define PG8_WAIT_L(n) asm volatile("s_waitcnt lgkmcnt(" #n ")" ::: "memory")
; #define PG8_BAR __builtin_amdgcn_s_barrier()
; #define PG8_SCHED __builtin_amdgcn_sched_barrier(0)
; template <class Epi>
; __device__ __forceinline__ void gemm_phase(LAS unsigned char* lds, const int tid, const Gemm g, const StaticOrder& S, const Epi& E) {
;     ...
;             const bool last = (t == nt - 2);
;             const char* a1 = cA + (size_t)(t + 1) * kstep;
;             const char* a2 = last ? nA : cA + (size_t)(t + 2) * kstep; const char* b2 = last ? nB : cB + (size_t)(t + 2) * kstep;
;             const char* a3 = a2 + kstep; const char* b3 = b2 + kstep;
;             PG8_LDB(B0, 0, 0); PG8_LDB(B1, 0, 1); PG8_SCHED; PG8_LDA(At, 0, 0); PG8_STAGE(PG8_SA(1, 1), a1 + hstepA, voffA);
;             PG8_WAIT_V(8); PG8_WAIT_L(0); PG8_BAR; PG8_MMA(0, 0, At, B0); PG8_MMA(0, 1, At, B1); PG8_BAR; PG8_SCHED;
;             PG8_LDA(At, 0, 1); PG8_STAGE(PG8_SB(0, 0), b2, voffB); PG8_STAGE(PG8_SB(0, 1), b2 + hstepB, voffB); PG8_STAGE(PG8_SA(0, 0), a2, voffA);
.LBB0_2193:
	v_lshl_add_u64 v[162:163], s[30:31], 0, v[150:151]
	s_add_i32 m0, s5, 0xc000
	s_nop 0
	global_load_lds_dwordx4 v[162:163], off
	v_lshl_add_u64 v[162:163], s[30:31], 0, v[152:153]
	s_add_i32 m0, s5, 0xe000
	s_nop 0
	global_load_lds_dwordx4 v[162:163], off
	s_add_u32 s70, s30, 0x100
	s_addc_u32 s71, s31, 0
	s_add_i32 s76, 0, 0x10000
	s_cmp_eq_u32 vcc_hi, 40
	s_cselect_b32 s75, s1, s71
	s_cselect_b32 s74, s0, s70
	s_cselect_b32 s73, s69, vcc_lo
	s_cselect_b32 s72, s68, s28
	s_add_i32 s2, 0, 0x14000
	v_add_u32_e32 v154, s76, v179
	v_add_u32_e32 v162, s2, v179
	ds_read_b128 v[130:133], v154
	ds_read_b128 v[134:137], v154 offset:1024
	ds_read_b128 v[138:141], v154 offset:2048
	ds_read_b128 v[154:157], v154 offset:3072
	ds_read_b128 v[158:161], v162
	ds_read_b128 v[170:173], v162 offset:1024
	ds_read_b128 v[174:177], v162 offset:2048
	ds_read_b128 v[184:187], v162 offset:3072
	ds_read_b128 v[188:191], v181
	ds_read_b128 v[192:195], v181 offset:1024
	ds_read_b128 v[196:199], v181 offset:2048
	ds_read_b128 v[200:203], v181 offset:3072
	ds_read_b128 v[212:215], v181 offset:4096
	ds_read_b128 v[216:219], v181 offset:5120
	ds_read_b128 v[220:223], v181 offset:6144
	ds_read_b128 v[224:227], v181 offset:7168
	s_waitcnt vmcnt(8)
	s_waitcnt lgkmcnt(0)
	s_barrier
	s_setprio 1
	s_waitcnt lgkmcnt(0)
	v_mfma_f32_16x16x32_bf16 v[126:129], v[130:133], v[188:191], v[126:129]
	v_mfma_f32_16x16x32_bf16 v[122:125], v[138:141], v[188:191], v[122:125]
	v_mfma_f32_16x16x32_bf16 v[110:113], v[130:133], v[196:199], v[110:113]
	v_mfma_f32_16x16x32_bf16 v[106:109], v[138:141], v[196:199], v[106:109]
	v_mfma_f32_16x16x32_bf16 v[94:97], v[130:133], v[212:215], v[94:97]
	v_mfma_f32_16x16x32_bf16 v[90:93], v[138:141], v[212:215], v[90:93]
	v_mfma_f32_16x16x32_bf16 v[78:81], v[130:133], v[220:223], v[78:81]
	v_mfma_f32_16x16x32_bf16 v[74:77], v[138:141], v[220:223], v[74:77]
	v_mfma_f32_16x16x32_bf16 v[126:129], v[134:137], v[192:195], v[126:129]
	v_mfma_f32_16x16x32_bf16 v[122:125], v[154:157], v[192:195], v[122:125]
	v_mfma_f32_16x16x32_bf16 v[110:113], v[134:137], v[200:203], v[110:113]
	v_mfma_f32_16x16x32_bf16 v[106:109], v[154:157], v[200:203], v[106:109]
	v_mfma_f32_16x16x32_bf16 v[94:97], v[134:137], v[216:219], v[94:97]
	v_mfma_f32_16x16x32_bf16 v[90:93], v[154:157], v[216:219], v[90:93]
	v_mfma_f32_16x16x32_bf16 v[78:81], v[134:137], v[224:227], v[78:81]
	v_mfma_f32_16x16x32_bf16 v[74:77], v[154:157], v[224:227], v[74:77]
	s_setprio 0
	s_setprio 1
	v_mfma_f32_16x16x32_bf16 v[118:121], v[158:161], v[188:191], v[118:121]
	v_mfma_f32_16x16x32_bf16 v[114:117], v[174:177], v[188:191], v[114:117]
	v_mfma_f32_16x16x32_bf16 v[102:105], v[158:161], v[196:199], v[102:105]
	v_mfma_f32_16x16x32_bf16 v[98:101], v[174:177], v[196:199], v[98:101]
	v_mfma_f32_16x16x32_bf16 v[86:89], v[158:161], v[212:215], v[86:89]
	v_mfma_f32_16x16x32_bf16 v[82:85], v[174:177], v[212:215], v[82:85]
	v_mfma_f32_16x16x32_bf16 v[70:73], v[158:161], v[220:223], v[70:73]
	v_mfma_f32_16x16x32_bf16 v[66:69], v[174:177], v[220:223], v[66:69]
	v_mfma_f32_16x16x32_bf16 v[118:121], v[170:173], v[192:195], v[118:121]
	v_mfma_f32_16x16x32_bf16 v[114:117], v[184:187], v[192:195], v[114:117]
	v_mfma_f32_16x16x32_bf16 v[102:105], v[170:173], v[200:203], v[102:105]
	v_mfma_f32_16x16x32_bf16 v[98:101], v[184:187], v[200:203], v[98:101]
	v_mfma_f32_16x16x32_bf16 v[86:89], v[170:173], v[216:219], v[86:89]
	v_mfma_f32_16x16x32_bf16 v[82:85], v[184:187], v[216:219], v[82:85]
	v_mfma_f32_16x16x32_bf16 v[70:73], v[170:173], v[224:227], v[70:73]
	v_mfma_f32_16x16x32_bf16 v[66:69], v[184:187], v[224:227], v[66:69]
	s_setprio 0
	s_barrier
	s_add_i32 s3, s76, s4
	v_lshl_add_u64 v[162:163], s[72:73], 0, v[0:1]
	s_mov_b32 m0, s3
	s_nop 0
	global_load_lds_dwordx4 v[162:163], off
	s_add_i32 m0, s3, 0x2000
	s_add_u32 s30, s72, 0xb0000
	v_lshl_add_u64 v[164:165], s[72:73], 0, v[148:149]
	s_addc_u32 s31, s73, 0
	s_add_i32 s2, s2, s4
	global_load_lds_dwordx4 v[164:165], off
	v_lshl_add_u64 v[206:207], s[30:31], 0, v[0:1]
	s_mov_b32 m0, s2
	v_lshl_add_u64 v[228:229], s[74:75], 0, v[144:145]
	global_load_lds_dwordx4 v[206:207], off
	v_lshl_add_u64 v[206:207], s[30:31], 0, v[148:149]
	s_add_i32 m0, s2, 0x2000
	s_nop 0
	global_load_lds_dwordx4 v[206:207], off
	v_lshl_add_u64 v[206:207], s[74:75], 0, v[142:143]
	s_mov_b32 m0, s5
	s_nop 0
	global_load_lds_dwordx4 v[206:207], off
	s_mov_b32 m0, s6
	s_nop 0
	global_load_lds_dwordx4 v[228:229], off
	ds_read_b128 v[188:191], v181 offset:16384
	ds_read_b128 v[192:195], v181 offset:17408
	ds_read_b128 v[196:199], v181 offset:18432
	ds_read_b128 v[200:203], v181 offset:19456
	ds_read_b128 v[212:215], v181 offset:20480
	ds_read_b128 v[216:219], v181 offset:21504
	ds_read_b128 v[220:223], v181 offset:22528
	ds_read_b128 v[224:227], v181 offset:23552
	s_waitcnt vmcnt(8)
	s_waitcnt lgkmcnt(0)
	s_barrier
; #define PG8_STAGE(bufoff, gbase, voff) do { _Pragma("unroll") for (int _i = 0; _i < 2; ++_i) \
;         __builtin_amdgcn_global_load_lds((const unsigned*)((const char*)(gbase) + (voff)[_i]), (LAS unsigned*)(lds + (bufoff) + ldsw + _i * 8192), 16, 0, 0); } while (0)
; #define PG8_LDA(dst, b, h) do { _Pragma("unroll") for (int m = 0; m < 4; ++m) _Pragma("unroll") for (int k = 0; k < 2; ++k) dst[m][k] = *(const LAS bf16x8*)(lds + PG8_SA(b, h) + aoff + m * 2048 + k * 1024); } while (0)
; #define PG8_LDB(dst, b, h) do { _Pragma("unroll") for (int n = 0; n < 2; ++n) _Pragma("unroll") for (int k = 0; k < 2; ++k) dst[n][k] = *(const LAS bf16x8*)(lds + PG8_SB(b, h) + boff + n * 2048 + k * 1024); } while (0)
; #define PG8_MMA(ai, bj, At, Bt) do { __builtin_amdgcn_s_setprio(1); _Pragma("unroll") for (int m = 0; m < 4; ++m) _Pragma("unroll") for (int n = 0; n < 2; ++n) _Pragma("unroll") for (int k = 0; k < 2; ++k) \
;         acc[ai][bj][m][n] = __builtin_amdgcn_mfma_f32_16x16x32_bf16(Bt[n][k], At[m][k], acc[ai][bj][m][n], 0, 0, 0); __builtin_amdgcn_s_setprio(0); } while (0)
; #define PG8_WAIT_V(n) asm volatile("s_waitcnt vmcnt(" #n ")" ::: "memory")
; #define PG8_WAIT_L(n) asm volatile("s_waitcnt lgkmcnt(" #n ")" ::: "memory")
; #define PG8_BAR __builtin_amdgcn_s_barrier()
; #define PG8_SCHED __builtin_amdgcn_sched_barrier(0)
; template <class Epi>
; __device__ __forceinline__ void gemm_phase(LAS unsigned char* lds, const int tid, const Gemm g, const StaticOrder& S, const Epi& E) {
;     ...
;             PG8_WAIT_V(8); PG8_WAIT_L(0); PG8_BAR; PG8_MMA(1, 0, At, B0); PG8_MMA(1, 1, At, B1); PG8_BAR; PG8_SCHED;
;             PG8_LDB(B0, 1, 0); PG8_LDB(B1, 1, 1); PG8_SCHED; PG8_LDA(At, 1, 0); PG8_STAGE(PG8_SA(0, 1), a2 + hstepA, voffA);
;             PG8_WAIT_V(8); PG8_WAIT_L(0); PG8_BAR; PG8_MMA(0, 0, At, B0); PG8_MMA(0, 1, At, B1); PG8_BAR; PG8_SCHED;
	s_setprio 1
	s_waitcnt lgkmcnt(0)
	v_mfma_f32_16x16x32_bf16 v[62:65], v[130:133], v[188:191], v[62:65]
	v_mfma_f32_16x16x32_bf16 v[58:61], v[138:141], v[188:191], v[58:61]
	v_mfma_f32_16x16x32_bf16 v[46:49], v[130:133], v[196:199], v[46:49]
	v_mfma_f32_16x16x32_bf16 v[42:45], v[138:141], v[196:199], v[42:45]
	v_mfma_f32_16x16x32_bf16 v[30:33], v[130:133], v[212:215], v[30:33]
	v_mfma_f32_16x16x32_bf16 v[26:29], v[138:141], v[212:215], v[26:29]
	v_mfma_f32_16x16x32_bf16 v[14:17], v[130:133], v[220:223], v[14:17]
	v_mfma_f32_16x16x32_bf16 v[10:13], v[138:141], v[220:223], v[10:13]
	v_mfma_f32_16x16x32_bf16 v[62:65], v[134:137], v[192:195], v[62:65]
	v_mfma_f32_16x16x32_bf16 v[58:61], v[154:157], v[192:195], v[58:61]
	v_mfma_f32_16x16x32_bf16 v[46:49], v[134:137], v[200:203], v[46:49]
	v_mfma_f32_16x16x32_bf16 v[42:45], v[154:157], v[200:203], v[42:45]
	v_mfma_f32_16x16x32_bf16 v[30:33], v[134:137], v[216:219], v[30:33]
	v_mfma_f32_16x16x32_bf16 v[26:29], v[154:157], v[216:219], v[26:29]
	v_mfma_f32_16x16x32_bf16 v[14:17], v[134:137], v[224:227], v[14:17]
	v_mfma_f32_16x16x32_bf16 v[10:13], v[154:157], v[224:227], v[10:13]
	s_setprio 0
	s_setprio 1
	v_mfma_f32_16x16x32_bf16 v[54:57], v[158:161], v[188:191], v[54:57]
	v_mfma_f32_16x16x32_bf16 v[50:53], v[174:177], v[188:191], v[50:53]
	v_mfma_f32_16x16x32_bf16 v[38:41], v[158:161], v[196:199], v[38:41]
	v_mfma_f32_16x16x32_bf16 v[34:37], v[174:177], v[196:199], v[34:37]
	v_mfma_f32_16x16x32_bf16 v[22:25], v[158:161], v[212:215], v[22:25]
	v_mfma_f32_16x16x32_bf16 v[18:21], v[174:177], v[212:215], v[18:21]
	v_mfma_f32_16x16x32_bf16 v[6:9], v[158:161], v[220:223], v[6:9]
	v_mfma_f32_16x16x32_bf16 v[2:5], v[174:177], v[220:223], v[2:5]
	v_mfma_f32_16x16x32_bf16 v[54:57], v[170:173], v[192:195], v[54:57]
	v_mfma_f32_16x16x32_bf16 v[50:53], v[184:187], v[192:195], v[50:53]
	v_mfma_f32_16x16x32_bf16 v[38:41], v[170:173], v[200:203], v[38:41]
	v_mfma_f32_16x16x32_bf16 v[34:37], v[184:187], v[200:203], v[34:37]
	v_mfma_f32_16x16x32_bf16 v[22:25], v[170:173], v[216:219], v[22:25]
	v_mfma_f32_16x16x32_bf16 v[18:21], v[184:187], v[216:219], v[18:21]
	v_mfma_f32_16x16x32_bf16 v[6:9], v[170:173], v[224:227], v[6:9]
	v_mfma_f32_16x16x32_bf16 v[2:5], v[184:187], v[224:227], v[2:5]
	s_setprio 0
	s_barrier
	s_add_u32 s30, s74, 0x160000
	s_addc_u32 s31, s75, 0
	s_mov_b32 m0, s7
	v_lshl_add_u64 v[230:231], s[30:31], 0, v[142:143]
	global_load_lds_dwordx4 v[230:231], off
	v_lshl_add_u64 v[230:231], s[30:31], 0, v[144:145]
	s_mov_b32 m0, s77
	s_nop 0
	global_load_lds_dwordx4 v[230:231], off
	s_add_i32 s2, 0, 0x18000
	s_add_i32 s3, 0, 0x1c000
	v_add_u32_e32 v154, s2, v179
	v_add_u32_e32 v183, s3, v179
	ds_read_b128 v[130:133], v154
	ds_read_b128 v[134:137], v154 offset:1024
	ds_read_b128 v[138:141], v154 offset:2048
	ds_read_b128 v[154:157], v154 offset:3072
	ds_read_b128 v[158:161], v183
	ds_read_b128 v[170:173], v183 offset:1024
	ds_read_b128 v[174:177], v183 offset:2048
	ds_read_b128 v[184:187], v183 offset:3072
	ds_read_b128 v[188:191], v181 offset:32768
	ds_read_b128 v[192:195], v181 offset:33792
	ds_read_b128 v[196:199], v181 offset:34816
	ds_read_b128 v[200:203], v181 offset:35840
	ds_read_b128 v[212:215], v181 offset:36864
	ds_read_b128 v[216:219], v181 offset:37888
	ds_read_b128 v[220:223], v181 offset:38912
	ds_read_b128 v[224:227], v181 offset:39936
	s_waitcnt vmcnt(8)
	s_waitcnt lgkmcnt(0)
	s_barrier
	s_setprio 1
	s_waitcnt lgkmcnt(0)
	v_mfma_f32_16x16x32_bf16 v[126:129], v[130:133], v[188:191], v[126:129]
	v_mfma_f32_16x16x32_bf16 v[122:125], v[138:141], v[188:191], v[122:125]
	v_mfma_f32_16x16x32_bf16 v[110:113], v[130:133], v[196:199], v[110:113]
	v_mfma_f32_16x16x32_bf16 v[106:109], v[138:141], v[196:199], v[106:109]
	v_mfma_f32_16x16x32_bf16 v[94:97], v[130:133], v[212:215], v[94:97]
	v_mfma_f32_16x16x32_bf16 v[90:93], v[138:141], v[212:215], v[90:93]
	v_mfma_f32_16x16x32_bf16 v[78:81], v[130:133], v[220:223], v[78:81]
	v_mfma_f32_16x16x32_bf16 v[74:77], v[138:141], v[220:223], v[74:77]
	v_mfma_f32_16x16x32_bf16 v[126:129], v[134:137], v[192:195], v[126:129]
	v_mfma_f32_16x16x32_bf16 v[122:125], v[154:157], v[192:195], v[122:125]
	v_mfma_f32_16x16x32_bf16 v[110:113], v[134:137], v[200:203], v[110:113]
	v_mfma_f32_16x16x32_bf16 v[106:109], v[154:157], v[200:203], v[106:109]
	v_mfma_f32_16x16x32_bf16 v[94:97], v[134:137], v[216:219], v[94:97]
	v_mfma_f32_16x16x32_bf16 v[90:93], v[154:157], v[216:219], v[90:93]
	v_mfma_f32_16x16x32_bf16 v[78:81], v[134:137], v[224:227], v[78:81]
	v_mfma_f32_16x16x32_bf16 v[74:77], v[154:157], v[224:227], v[74:77]
	s_setprio 0
	s_setprio 1
	v_mfma_f32_16x16x32_bf16 v[118:121], v[158:161], v[188:191], v[118:121]
	v_mfma_f32_16x16x32_bf16 v[114:117], v[174:177], v[188:191], v[114:117]
	v_mfma_f32_16x16x32_bf16 v[102:105], v[158:161], v[196:199], v[102:105]
	v_mfma_f32_16x16x32_bf16 v[98:101], v[174:177], v[196:199], v[98:101]
	v_mfma_f32_16x16x32_bf16 v[86:89], v[158:161], v[212:215], v[86:89]
	v_mfma_f32_16x16x32_bf16 v[82:85], v[174:177], v[212:215], v[82:85]
	v_mfma_f32_16x16x32_bf16 v[70:73], v[158:161], v[220:223], v[70:73]
	v_mfma_f32_16x16x32_bf16 v[66:69], v[174:177], v[220:223], v[66:69]
	v_mfma_f32_16x16x32_bf16 v[118:121], v[170:173], v[192:195], v[118:121]
	v_mfma_f32_16x16x32_bf16 v[114:117], v[184:187], v[192:195], v[114:117]
	v_mfma_f32_16x16x32_bf16 v[102:105], v[170:173], v[200:203], v[102:105]
	v_mfma_f32_16x16x32_bf16 v[98:101], v[184:187], v[200:203], v[98:101]
	v_mfma_f32_16x16x32_bf16 v[86:89], v[170:173], v[216:219], v[86:89]
	v_mfma_f32_16x16x32_bf16 v[82:85], v[184:187], v[216:219], v[82:85]
	v_mfma_f32_16x16x32_bf16 v[70:73], v[170:173], v[224:227], v[70:73]
	v_mfma_f32_16x16x32_bf16 v[66:69], v[184:187], v[224:227], v[66:69]
	s_setprio 0
	s_barrier
; #define PG8_STAGE(bufoff, gbase, voff) do { _Pragma("unroll") for (int _i = 0; _i < 2; ++_i) \
;         __builtin_amdgcn_global_load_lds((const unsigned*)((const char*)(gbase) + (voff)[_i]), (LAS unsigned*)(lds + (bufoff) + ldsw + _i * 8192), 16, 0, 0); } while (0)
; #define PG8_LDA(dst, b, h) do { _Pragma("unroll") for (int m = 0; m < 4; ++m) _Pragma("unroll") for (int k = 0; k < 2; ++k) dst[m][k] = *(const LAS bf16x8*)(lds + PG8_SA(b, h) + aoff + m * 2048 + k * 1024); } while (0)
; #define PG8_MMA(ai, bj, At, Bt) do { __builtin_amdgcn_s_setprio(1); _Pragma("unroll") for (int m = 0; m < 4; ++m) _Pragma("unroll") for (int n = 0; n < 2; ++n) _Pragma("unroll") for (int k = 0; k < 2; ++k) \
;         acc[ai][bj][m][n] = __builtin_amdgcn_mfma_f32_16x16x32_bf16(Bt[n][k], At[m][k], acc[ai][bj][m][n], 0, 0, 0); __builtin_amdgcn_s_setprio(0); } while (0)
; #define PG8_WAIT_V(n) asm volatile("s_waitcnt vmcnt(" #n ")" ::: "memory")
; #define PG8_WAIT_L(n) asm volatile("s_waitcnt lgkmcnt(" #n ")" ::: "memory")
; #define PG8_BAR __builtin_amdgcn_s_barrier()
; #define PG8_SCHED __builtin_amdgcn_sched_barrier(0)
; template <class Epi>
; __device__ __forceinline__ void gemm_phase(LAS unsigned char* lds, const int tid, const Gemm g, const StaticOrder& S, const Epi& E) {
;     ...
;             PG8_LDA(At, 1, 1); PG8_STAGE(PG8_SB(1, 0), b3, voffB); PG8_STAGE(PG8_SB(1, 1), b3 + hstepB, voffB); PG8_STAGE(PG8_SA(1, 0), a3, voffA);
;             PG8_WAIT_V(8); PG8_WAIT_L(0); PG8_BAR; PG8_MMA(1, 0, At, B0); PG8_MMA(1, 1, At, B1); PG8_BAR; PG8_SCHED;
;         }
	s_add_i32 s2, s2, s4
	v_lshl_add_u64 v[162:163], v[162:163], 0, s[36:37]
	s_mov_b32 m0, s2
	s_nop 0
	global_load_lds_dwordx4 v[162:163], off
	s_add_i32 m0, s2, 0x2000
	s_add_u32 s30, s72, 0xb0080
	v_lshl_add_u64 v[162:163], v[164:165], 0, s[36:37]
	s_addc_u32 s31, s73, 0
	s_add_i32 s2, s3, s4
	global_load_lds_dwordx4 v[162:163], off
	v_lshl_add_u64 v[162:163], s[30:31], 0, v[0:1]
	s_mov_b32 m0, s2
	s_nop 0
	global_load_lds_dwordx4 v[162:163], off
	v_lshl_add_u64 v[162:163], s[30:31], 0, v[148:149]
	s_add_i32 m0, s2, 0x2000
	s_nop 0
	global_load_lds_dwordx4 v[162:163], off
	v_lshl_add_u64 v[162:163], v[206:207], 0, s[36:37]
	s_mov_b32 m0, s83
	s_nop 0
	global_load_lds_dwordx4 v[162:163], off
	v_lshl_add_u64 v[162:163], v[228:229], 0, s[36:37]
	s_mov_b32 m0, s88
	s_nop 0
	global_load_lds_dwordx4 v[162:163], off
	ds_read_b128 v[188:191], v181 offset:49152
	ds_read_b128 v[192:195], v181 offset:50176
	ds_read_b128 v[196:199], v181 offset:51200
	ds_read_b128 v[200:203], v181 offset:52224
	ds_read_b128 v[212:215], v181 offset:53248
	ds_read_b128 v[216:219], v181 offset:54272
	ds_read_b128 v[220:223], v181 offset:55296
	ds_read_b128 v[224:227], v181 offset:56320
	s_waitcnt vmcnt(8)
	s_waitcnt lgkmcnt(0)
	s_barrier
	s_setprio 1
	s_waitcnt lgkmcnt(0)
	v_mfma_f32_16x16x32_bf16 v[62:65], v[130:133], v[188:191], v[62:65]
	v_mfma_f32_16x16x32_bf16 v[58:61], v[138:141], v[188:191], v[58:61]
	v_mfma_f32_16x16x32_bf16 v[46:49], v[130:133], v[196:199], v[46:49]
	v_mfma_f32_16x16x32_bf16 v[42:45], v[138:141], v[196:199], v[42:45]
	v_mfma_f32_16x16x32_bf16 v[30:33], v[130:133], v[212:215], v[30:33]
	v_mfma_f32_16x16x32_bf16 v[26:29], v[138:141], v[212:215], v[26:29]
	v_mfma_f32_16x16x32_bf16 v[14:17], v[130:133], v[220:223], v[14:17]
	v_mfma_f32_16x16x32_bf16 v[10:13], v[138:141], v[220:223], v[10:13]
	v_mfma_f32_16x16x32_bf16 v[62:65], v[134:137], v[192:195], v[62:65]
	v_mfma_f32_16x16x32_bf16 v[58:61], v[154:157], v[192:195], v[58:61]
	v_mfma_f32_16x16x32_bf16 v[46:49], v[134:137], v[200:203], v[46:49]
	v_mfma_f32_16x16x32_bf16 v[42:45], v[154:157], v[200:203], v[42:45]
	v_mfma_f32_16x16x32_bf16 v[30:33], v[134:137], v[216:219], v[30:33]
	v_mfma_f32_16x16x32_bf16 v[26:29], v[154:157], v[216:219], v[26:29]
	v_mfma_f32_16x16x32_bf16 v[14:17], v[134:137], v[224:227], v[14:17]
	v_mfma_f32_16x16x32_bf16 v[10:13], v[154:157], v[224:227], v[10:13]
	s_setprio 0
	s_setprio 1
	v_mfma_f32_16x16x32_bf16 v[54:57], v[158:161], v[188:191], v[54:57]
	v_mfma_f32_16x16x32_bf16 v[50:53], v[174:177], v[188:191], v[50:53]
	v_mfma_f32_16x16x32_bf16 v[38:41], v[158:161], v[196:199], v[38:41]
	v_mfma_f32_16x16x32_bf16 v[34:37], v[174:177], v[196:199], v[34:37]
	v_mfma_f32_16x16x32_bf16 v[22:25], v[158:161], v[212:215], v[22:25]
	v_mfma_f32_16x16x32_bf16 v[18:21], v[174:177], v[212:215], v[18:21]
	v_mfma_f32_16x16x32_bf16 v[6:9], v[158:161], v[220:223], v[6:9]
	v_mfma_f32_16x16x32_bf16 v[2:5], v[174:177], v[220:223], v[2:5]
	v_mfma_f32_16x16x32_bf16 v[54:57], v[170:173], v[192:195], v[54:57]
	v_mfma_f32_16x16x32_bf16 v[50:53], v[184:187], v[192:195], v[50:53]
	v_mfma_f32_16x16x32_bf16 v[38:41], v[170:173], v[200:203], v[38:41]
	v_mfma_f32_16x16x32_bf16 v[34:37], v[184:187], v[200:203], v[34:37]
	v_mfma_f32_16x16x32_bf16 v[22:25], v[170:173], v[216:219], v[22:25]
	v_mfma_f32_16x16x32_bf16 v[18:21], v[184:187], v[216:219], v[18:21]
	v_mfma_f32_16x16x32_bf16 v[6:9], v[170:173], v[224:227], v[6:9]
	v_mfma_f32_16x16x32_bf16 v[2:5], v[184:187], v[224:227], v[2:5]
	s_setprio 0
	s_barrier
	s_add_i32 vcc_hi, vcc_hi, 2
	s_add_u32 s28, s28, 0x100
	s_addc_u32 vcc_lo, vcc_lo, 0
	s_cmp_gt_u32 vcc_hi, 41
	s_mov_b64 s[30:31], s[70:71]
	s_cbranch_scc0 .LBB0_2193
	s_and_b64 vcc, exec, s[26:27]
	s_cbranch_vccz .LBB0_2196
	s_barrier

; #define PG8_STAGE(bufoff, gbase, voff) do { _Pragma("unroll") for (int _i = 0; _i < 2; ++_i) \
;         __builtin_amdgcn_global_load_lds((const unsigned*)((const char*)(gbase) + (voff)[_i]), (LAS unsigned*)(lds + (bufoff) + ldsw + _i * 8192), 16, 0, 0); } while (0)
; #define PG8_LDA(dst, b, h) do { _Pragma("unroll") for (int m = 0; m < 4; ++m) _Pragma("unroll") for (int k = 0; k < 2; ++k) dst[m][k] = *(const LAS bf16x8*)(lds + PG8_SA(b, h) + aoff + m * 2048 + k * 1024); } while (0)
; #define PG8_LDB(dst, b, h) do { _Pragma("unroll") for (int n = 0; n < 2; ++n) _Pragma("unroll") for (int k = 0; k < 2; ++k) dst[n][k] = *(const LAS bf16x8*)(lds + PG8_SB(b, h) + boff + n * 2048 + k * 1024); } while (0)
; #define PG8_MMA(ai, bj, At, Bt) do { __builtin_amdgcn_s_setprio(1); _Pragma("unroll") for (int m = 0; m < 4; ++m) _Pragma("unroll") for (int n = 0; n < 2; ++n) _Pragma("unroll") for (int k = 0; k < 2; ++k) \
;         acc[ai][bj][m][n] = __builtin_amdgcn_mfma_f32_16x16x32_bf16(Bt[n][k], At[m][k], acc[ai][bj][m][n], 0, 0, 0); __builtin_amdgcn_s_setprio(0); } while (0)
; #define PG8_WAIT_V(n) asm volatile("s_waitcnt vmcnt(" #n ")" ::: "memory")
; #define PG8_WAIT_L(n) asm volatile("s_waitcnt lgkmcnt(" #n ")" ::: "memory")
; #define PG8_BAR __builtin_amdgcn_s_barrier()
; #define PG8_SCHED __builtin_amdgcn_sched_barrier(0)
; template <class Epi>
; __device__ __forceinline__ void gemm_phase(LAS unsigned char* lds, const int tid, const Gemm g, const StaticOrder& S, const Epi& E) {
;     ...
;             const bool last = (t == nt - 2);
;             const char* a1 = cA + (size_t)(t + 1) * kstep;
;             const char* a2 = last ? nA : cA + (size_t)(t + 2) * kstep; const char* b2 = last ? nB : cB + (size_t)(t + 2) * kstep;
;             const char* a3 = a2 + kstep; const char* b3 = b2 + kstep;
;             PG8_LDB(B0, 0, 0); PG8_LDB(B1, 0, 1); PG8_SCHED; PG8_LDA(At, 0, 0); PG8_STAGE(PG8_SA(1, 1), a1 + hstepA, voffA);
;             PG8_WAIT_V(8); PG8_WAIT_L(0); PG8_BAR; PG8_MMA(0, 0, At, B0); PG8_MMA(0, 1, At, B1); PG8_BAR; PG8_SCHED;
;             PG8_LDA(At, 0, 1); PG8_STAGE(PG8_SB(0, 0), b2, voffB); PG8_STAGE(PG8_SB(0, 1), b2 + hstepB, voffB); PG8_STAGE(PG8_SA(0, 0), a2, voffA);
.LBB0_2303:
	v_lshl_add_u64 v[162:163], s[66:67], 0, v[154:155]
	s_add_i32 m0, s5, 0xc000
	s_nop 0
	global_load_lds_dwordx4 v[162:163], off
	v_lshl_add_u64 v[162:163], s[66:67], 0, v[156:157]
	s_add_i32 m0, s5, 0xe000
	s_nop 0
	global_load_lds_dwordx4 v[162:163], off
	s_add_u32 s68, s66, 0x100
	s_addc_u32 s69, s67, 0
	s_add_i32 s76, 0, 0x10000
	s_cmp_eq_u32 s93, 40
	s_cselect_b32 s73, s1, s69
	s_cselect_b32 s72, s0, s68
	s_cselect_b32 s71, s31, s28
	s_cselect_b32 s70, s30, s11
	s_add_i32 vcc_lo, 0, 0x14000
	v_add_u32_e32 v70, s76, v212
	v_add_u32_e32 v162, vcc_lo, v212
	ds_read_b128 v[42:45], v70
	ds_read_b128 v[46:49], v70 offset:1024
	ds_read_b128 v[66:69], v70 offset:2048
	ds_read_b128 v[70:73], v70 offset:3072
	ds_read_b128 v[158:161], v162
	ds_read_b128 v[170:173], v162 offset:1024
	ds_read_b128 v[174:177], v162 offset:2048
	ds_read_b128 v[178:181], v162 offset:3072
	ds_read_b128 v[182:185], v214
	ds_read_b128 v[186:189], v214 offset:1024
	ds_read_b128 v[190:193], v214 offset:2048
	ds_read_b128 v[194:197], v214 offset:3072
	ds_read_b128 v[198:201], v214 offset:4096
	ds_read_b128 v[216:219], v214 offset:5120
	ds_read_b128 v[220:223], v214 offset:6144
	ds_read_b128 v[224:227], v214 offset:7168
	s_waitcnt vmcnt(8)
	s_waitcnt lgkmcnt(0)
	s_barrier
	s_setprio 1
	s_waitcnt lgkmcnt(0)
	v_mfma_f32_16x16x32_bf16 v[142:145], v[42:45], v[182:185], v[142:145]
	v_mfma_f32_16x16x32_bf16 v[138:141], v[66:69], v[182:185], v[138:141]
	v_mfma_f32_16x16x32_bf16 v[126:129], v[42:45], v[190:193], v[126:129]
	v_mfma_f32_16x16x32_bf16 v[122:125], v[66:69], v[190:193], v[122:125]
	v_mfma_f32_16x16x32_bf16 v[110:113], v[42:45], v[198:201], v[110:113]
	v_mfma_f32_16x16x32_bf16 v[106:109], v[66:69], v[198:201], v[106:109]
	v_mfma_f32_16x16x32_bf16 v[94:97], v[42:45], v[220:223], v[94:97]
	v_mfma_f32_16x16x32_bf16 v[90:93], v[66:69], v[220:223], v[90:93]
	v_mfma_f32_16x16x32_bf16 v[142:145], v[46:49], v[186:189], v[142:145]
	v_mfma_f32_16x16x32_bf16 v[138:141], v[70:73], v[186:189], v[138:141]
	v_mfma_f32_16x16x32_bf16 v[126:129], v[46:49], v[194:197], v[126:129]
	v_mfma_f32_16x16x32_bf16 v[122:125], v[70:73], v[194:197], v[122:125]
	v_mfma_f32_16x16x32_bf16 v[110:113], v[46:49], v[216:219], v[110:113]
	v_mfma_f32_16x16x32_bf16 v[106:109], v[70:73], v[216:219], v[106:109]
	v_mfma_f32_16x16x32_bf16 v[94:97], v[46:49], v[224:227], v[94:97]
	v_mfma_f32_16x16x32_bf16 v[90:93], v[70:73], v[224:227], v[90:93]
	s_setprio 0
	s_setprio 1
	v_mfma_f32_16x16x32_bf16 v[134:137], v[158:161], v[182:185], v[134:137]
	v_mfma_f32_16x16x32_bf16 v[130:133], v[174:177], v[182:185], v[130:133]
	v_mfma_f32_16x16x32_bf16 v[118:121], v[158:161], v[190:193], v[118:121]
	v_mfma_f32_16x16x32_bf16 v[114:117], v[174:177], v[190:193], v[114:117]
	v_mfma_f32_16x16x32_bf16 v[102:105], v[158:161], v[198:201], v[102:105]
	v_mfma_f32_16x16x32_bf16 v[98:101], v[174:177], v[198:201], v[98:101]
	v_mfma_f32_16x16x32_bf16 v[86:89], v[158:161], v[220:223], v[86:89]
	v_mfma_f32_16x16x32_bf16 v[82:85], v[174:177], v[220:223], v[82:85]
	v_mfma_f32_16x16x32_bf16 v[134:137], v[170:173], v[186:189], v[134:137]
	v_mfma_f32_16x16x32_bf16 v[130:133], v[178:181], v[186:189], v[130:133]
	v_mfma_f32_16x16x32_bf16 v[118:121], v[170:173], v[194:197], v[118:121]
	v_mfma_f32_16x16x32_bf16 v[114:117], v[178:181], v[194:197], v[114:117]
	v_mfma_f32_16x16x32_bf16 v[102:105], v[170:173], v[216:219], v[102:105]
	v_mfma_f32_16x16x32_bf16 v[98:101], v[178:181], v[216:219], v[98:101]
	v_mfma_f32_16x16x32_bf16 v[86:89], v[170:173], v[224:227], v[86:89]
	v_mfma_f32_16x16x32_bf16 v[82:85], v[178:181], v[224:227], v[82:85]
	s_setprio 0
	s_barrier
	s_add_i32 s66, s76, s4
	v_lshl_add_u64 v[162:163], s[70:71], 0, v[0:1]
	s_mov_b32 m0, s66
	s_nop 0
	global_load_lds_dwordx4 v[162:163], off
	s_add_i32 m0, s66, 0x2000
	s_add_u32 s66, s70, 0xb0000
	v_lshl_add_u64 v[164:165], s[70:71], 0, v[152:153]
	s_addc_u32 s67, s71, 0
	s_add_i32 s76, vcc_lo, s4
	global_load_lds_dwordx4 v[164:165], off
	v_lshl_add_u64 v[202:203], s[66:67], 0, v[0:1]
	s_mov_b32 m0, s76
	v_lshl_add_u64 v[206:207], s[72:73], 0, v[150:151]
	global_load_lds_dwordx4 v[202:203], off
	v_lshl_add_u64 v[202:203], s[66:67], 0, v[152:153]
	s_add_i32 m0, s76, 0x2000
	s_nop 0
	global_load_lds_dwordx4 v[202:203], off
	v_lshl_add_u64 v[202:203], s[72:73], 0, v[148:149]
	s_mov_b32 m0, s5
	s_nop 0
	global_load_lds_dwordx4 v[202:203], off
	s_mov_b32 m0, s6
	s_nop 0
	global_load_lds_dwordx4 v[206:207], off
	ds_read_b128 v[182:185], v214 offset:16384
	ds_read_b128 v[186:189], v214 offset:17408
	ds_read_b128 v[190:193], v214 offset:18432
	ds_read_b128 v[194:197], v214 offset:19456
	ds_read_b128 v[198:201], v214 offset:20480
	ds_read_b128 v[216:219], v214 offset:21504
	ds_read_b128 v[220:223], v214 offset:22528
	ds_read_b128 v[224:227], v214 offset:23552
	s_waitcnt vmcnt(8)
	s_waitcnt lgkmcnt(0)
	s_barrier
; #define PG8_STAGE(bufoff, gbase, voff) do { _Pragma("unroll") for (int _i = 0; _i < 2; ++_i) \
;         __builtin_amdgcn_global_load_lds((const unsigned*)((const char*)(gbase) + (voff)[_i]), (LAS unsigned*)(lds + (bufoff) + ldsw + _i * 8192), 16, 0, 0); } while (0)
; #define PG8_LDA(dst, b, h) do { _Pragma("unroll") for (int m = 0; m < 4; ++m) _Pragma("unroll") for (int k = 0; k < 2; ++k) dst[m][k] = *(const LAS bf16x8*)(lds + PG8_SA(b, h) + aoff + m * 2048 + k * 1024); } while (0)
; #define PG8_LDB(dst, b, h) do { _Pragma("unroll") for (int n = 0; n < 2; ++n) _Pragma("unroll") for (int k = 0; k < 2; ++k) dst[n][k] = *(const LAS bf16x8*)(lds + PG8_SB(b, h) + boff + n * 2048 + k * 1024); } while (0)
; #define PG8_MMA(ai, bj, At, Bt) do { __builtin_amdgcn_s_setprio(1); _Pragma("unroll") for (int m = 0; m < 4; ++m) _Pragma("unroll") for (int n = 0; n < 2; ++n) _Pragma("unroll") for (int k = 0; k < 2; ++k) \
;         acc[ai][bj][m][n] = __builtin_amdgcn_mfma_f32_16x16x32_bf16(Bt[n][k], At[m][k], acc[ai][bj][m][n], 0, 0, 0); __builtin_amdgcn_s_setprio(0); } while (0)
; #define PG8_WAIT_V(n) asm volatile("s_waitcnt vmcnt(" #n ")" ::: "memory")
; #define PG8_WAIT_L(n) asm volatile("s_waitcnt lgkmcnt(" #n ")" ::: "memory")
; #define PG8_BAR __builtin_amdgcn_s_barrier()
; #define PG8_SCHED __builtin_amdgcn_sched_barrier(0)
; template <class Epi>
; __device__ __forceinline__ void gemm_phase(LAS unsigned char* lds, const int tid, const Gemm g, const StaticOrder& S, const Epi& E) {
;     ...
;             PG8_WAIT_V(8); PG8_WAIT_L(0); PG8_BAR; PG8_MMA(1, 0, At, B0); PG8_MMA(1, 1, At, B1); PG8_BAR; PG8_SCHED;
;             PG8_LDB(B0, 1, 0); PG8_LDB(B1, 1, 1); PG8_SCHED; PG8_LDA(At, 1, 0); PG8_STAGE(PG8_SA(0, 1), a2 + hstepA, voffA);
;             PG8_WAIT_V(8); PG8_WAIT_L(0); PG8_BAR; PG8_MMA(0, 0, At, B0); PG8_MMA(0, 1, At, B1); PG8_BAR; PG8_SCHED;
	s_setprio 1
	s_waitcnt lgkmcnt(0)
	v_mfma_f32_16x16x32_bf16 v[78:81], v[42:45], v[182:185], v[78:81]
	v_mfma_f32_16x16x32_bf16 v[74:77], v[66:69], v[182:185], v[74:77]
	v_mfma_f32_16x16x32_bf16 v[54:57], v[42:45], v[190:193], v[54:57]
	v_mfma_f32_16x16x32_bf16 v[50:53], v[66:69], v[190:193], v[50:53]
	v_mfma_f32_16x16x32_bf16 v[30:33], v[42:45], v[198:201], v[30:33]
	v_mfma_f32_16x16x32_bf16 v[26:29], v[66:69], v[198:201], v[26:29]
	v_mfma_f32_16x16x32_bf16 v[14:17], v[42:45], v[220:223], v[14:17]
	v_mfma_f32_16x16x32_bf16 v[10:13], v[66:69], v[220:223], v[10:13]
	v_mfma_f32_16x16x32_bf16 v[78:81], v[46:49], v[186:189], v[78:81]
	v_mfma_f32_16x16x32_bf16 v[74:77], v[70:73], v[186:189], v[74:77]
	v_mfma_f32_16x16x32_bf16 v[54:57], v[46:49], v[194:197], v[54:57]
	v_mfma_f32_16x16x32_bf16 v[50:53], v[70:73], v[194:197], v[50:53]
	v_mfma_f32_16x16x32_bf16 v[30:33], v[46:49], v[216:219], v[30:33]
	v_mfma_f32_16x16x32_bf16 v[26:29], v[70:73], v[216:219], v[26:29]
	v_mfma_f32_16x16x32_bf16 v[14:17], v[46:49], v[224:227], v[14:17]
	v_mfma_f32_16x16x32_bf16 v[10:13], v[70:73], v[224:227], v[10:13]
	s_setprio 0
	s_setprio 1
	v_mfma_f32_16x16x32_bf16 v[38:41], v[158:161], v[190:193], v[38:41]
	v_mfma_f32_16x16x32_bf16 v[34:37], v[174:177], v[190:193], v[34:37]
	v_mfma_f32_16x16x32_bf16 v[22:25], v[158:161], v[198:201], v[22:25]
	v_mfma_f32_16x16x32_bf16 v[18:21], v[174:177], v[198:201], v[18:21]
	v_mfma_f32_16x16x32_bf16 v[6:9], v[158:161], v[220:223], v[6:9]
	v_mfma_f32_16x16x32_bf16 v[2:5], v[174:177], v[220:223], v[2:5]
	v_mfma_f32_16x16x32_bf16 v[42:45], v[158:161], v[182:185], v[62:65]
	v_mfma_f32_16x16x32_bf16 v[46:49], v[174:177], v[182:185], v[58:61]
	v_mfma_f32_16x16x32_bf16 v[38:41], v[170:173], v[194:197], v[38:41]
	v_mfma_f32_16x16x32_bf16 v[34:37], v[178:181], v[194:197], v[34:37]
	v_mfma_f32_16x16x32_bf16 v[22:25], v[170:173], v[216:219], v[22:25]
	v_mfma_f32_16x16x32_bf16 v[18:21], v[178:181], v[216:219], v[18:21]
	v_mfma_f32_16x16x32_bf16 v[6:9], v[170:173], v[224:227], v[6:9]
	v_mfma_f32_16x16x32_bf16 v[2:5], v[178:181], v[224:227], v[2:5]
	v_mfma_f32_16x16x32_bf16 v[42:45], v[170:173], v[186:189], v[42:45]
	v_mfma_f32_16x16x32_bf16 v[46:49], v[178:181], v[186:189], v[46:49]
	s_setprio 0
	s_barrier
	s_add_u32 s66, s72, 0x160000
	s_addc_u32 s67, s73, 0
	s_mov_b32 m0, s7
	v_lshl_add_u64 v[228:229], s[66:67], 0, v[148:149]
	global_load_lds_dwordx4 v[228:229], off
	v_lshl_add_u64 v[228:229], s[66:67], 0, v[150:151]
	s_mov_b32 m0, s74
	s_nop 0
	global_load_lds_dwordx4 v[228:229], off
	s_add_i32 s76, 0, 0x18000
	s_add_i32 vcc_lo, 0, 0x1c000
	v_add_u32_e32 v70, s76, v212
	v_add_u32_e32 v178, vcc_lo, v212
	ds_read_b128 v[58:61], v70
	ds_read_b128 v[62:65], v70 offset:1024
	ds_read_b128 v[66:69], v70 offset:2048
	ds_read_b128 v[70:73], v70 offset:3072
	ds_read_b128 v[158:161], v178
	ds_read_b128 v[170:173], v178 offset:1024
	ds_read_b128 v[174:177], v178 offset:2048
	ds_read_b128 v[178:181], v178 offset:3072
	ds_read_b128 v[182:185], v214 offset:32768
	ds_read_b128 v[186:189], v214 offset:33792
	ds_read_b128 v[190:193], v214 offset:34816
	ds_read_b128 v[194:197], v214 offset:35840
	ds_read_b128 v[198:201], v214 offset:36864
	ds_read_b128 v[216:219], v214 offset:37888
	ds_read_b128 v[220:223], v214 offset:38912
	ds_read_b128 v[224:227], v214 offset:39936
	s_waitcnt vmcnt(8)
	s_waitcnt lgkmcnt(0)
	s_barrier
	s_setprio 1
	s_waitcnt lgkmcnt(0)
	v_mfma_f32_16x16x32_bf16 v[142:145], v[58:61], v[182:185], v[142:145]
	v_mfma_f32_16x16x32_bf16 v[138:141], v[66:69], v[182:185], v[138:141]
	v_mfma_f32_16x16x32_bf16 v[126:129], v[58:61], v[190:193], v[126:129]
	v_mfma_f32_16x16x32_bf16 v[122:125], v[66:69], v[190:193], v[122:125]
	v_mfma_f32_16x16x32_bf16 v[110:113], v[58:61], v[198:201], v[110:113]
	v_mfma_f32_16x16x32_bf16 v[106:109], v[66:69], v[198:201], v[106:109]
	v_mfma_f32_16x16x32_bf16 v[94:97], v[58:61], v[220:223], v[94:97]
	v_mfma_f32_16x16x32_bf16 v[90:93], v[66:69], v[220:223], v[90:93]
	v_mfma_f32_16x16x32_bf16 v[142:145], v[62:65], v[186:189], v[142:145]
	v_mfma_f32_16x16x32_bf16 v[138:141], v[70:73], v[186:189], v[138:141]
	v_mfma_f32_16x16x32_bf16 v[126:129], v[62:65], v[194:197], v[126:129]
	v_mfma_f32_16x16x32_bf16 v[122:125], v[70:73], v[194:197], v[122:125]
	v_mfma_f32_16x16x32_bf16 v[110:113], v[62:65], v[216:219], v[110:113]
	v_mfma_f32_16x16x32_bf16 v[106:109], v[70:73], v[216:219], v[106:109]
	v_mfma_f32_16x16x32_bf16 v[94:97], v[62:65], v[224:227], v[94:97]
	v_mfma_f32_16x16x32_bf16 v[90:93], v[70:73], v[224:227], v[90:93]
	s_setprio 0
	s_setprio 1
	v_mfma_f32_16x16x32_bf16 v[134:137], v[158:161], v[182:185], v[134:137]
	v_mfma_f32_16x16x32_bf16 v[130:133], v[174:177], v[182:185], v[130:133]
	v_mfma_f32_16x16x32_bf16 v[118:121], v[158:161], v[190:193], v[118:121]
	v_mfma_f32_16x16x32_bf16 v[114:117], v[174:177], v[190:193], v[114:117]
	v_mfma_f32_16x16x32_bf16 v[102:105], v[158:161], v[198:201], v[102:105]
	v_mfma_f32_16x16x32_bf16 v[98:101], v[174:177], v[198:201], v[98:101]
	v_mfma_f32_16x16x32_bf16 v[86:89], v[158:161], v[220:223], v[86:89]
	v_mfma_f32_16x16x32_bf16 v[82:85], v[174:177], v[220:223], v[82:85]
	v_mfma_f32_16x16x32_bf16 v[134:137], v[170:173], v[186:189], v[134:137]
	v_mfma_f32_16x16x32_bf16 v[130:133], v[178:181], v[186:189], v[130:133]
	v_mfma_f32_16x16x32_bf16 v[118:121], v[170:173], v[194:197], v[118:121]
	v_mfma_f32_16x16x32_bf16 v[114:117], v[178:181], v[194:197], v[114:117]
	v_mfma_f32_16x16x32_bf16 v[102:105], v[170:173], v[216:219], v[102:105]
	v_mfma_f32_16x16x32_bf16 v[98:101], v[178:181], v[216:219], v[98:101]
	v_mfma_f32_16x16x32_bf16 v[86:89], v[170:173], v[224:227], v[86:89]
	v_mfma_f32_16x16x32_bf16 v[82:85], v[178:181], v[224:227], v[82:85]
	s_setprio 0
	s_barrier
; #define PG8_STAGE(bufoff, gbase, voff) do { _Pragma("unroll") for (int _i = 0; _i < 2; ++_i) \
;         __builtin_amdgcn_global_load_lds((const unsigned*)((const char*)(gbase) + (voff)[_i]), (LAS unsigned*)(lds + (bufoff) + ldsw + _i * 8192), 16, 0, 0); } while (0)
; #define PG8_LDA(dst, b, h) do { _Pragma("unroll") for (int m = 0; m < 4; ++m) _Pragma("unroll") for (int k = 0; k < 2; ++k) dst[m][k] = *(const LAS bf16x8*)(lds + PG8_SA(b, h) + aoff + m * 2048 + k * 1024); } while (0)
; #define PG8_MMA(ai, bj, At, Bt) do { __builtin_amdgcn_s_setprio(1); _Pragma("unroll") for (int m = 0; m < 4; ++m) _Pragma("unroll") for (int n = 0; n < 2; ++n) _Pragma("unroll") for (int k = 0; k < 2; ++k) \
;         acc[ai][bj][m][n] = __builtin_amdgcn_mfma_f32_16x16x32_bf16(Bt[n][k], At[m][k], acc[ai][bj][m][n], 0, 0, 0); __builtin_amdgcn_s_setprio(0); } while (0)
; #define PG8_WAIT_V(n) asm volatile("s_waitcnt vmcnt(" #n ")" ::: "memory")
; #define PG8_WAIT_L(n) asm volatile("s_waitcnt lgkmcnt(" #n ")" ::: "memory")
; #define PG8_BAR __builtin_amdgcn_s_barrier()
; #define PG8_SCHED __builtin_amdgcn_sched_barrier(0)
; template <class Epi>
; __device__ __forceinline__ void gemm_phase(LAS unsigned char* lds, const int tid, const Gemm g, const StaticOrder& S, const Epi& E) {
;     ...
;             PG8_LDA(At, 1, 1); PG8_STAGE(PG8_SB(1, 0), b3, voffB); PG8_STAGE(PG8_SB(1, 1), b3 + hstepB, voffB); PG8_STAGE(PG8_SA(1, 0), a3, voffA);
;             PG8_WAIT_V(8); PG8_WAIT_L(0); PG8_BAR; PG8_MMA(1, 0, At, B0); PG8_MMA(1, 1, At, B1); PG8_BAR; PG8_SCHED;
;         }
;         if (wr == 0) PG8_BAR;
	s_add_i32 s66, s76, s4
	v_lshl_add_u64 v[162:163], v[162:163], 0, s[36:37]
	s_mov_b32 m0, s66
	s_nop 0
	global_load_lds_dwordx4 v[162:163], off
	s_add_i32 m0, s66, 0x2000
	s_add_u32 s66, s70, 0xb0080
	v_lshl_add_u64 v[162:163], v[164:165], 0, s[36:37]
	s_addc_u32 s67, s71, 0
	s_add_i32 s70, vcc_lo, s4
	global_load_lds_dwordx4 v[162:163], off
	v_lshl_add_u64 v[162:163], s[66:67], 0, v[0:1]
	s_mov_b32 m0, s70
	s_nop 0
	global_load_lds_dwordx4 v[162:163], off
	v_lshl_add_u64 v[162:163], s[66:67], 0, v[152:153]
	s_add_i32 m0, s70, 0x2000
	s_nop 0
	global_load_lds_dwordx4 v[162:163], off
	v_lshl_add_u64 v[162:163], v[202:203], 0, s[36:37]
	s_mov_b32 m0, s77
	s_nop 0
	global_load_lds_dwordx4 v[162:163], off
	v_lshl_add_u64 v[162:163], v[206:207], 0, s[36:37]
	s_mov_b32 m0, s79
	s_nop 0
	global_load_lds_dwordx4 v[162:163], off
	ds_read_b128 v[182:185], v214 offset:49152
	ds_read_b128 v[186:189], v214 offset:50176
	ds_read_b128 v[190:193], v214 offset:51200
	ds_read_b128 v[194:197], v214 offset:52224
	ds_read_b128 v[198:201], v214 offset:53248
	ds_read_b128 v[216:219], v214 offset:54272
	ds_read_b128 v[220:223], v214 offset:55296
	ds_read_b128 v[224:227], v214 offset:56320
	s_waitcnt vmcnt(8)
	s_waitcnt lgkmcnt(0)
	s_barrier
	s_setprio 1
	s_waitcnt lgkmcnt(0)
	v_mfma_f32_16x16x32_bf16 v[78:81], v[58:61], v[182:185], v[78:81]
	v_mfma_f32_16x16x32_bf16 v[74:77], v[66:69], v[182:185], v[74:77]
	v_mfma_f32_16x16x32_bf16 v[54:57], v[58:61], v[190:193], v[54:57]
	v_mfma_f32_16x16x32_bf16 v[50:53], v[66:69], v[190:193], v[50:53]
	v_mfma_f32_16x16x32_bf16 v[30:33], v[58:61], v[198:201], v[30:33]
	v_mfma_f32_16x16x32_bf16 v[26:29], v[66:69], v[198:201], v[26:29]
	v_mfma_f32_16x16x32_bf16 v[14:17], v[58:61], v[220:223], v[14:17]
	v_mfma_f32_16x16x32_bf16 v[10:13], v[66:69], v[220:223], v[10:13]
	v_mfma_f32_16x16x32_bf16 v[78:81], v[62:65], v[186:189], v[78:81]
	v_mfma_f32_16x16x32_bf16 v[74:77], v[70:73], v[186:189], v[74:77]
	v_mfma_f32_16x16x32_bf16 v[54:57], v[62:65], v[194:197], v[54:57]
	v_mfma_f32_16x16x32_bf16 v[50:53], v[70:73], v[194:197], v[50:53]
	v_mfma_f32_16x16x32_bf16 v[30:33], v[62:65], v[216:219], v[30:33]
	v_mfma_f32_16x16x32_bf16 v[26:29], v[70:73], v[216:219], v[26:29]
	v_mfma_f32_16x16x32_bf16 v[14:17], v[62:65], v[224:227], v[14:17]
	v_mfma_f32_16x16x32_bf16 v[10:13], v[70:73], v[224:227], v[10:13]
	s_setprio 0
	s_setprio 1
	v_mfma_f32_16x16x32_bf16 v[42:45], v[158:161], v[182:185], v[42:45]
	v_mfma_f32_16x16x32_bf16 v[62:65], v[170:173], v[186:189], v[42:45]
	v_mfma_f32_16x16x32_bf16 v[42:45], v[174:177], v[182:185], v[46:49]
	v_mfma_f32_16x16x32_bf16 v[38:41], v[158:161], v[190:193], v[38:41]
	v_mfma_f32_16x16x32_bf16 v[34:37], v[174:177], v[190:193], v[34:37]
	v_mfma_f32_16x16x32_bf16 v[22:25], v[158:161], v[198:201], v[22:25]
	v_mfma_f32_16x16x32_bf16 v[18:21], v[174:177], v[198:201], v[18:21]
	v_mfma_f32_16x16x32_bf16 v[6:9], v[158:161], v[220:223], v[6:9]
	v_mfma_f32_16x16x32_bf16 v[2:5], v[174:177], v[220:223], v[2:5]
	v_mfma_f32_16x16x32_bf16 v[58:61], v[178:181], v[186:189], v[42:45]
	v_mfma_f32_16x16x32_bf16 v[38:41], v[170:173], v[194:197], v[38:41]
	v_mfma_f32_16x16x32_bf16 v[34:37], v[178:181], v[194:197], v[34:37]
	v_mfma_f32_16x16x32_bf16 v[22:25], v[170:173], v[216:219], v[22:25]
	v_mfma_f32_16x16x32_bf16 v[18:21], v[178:181], v[216:219], v[18:21]
	v_mfma_f32_16x16x32_bf16 v[6:9], v[170:173], v[224:227], v[6:9]
	v_mfma_f32_16x16x32_bf16 v[2:5], v[178:181], v[224:227], v[2:5]
	s_setprio 0
	s_barrier
	s_add_i32 s93, s93, 2
	s_add_u32 s11, s11, 0x100
	s_addc_u32 s28, s28, 0
	s_cmp_gt_u32 s93, 41
	s_mov_b64 s[66:67], s[68:69]
	s_cbranch_scc0 .LBB0_2303
	s_and_b64 vcc, exec, s[26:27]
	s_cbranch_vccz .LBB0_2306
	s_barrier

; #define PG8_STAGE(bufoff, gbase, voff) do { _Pragma("unroll") for (int _i = 0; _i < 2; ++_i) \
;         __builtin_amdgcn_global_load_lds((const unsigned*)((const char*)(gbase) + (voff)[_i]), (LAS unsigned*)(lds + (bufoff) + ldsw + _i * 8192), 16, 0, 0); } while (0)
; #define PG8_LDA(dst, b, h) do { _Pragma("unroll") for (int m = 0; m < 4; ++m) _Pragma("unroll") for (int k = 0; k < 2; ++k) dst[m][k] = *(const LAS bf16x8*)(lds + PG8_SA(b, h) + aoff + m * 2048 + k * 1024); } while (0)
; #define PG8_LDB(dst, b, h) do { _Pragma("unroll") for (int n = 0; n < 2; ++n) _Pragma("unroll") for (int k = 0; k < 2; ++k) dst[n][k] = *(const LAS bf16x8*)(lds + PG8_SB(b, h) + boff + n * 2048 + k * 1024); } while (0)
; #define PG8_MMA(ai, bj, At, Bt) do { __builtin_amdgcn_s_setprio(1); _Pragma("unroll") for (int m = 0; m < 4; ++m) _Pragma("unroll") for (int n = 0; n < 2; ++n) _Pragma("unroll") for (int k = 0; k < 2; ++k) \
;         acc[ai][bj][m][n] = __builtin_amdgcn_mfma_f32_16x16x32_bf16(Bt[n][k], At[m][k], acc[ai][bj][m][n], 0, 0, 0); __builtin_amdgcn_s_setprio(0); } while (0)
; #define PG8_WAIT_V(n) asm volatile("s_waitcnt vmcnt(" #n ")" ::: "memory")
; #define PG8_WAIT_L(n) asm volatile("s_waitcnt lgkmcnt(" #n ")" ::: "memory")
; #define PG8_BAR __builtin_amdgcn_s_barrier()
; #define PG8_SCHED __builtin_amdgcn_sched_barrier(0)
; template <class Epi>
; __device__ __forceinline__ void gemm_phase(LAS unsigned char* lds, const int tid, const Gemm g, const StaticOrder& S, const Epi& E) {
;     ...
;         for (int t = 0; t < nt; t += 2) {
;             const bool last = (t == nt - 2);
;             const char* a1 = cA + (size_t)(t + 1) * kstep;
;             const char* a2 = last ? nA : cA + (size_t)(t + 2) * kstep; const char* b2 = last ? nB : cB + (size_t)(t + 2) * kstep;
;             const char* a3 = a2 + kstep; const char* b3 = b2 + kstep;
;             PG8_LDB(B0, 0, 0); PG8_LDB(B1, 0, 1); PG8_SCHED; PG8_LDA(At, 0, 0); PG8_STAGE(PG8_SA(1, 1), a1 + hstepA, voffA);
;             PG8_WAIT_V(8); PG8_WAIT_L(0); PG8_BAR; PG8_MMA(0, 0, At, B0); PG8_MMA(0, 1, At, B1); PG8_BAR; PG8_SCHED;
;             PG8_LDA(At, 0, 1); PG8_STAGE(PG8_SB(0, 0), b2, voffB); PG8_STAGE(PG8_SB(0, 1), b2 + hstepB, voffB); PG8_STAGE(PG8_SA(0, 0), a2, voffA);
.LBB0_2353:
	v_lshl_add_u64 v[162:163], s[68:69], 0, v[150:151]
	s_add_i32 m0, s83, 0xc000
	s_nop 0
	global_load_lds_dwordx4 v[162:163], off
	v_lshl_add_u64 v[162:163], s[68:69], 0, v[152:153]
	s_add_i32 m0, s83, 0xe000
	s_nop 0
	global_load_lds_dwordx4 v[162:163], off
	s_add_u32 s70, s68, 0x100
	s_addc_u32 s71, s69, 0
	s_add_i32 s76, 0, 0x10000
	s_cmp_eq_u32 vcc_hi, 40
	s_cselect_b32 s75, s1, s71
	s_cselect_b32 s74, s0, s70
	s_cselect_b32 s73, s31, vcc_lo
	s_cselect_b32 s72, s30, s11
	s_add_i32 s2, 0, 0x14000
	v_add_u32_e32 v154, s76, v199
	v_add_u32_e32 v162, s2, v199
	ds_read_b128 v[130:133], v154
	ds_read_b128 v[134:137], v154 offset:1024
	ds_read_b128 v[138:141], v154 offset:2048
	ds_read_b128 v[154:157], v154 offset:3072
	ds_read_b128 v[158:161], v162
	ds_read_b128 v[170:173], v162 offset:1024
	ds_read_b128 v[174:177], v162 offset:2048
	ds_read_b128 v[212:215], v162 offset:3072
	ds_read_b128 v[216:219], v201
	ds_read_b128 v[220:223], v201 offset:1024
	ds_read_b128 v[224:227], v201 offset:2048
	ds_read_b128 v[228:231], v201 offset:3072
	ds_read_b128 v[232:235], v201 offset:4096
	ds_read_b128 v[236:239], v201 offset:5120
	ds_read_b128 v[240:243], v201 offset:6144
	ds_read_b128 v[244:247], v201 offset:7168
	s_waitcnt vmcnt(8)
	s_waitcnt lgkmcnt(0)
	s_barrier
	s_setprio 1
	s_waitcnt lgkmcnt(0)
	v_mfma_f32_16x16x32_bf16 v[126:129], v[130:133], v[216:219], v[126:129]
	v_mfma_f32_16x16x32_bf16 v[122:125], v[138:141], v[216:219], v[122:125]
	v_mfma_f32_16x16x32_bf16 v[110:113], v[130:133], v[224:227], v[110:113]
	v_mfma_f32_16x16x32_bf16 v[106:109], v[138:141], v[224:227], v[106:109]
	v_mfma_f32_16x16x32_bf16 v[94:97], v[130:133], v[232:235], v[94:97]
	v_mfma_f32_16x16x32_bf16 v[90:93], v[138:141], v[232:235], v[90:93]
	v_mfma_f32_16x16x32_bf16 v[78:81], v[130:133], v[240:243], v[78:81]
	v_mfma_f32_16x16x32_bf16 v[74:77], v[138:141], v[240:243], v[74:77]
	v_mfma_f32_16x16x32_bf16 v[126:129], v[134:137], v[220:223], v[126:129]
	v_mfma_f32_16x16x32_bf16 v[122:125], v[154:157], v[220:223], v[122:125]
	v_mfma_f32_16x16x32_bf16 v[110:113], v[134:137], v[228:231], v[110:113]
	v_mfma_f32_16x16x32_bf16 v[106:109], v[154:157], v[228:231], v[106:109]
	v_mfma_f32_16x16x32_bf16 v[94:97], v[134:137], v[236:239], v[94:97]
	v_mfma_f32_16x16x32_bf16 v[90:93], v[154:157], v[236:239], v[90:93]
	v_mfma_f32_16x16x32_bf16 v[78:81], v[134:137], v[244:247], v[78:81]
	v_mfma_f32_16x16x32_bf16 v[74:77], v[154:157], v[244:247], v[74:77]
	s_setprio 0
	s_setprio 1
	v_mfma_f32_16x16x32_bf16 v[118:121], v[158:161], v[216:219], v[118:121]
	v_mfma_f32_16x16x32_bf16 v[114:117], v[174:177], v[216:219], v[114:117]
	v_mfma_f32_16x16x32_bf16 v[102:105], v[158:161], v[224:227], v[102:105]
	v_mfma_f32_16x16x32_bf16 v[98:101], v[174:177], v[224:227], v[98:101]
	v_mfma_f32_16x16x32_bf16 v[86:89], v[158:161], v[232:235], v[86:89]
	v_mfma_f32_16x16x32_bf16 v[82:85], v[174:177], v[232:235], v[82:85]
	v_mfma_f32_16x16x32_bf16 v[70:73], v[158:161], v[240:243], v[70:73]
	v_mfma_f32_16x16x32_bf16 v[66:69], v[174:177], v[240:243], v[66:69]
	v_mfma_f32_16x16x32_bf16 v[118:121], v[170:173], v[220:223], v[118:121]
	v_mfma_f32_16x16x32_bf16 v[114:117], v[212:215], v[220:223], v[114:117]
	v_mfma_f32_16x16x32_bf16 v[102:105], v[170:173], v[228:231], v[102:105]
	v_mfma_f32_16x16x32_bf16 v[98:101], v[212:215], v[228:231], v[98:101]
	v_mfma_f32_16x16x32_bf16 v[86:89], v[170:173], v[236:239], v[86:89]
	v_mfma_f32_16x16x32_bf16 v[82:85], v[212:215], v[236:239], v[82:85]
	v_mfma_f32_16x16x32_bf16 v[70:73], v[170:173], v[244:247], v[70:73]
	v_mfma_f32_16x16x32_bf16 v[66:69], v[212:215], v[244:247], v[66:69]
	s_setprio 0
	s_barrier
	s_add_i32 s3, s76, s82
	v_lshl_add_u64 v[162:163], s[72:73], 0, v[0:1]
	s_mov_b32 m0, s3
	s_nop 0
	global_load_lds_dwordx4 v[162:163], off
	s_add_i32 m0, s3, 0x2000
	s_add_u32 s68, s72, 0xb0000
	v_lshl_add_u64 v[164:165], s[72:73], 0, v[142:143]
	s_addc_u32 s69, s73, 0
	s_add_i32 s2, s2, s82
	global_load_lds_dwordx4 v[164:165], off
	v_lshl_add_u64 v[178:179], s[68:69], 0, v[0:1]
	s_mov_b32 m0, s2
	v_lshl_add_u64 v[206:207], s[74:75], 0, v[148:149]
	global_load_lds_dwordx4 v[178:179], off
	v_lshl_add_u64 v[178:179], s[68:69], 0, v[142:143]
	s_add_i32 m0, s2, 0x2000
	s_nop 0
	global_load_lds_dwordx4 v[178:179], off
	v_lshl_add_u64 v[178:179], s[74:75], 0, v[144:145]
	s_mov_b32 m0, s83
	s_nop 0
	global_load_lds_dwordx4 v[178:179], off
	s_mov_b32 m0, s88
	s_nop 0
	global_load_lds_dwordx4 v[206:207], off
	ds_read_b128 v[216:219], v201 offset:16384
	ds_read_b128 v[220:223], v201 offset:17408
	ds_read_b128 v[224:227], v201 offset:18432
	ds_read_b128 v[228:231], v201 offset:19456
	ds_read_b128 v[232:235], v201 offset:20480
	ds_read_b128 v[236:239], v201 offset:21504
	ds_read_b128 v[240:243], v201 offset:22528
	ds_read_b128 v[244:247], v201 offset:23552
	s_waitcnt vmcnt(8)
	s_waitcnt lgkmcnt(0)
	s_barrier
; #define PG8_STAGE(bufoff, gbase, voff) do { _Pragma("unroll") for (int _i = 0; _i < 2; ++_i) \
;         __builtin_amdgcn_global_load_lds((const unsigned*)((const char*)(gbase) + (voff)[_i]), (LAS unsigned*)(lds + (bufoff) + ldsw + _i * 8192), 16, 0, 0); } while (0)
; #define PG8_LDA(dst, b, h) do { _Pragma("unroll") for (int m = 0; m < 4; ++m) _Pragma("unroll") for (int k = 0; k < 2; ++k) dst[m][k] = *(const LAS bf16x8*)(lds + PG8_SA(b, h) + aoff + m * 2048 + k * 1024); } while (0)
; #define PG8_LDB(dst, b, h) do { _Pragma("unroll") for (int n = 0; n < 2; ++n) _Pragma("unroll") for (int k = 0; k < 2; ++k) dst[n][k] = *(const LAS bf16x8*)(lds + PG8_SB(b, h) + boff + n * 2048 + k * 1024); } while (0)
; #define PG8_MMA(ai, bj, At, Bt) do { __builtin_amdgcn_s_setprio(1); _Pragma("unroll") for (int m = 0; m < 4; ++m) _Pragma("unroll") for (int n = 0; n < 2; ++n) _Pragma("unroll") for (int k = 0; k < 2; ++k) \
;         acc[ai][bj][m][n] = __builtin_amdgcn_mfma_f32_16x16x32_bf16(Bt[n][k], At[m][k], acc[ai][bj][m][n], 0, 0, 0); __builtin_amdgcn_s_setprio(0); } while (0)
; #define PG8_WAIT_V(n) asm volatile("s_waitcnt vmcnt(" #n ")" ::: "memory")
; #define PG8_WAIT_L(n) asm volatile("s_waitcnt lgkmcnt(" #n ")" ::: "memory")
; #define PG8_BAR __builtin_amdgcn_s_barrier()
; #define PG8_SCHED __builtin_amdgcn_sched_barrier(0)
; template <class Epi>
; __device__ __forceinline__ void gemm_phase(LAS unsigned char* lds, const int tid, const Gemm g, const StaticOrder& S, const Epi& E) {
;     ...
;             PG8_WAIT_V(8); PG8_WAIT_L(0); PG8_BAR; PG8_MMA(1, 0, At, B0); PG8_MMA(1, 1, At, B1); PG8_BAR; PG8_SCHED;
;             PG8_LDB(B0, 1, 0); PG8_LDB(B1, 1, 1); PG8_SCHED; PG8_LDA(At, 1, 0); PG8_STAGE(PG8_SA(0, 1), a2 + hstepA, voffA);
;             PG8_WAIT_V(8); PG8_WAIT_L(0); PG8_BAR; PG8_MMA(0, 0, At, B0); PG8_MMA(0, 1, At, B1); PG8_BAR; PG8_SCHED;
	s_setprio 1
	s_waitcnt lgkmcnt(0)
	v_mfma_f32_16x16x32_bf16 v[62:65], v[130:133], v[216:219], v[62:65]
	v_mfma_f32_16x16x32_bf16 v[58:61], v[138:141], v[216:219], v[58:61]
	v_mfma_f32_16x16x32_bf16 v[46:49], v[130:133], v[224:227], v[46:49]
	v_mfma_f32_16x16x32_bf16 v[42:45], v[138:141], v[224:227], v[42:45]
	v_mfma_f32_16x16x32_bf16 v[30:33], v[130:133], v[232:235], v[30:33]
	v_mfma_f32_16x16x32_bf16 v[26:29], v[138:141], v[232:235], v[26:29]
	v_mfma_f32_16x16x32_bf16 v[14:17], v[130:133], v[240:243], v[14:17]
	v_mfma_f32_16x16x32_bf16 v[10:13], v[138:141], v[240:243], v[10:13]
	v_mfma_f32_16x16x32_bf16 v[62:65], v[134:137], v[220:223], v[62:65]
	v_mfma_f32_16x16x32_bf16 v[58:61], v[154:157], v[220:223], v[58:61]
	v_mfma_f32_16x16x32_bf16 v[46:49], v[134:137], v[228:231], v[46:49]
	v_mfma_f32_16x16x32_bf16 v[42:45], v[154:157], v[228:231], v[42:45]
	v_mfma_f32_16x16x32_bf16 v[30:33], v[134:137], v[236:239], v[30:33]
	v_mfma_f32_16x16x32_bf16 v[26:29], v[154:157], v[236:239], v[26:29]
	v_mfma_f32_16x16x32_bf16 v[14:17], v[134:137], v[244:247], v[14:17]
	v_mfma_f32_16x16x32_bf16 v[10:13], v[154:157], v[244:247], v[10:13]
	s_setprio 0
	s_setprio 1
	v_mfma_f32_16x16x32_bf16 v[54:57], v[158:161], v[216:219], v[54:57]
	v_mfma_f32_16x16x32_bf16 v[50:53], v[174:177], v[216:219], v[50:53]
	v_mfma_f32_16x16x32_bf16 v[38:41], v[158:161], v[224:227], v[38:41]
	v_mfma_f32_16x16x32_bf16 v[34:37], v[174:177], v[224:227], v[34:37]
	v_mfma_f32_16x16x32_bf16 v[22:25], v[158:161], v[232:235], v[22:25]
	v_mfma_f32_16x16x32_bf16 v[18:21], v[174:177], v[232:235], v[18:21]
	v_mfma_f32_16x16x32_bf16 v[6:9], v[158:161], v[240:243], v[6:9]
	v_mfma_f32_16x16x32_bf16 v[2:5], v[174:177], v[240:243], v[2:5]
	v_mfma_f32_16x16x32_bf16 v[54:57], v[170:173], v[220:223], v[54:57]
	v_mfma_f32_16x16x32_bf16 v[50:53], v[212:215], v[220:223], v[50:53]
	v_mfma_f32_16x16x32_bf16 v[38:41], v[170:173], v[228:231], v[38:41]
	v_mfma_f32_16x16x32_bf16 v[34:37], v[212:215], v[228:231], v[34:37]
	v_mfma_f32_16x16x32_bf16 v[22:25], v[170:173], v[236:239], v[22:25]
	v_mfma_f32_16x16x32_bf16 v[18:21], v[212:215], v[236:239], v[18:21]
	v_mfma_f32_16x16x32_bf16 v[6:9], v[170:173], v[244:247], v[6:9]
	v_mfma_f32_16x16x32_bf16 v[2:5], v[212:215], v[244:247], v[2:5]
	s_setprio 0
	s_barrier
	s_add_u32 s68, s74, 0x160000
	s_addc_u32 s69, s75, 0
	s_mov_b32 m0, s89
	v_lshl_add_u64 v[192:193], s[68:69], 0, v[144:145]
	global_load_lds_dwordx4 v[192:193], off
	v_lshl_add_u64 v[192:193], s[68:69], 0, v[148:149]
	s_mov_b32 m0, s92
	s_nop 0
	global_load_lds_dwordx4 v[192:193], off
	s_add_i32 s2, 0, 0x18000
	s_add_i32 s3, 0, 0x1c000
	v_add_u32_e32 v154, s2, v199
	v_add_u32_e32 v192, s3, v199
	ds_read_b128 v[130:133], v154
	ds_read_b128 v[134:137], v154 offset:1024
	ds_read_b128 v[138:141], v154 offset:2048
	ds_read_b128 v[154:157], v154 offset:3072
	ds_read_b128 v[158:161], v192
	ds_read_b128 v[170:173], v192 offset:1024
	ds_read_b128 v[174:177], v192 offset:2048
	ds_read_b128 v[212:215], v192 offset:3072
	ds_read_b128 v[216:219], v201 offset:32768
	ds_read_b128 v[220:223], v201 offset:33792
	ds_read_b128 v[224:227], v201 offset:34816
	ds_read_b128 v[228:231], v201 offset:35840
	ds_read_b128 v[232:235], v201 offset:36864
	ds_read_b128 v[236:239], v201 offset:37888
	ds_read_b128 v[240:243], v201 offset:38912
	ds_read_b128 v[244:247], v201 offset:39936
	s_waitcnt vmcnt(8)
	s_waitcnt lgkmcnt(0)
	s_barrier
	s_setprio 1
	s_waitcnt lgkmcnt(0)
	v_mfma_f32_16x16x32_bf16 v[126:129], v[130:133], v[216:219], v[126:129]
	v_mfma_f32_16x16x32_bf16 v[122:125], v[138:141], v[216:219], v[122:125]
	v_mfma_f32_16x16x32_bf16 v[110:113], v[130:133], v[224:227], v[110:113]
	v_mfma_f32_16x16x32_bf16 v[106:109], v[138:141], v[224:227], v[106:109]
	v_mfma_f32_16x16x32_bf16 v[94:97], v[130:133], v[232:235], v[94:97]
	v_mfma_f32_16x16x32_bf16 v[90:93], v[138:141], v[232:235], v[90:93]
	v_mfma_f32_16x16x32_bf16 v[78:81], v[130:133], v[240:243], v[78:81]
	v_mfma_f32_16x16x32_bf16 v[74:77], v[138:141], v[240:243], v[74:77]
	v_mfma_f32_16x16x32_bf16 v[126:129], v[134:137], v[220:223], v[126:129]
	v_mfma_f32_16x16x32_bf16 v[122:125], v[154:157], v[220:223], v[122:125]
	v_mfma_f32_16x16x32_bf16 v[110:113], v[134:137], v[228:231], v[110:113]
	v_mfma_f32_16x16x32_bf16 v[106:109], v[154:157], v[228:231], v[106:109]
	v_mfma_f32_16x16x32_bf16 v[94:97], v[134:137], v[236:239], v[94:97]
	v_mfma_f32_16x16x32_bf16 v[90:93], v[154:157], v[236:239], v[90:93]
	v_mfma_f32_16x16x32_bf16 v[78:81], v[134:137], v[244:247], v[78:81]
	v_mfma_f32_16x16x32_bf16 v[74:77], v[154:157], v[244:247], v[74:77]
	s_setprio 0
	s_setprio 1
	v_mfma_f32_16x16x32_bf16 v[118:121], v[158:161], v[216:219], v[118:121]
	v_mfma_f32_16x16x32_bf16 v[114:117], v[174:177], v[216:219], v[114:117]
	v_mfma_f32_16x16x32_bf16 v[102:105], v[158:161], v[224:227], v[102:105]
	v_mfma_f32_16x16x32_bf16 v[98:101], v[174:177], v[224:227], v[98:101]
	v_mfma_f32_16x16x32_bf16 v[86:89], v[158:161], v[232:235], v[86:89]
	v_mfma_f32_16x16x32_bf16 v[82:85], v[174:177], v[232:235], v[82:85]
	v_mfma_f32_16x16x32_bf16 v[70:73], v[158:161], v[240:243], v[70:73]
	v_mfma_f32_16x16x32_bf16 v[66:69], v[174:177], v[240:243], v[66:69]
	v_mfma_f32_16x16x32_bf16 v[118:121], v[170:173], v[220:223], v[118:121]
	v_mfma_f32_16x16x32_bf16 v[114:117], v[212:215], v[220:223], v[114:117]
	v_mfma_f32_16x16x32_bf16 v[102:105], v[170:173], v[228:231], v[102:105]
	v_mfma_f32_16x16x32_bf16 v[98:101], v[212:215], v[228:231], v[98:101]
	v_mfma_f32_16x16x32_bf16 v[86:89], v[170:173], v[236:239], v[86:89]
	v_mfma_f32_16x16x32_bf16 v[82:85], v[212:215], v[236:239], v[82:85]
	v_mfma_f32_16x16x32_bf16 v[70:73], v[170:173], v[244:247], v[70:73]
	v_mfma_f32_16x16x32_bf16 v[66:69], v[212:215], v[244:247], v[66:69]
	s_setprio 0
	s_barrier
; #define PG8_STAGE(bufoff, gbase, voff) do { _Pragma("unroll") for (int _i = 0; _i < 2; ++_i) \
;         __builtin_amdgcn_global_load_lds((const unsigned*)((const char*)(gbase) + (voff)[_i]), (LAS unsigned*)(lds + (bufoff) + ldsw + _i * 8192), 16, 0, 0); } while (0)
; #define PG8_LDA(dst, b, h) do { _Pragma("unroll") for (int m = 0; m < 4; ++m) _Pragma("unroll") for (int k = 0; k < 2; ++k) dst[m][k] = *(const LAS bf16x8*)(lds + PG8_SA(b, h) + aoff + m * 2048 + k * 1024); } while (0)
; #define PG8_MMA(ai, bj, At, Bt) do { __builtin_amdgcn_s_setprio(1); _Pragma("unroll") for (int m = 0; m < 4; ++m) _Pragma("unroll") for (int n = 0; n < 2; ++n) _Pragma("unroll") for (int k = 0; k < 2; ++k) \
;         acc[ai][bj][m][n] = __builtin_amdgcn_mfma_f32_16x16x32_bf16(Bt[n][k], At[m][k], acc[ai][bj][m][n], 0, 0, 0); __builtin_amdgcn_s_setprio(0); } while (0)
; #define PG8_WAIT_V(n) asm volatile("s_waitcnt vmcnt(" #n ")" ::: "memory")
; #define PG8_WAIT_L(n) asm volatile("s_waitcnt lgkmcnt(" #n ")" ::: "memory")
; #define PG8_BAR __builtin_amdgcn_s_barrier()
; #define PG8_SCHED __builtin_amdgcn_sched_barrier(0)
; template <class Epi>
; __device__ __forceinline__ void gemm_phase(LAS unsigned char* lds, const int tid, const Gemm g, const StaticOrder& S, const Epi& E) {
;     ...
;             PG8_LDA(At, 1, 1); PG8_STAGE(PG8_SB(1, 0), b3, voffB); PG8_STAGE(PG8_SB(1, 1), b3 + hstepB, voffB); PG8_STAGE(PG8_SA(1, 0), a3, voffA);
;             PG8_WAIT_V(8); PG8_WAIT_L(0); PG8_BAR; PG8_MMA(1, 0, At, B0); PG8_MMA(1, 1, At, B1); PG8_BAR; PG8_SCHED;
;         }
;         if (wr == 0) PG8_BAR;
	s_add_i32 s2, s2, s82
	v_lshl_add_u64 v[162:163], v[162:163], 0, s[36:37]
	s_mov_b32 m0, s2
	s_nop 0
	global_load_lds_dwordx4 v[162:163], off
	s_add_i32 m0, s2, 0x2000
	s_add_u32 s68, s72, 0xb0080
	v_lshl_add_u64 v[162:163], v[164:165], 0, s[36:37]
	s_addc_u32 s69, s73, 0
	s_add_i32 s2, s3, s82
	global_load_lds_dwordx4 v[162:163], off
	v_lshl_add_u64 v[162:163], s[68:69], 0, v[0:1]
	s_mov_b32 m0, s2
	s_nop 0
	global_load_lds_dwordx4 v[162:163], off
	v_lshl_add_u64 v[162:163], s[68:69], 0, v[142:143]
	s_add_i32 m0, s2, 0x2000
	s_nop 0
	global_load_lds_dwordx4 v[162:163], off
	v_lshl_add_u64 v[162:163], v[178:179], 0, s[36:37]
	s_mov_b32 m0, s4
	s_nop 0
	global_load_lds_dwordx4 v[162:163], off
	v_lshl_add_u64 v[162:163], v[206:207], 0, s[36:37]
	s_mov_b32 m0, s5
	s_nop 0
	global_load_lds_dwordx4 v[162:163], off
	ds_read_b128 v[216:219], v201 offset:49152
	ds_read_b128 v[220:223], v201 offset:50176
	ds_read_b128 v[224:227], v201 offset:51200
	ds_read_b128 v[228:231], v201 offset:52224
	ds_read_b128 v[232:235], v201 offset:53248
	ds_read_b128 v[236:239], v201 offset:54272
	ds_read_b128 v[240:243], v201 offset:55296
	ds_read_b128 v[244:247], v201 offset:56320
	s_waitcnt vmcnt(8)
	s_waitcnt lgkmcnt(0)
	s_barrier
	s_setprio 1
	s_waitcnt lgkmcnt(0)
	v_mfma_f32_16x16x32_bf16 v[62:65], v[130:133], v[216:219], v[62:65]
	v_mfma_f32_16x16x32_bf16 v[58:61], v[138:141], v[216:219], v[58:61]
	v_mfma_f32_16x16x32_bf16 v[46:49], v[130:133], v[224:227], v[46:49]
	v_mfma_f32_16x16x32_bf16 v[42:45], v[138:141], v[224:227], v[42:45]
	v_mfma_f32_16x16x32_bf16 v[30:33], v[130:133], v[232:235], v[30:33]
	v_mfma_f32_16x16x32_bf16 v[26:29], v[138:141], v[232:235], v[26:29]
	v_mfma_f32_16x16x32_bf16 v[14:17], v[130:133], v[240:243], v[14:17]
	v_mfma_f32_16x16x32_bf16 v[10:13], v[138:141], v[240:243], v[10:13]
	v_mfma_f32_16x16x32_bf16 v[62:65], v[134:137], v[220:223], v[62:65]
	v_mfma_f32_16x16x32_bf16 v[58:61], v[154:157], v[220:223], v[58:61]
	v_mfma_f32_16x16x32_bf16 v[46:49], v[134:137], v[228:231], v[46:49]
	v_mfma_f32_16x16x32_bf16 v[42:45], v[154:157], v[228:231], v[42:45]
	v_mfma_f32_16x16x32_bf16 v[30:33], v[134:137], v[236:239], v[30:33]
	v_mfma_f32_16x16x32_bf16 v[26:29], v[154:157], v[236:239], v[26:29]
	v_mfma_f32_16x16x32_bf16 v[14:17], v[134:137], v[244:247], v[14:17]
	v_mfma_f32_16x16x32_bf16 v[10:13], v[154:157], v[244:247], v[10:13]
	s_setprio 0
	s_setprio 1
	v_mfma_f32_16x16x32_bf16 v[54:57], v[158:161], v[216:219], v[54:57]
	v_mfma_f32_16x16x32_bf16 v[50:53], v[174:177], v[216:219], v[50:53]
	v_mfma_f32_16x16x32_bf16 v[38:41], v[158:161], v[224:227], v[38:41]
	v_mfma_f32_16x16x32_bf16 v[34:37], v[174:177], v[224:227], v[34:37]
	v_mfma_f32_16x16x32_bf16 v[22:25], v[158:161], v[232:235], v[22:25]
	v_mfma_f32_16x16x32_bf16 v[18:21], v[174:177], v[232:235], v[18:21]
	v_mfma_f32_16x16x32_bf16 v[6:9], v[158:161], v[240:243], v[6:9]
	v_mfma_f32_16x16x32_bf16 v[2:5], v[174:177], v[240:243], v[2:5]
	v_mfma_f32_16x16x32_bf16 v[54:57], v[170:173], v[220:223], v[54:57]
	v_mfma_f32_16x16x32_bf16 v[50:53], v[212:215], v[220:223], v[50:53]
	v_mfma_f32_16x16x32_bf16 v[38:41], v[170:173], v[228:231], v[38:41]
	v_mfma_f32_16x16x32_bf16 v[34:37], v[212:215], v[228:231], v[34:37]
	v_mfma_f32_16x16x32_bf16 v[22:25], v[170:173], v[236:239], v[22:25]
	v_mfma_f32_16x16x32_bf16 v[18:21], v[212:215], v[236:239], v[18:21]
	v_mfma_f32_16x16x32_bf16 v[6:9], v[170:173], v[244:247], v[6:9]
	v_mfma_f32_16x16x32_bf16 v[2:5], v[212:215], v[244:247], v[2:5]
	s_setprio 0
	s_barrier
	s_add_i32 vcc_hi, vcc_hi, 2
	s_add_u32 s11, s11, 0x100
	s_addc_u32 vcc_lo, vcc_lo, 0
	s_cmp_gt_u32 vcc_hi, 41
	s_mov_b64 s[68:69], s[70:71]
	s_cbranch_scc0 .LBB0_2353
	s_and_b64 vcc, exec, s[26:27]
	s_cbranch_vccz .LBB0_2356
	s_barrier
